# v74 minus the 48 mid-block s_setprio 0/1 flip pairs inside the K-loop MFMA blocks (A/B of the priority flips, timing-only edit)
# speedup vs baseline: 1.0055x; 1.0055x over previous
.LBB0_193:
	v_add_u32_e32 v126, s73, v177
	ds_read_b128 v[122:125], v126
	ds_read_b128 v[136:139], v126 offset:1024
	ds_read_b128 v[140:143], v126 offset:2048
	ds_read_b128 v[192:195], v126 offset:3072
	v_add_u32_e32 v126, s54, v177
	ds_read_b128 v[196:199], v126
	ds_read_b128 v[204:207], v126 offset:1024
	ds_read_b128 v[208:211], v126 offset:2048
	ds_read_b128 v[212:215], v126 offset:3072
	s_add_u32 s8, s0, 0xfff80080
	s_addc_u32 s9, s1, -1
	s_and_b64 s[4:5], s[4:5], exec
	s_cselect_b32 s9, s11, s9
	s_cselect_b32 s8, s12, s8
	s_cselect_b32 s5, s3, s17
	s_cselect_b32 s4, s13, s16
	v_lshl_add_u64 v[126:127], s[0:1], 0, v[168:169]
	s_add_i32 m0, s27, 0xc000
	ds_read_b128 v[216:219], v181
	ds_read_b128 v[220:223], v181 offset:1024
	ds_read_b128 v[224:227], v181 offset:2048
	ds_read_b128 v[228:231], v181 offset:3072
	ds_read_b128 v[232:235], v181 offset:4096
	ds_read_b128 v[236:239], v181 offset:5120
	ds_read_b128 v[240:243], v181 offset:6144
	ds_read_b128 v[244:247], v181 offset:7168
	global_load_lds_dwordx4 v[126:127], off
	v_lshl_add_u64 v[126:127], s[0:1], 0, v[166:167]
	s_add_i32 m0, s27, 0xe000
	s_nop 0
	global_load_lds_dwordx4 v[126:127], off
	s_waitcnt vmcnt(8)
	s_waitcnt lgkmcnt(0)
	s_barrier
	s_setprio 1
	s_waitcnt lgkmcnt(0)
	v_mfma_f32_16x16x32_bf16 v[112:115], v[122:125], v[216:219], v[112:115]
	v_mfma_f32_16x16x32_bf16 v[116:119], v[140:143], v[216:219], v[116:119]
	v_mfma_f32_16x16x32_bf16 v[108:111], v[122:125], v[224:227], v[108:111]
	v_mfma_f32_16x16x32_bf16 v[100:103], v[140:143], v[224:227], v[100:103]
	v_mfma_f32_16x16x32_bf16 v[92:95], v[122:125], v[232:235], v[92:95]
	v_mfma_f32_16x16x32_bf16 v[84:87], v[140:143], v[232:235], v[84:87]
	v_mfma_f32_16x16x32_bf16 v[76:79], v[122:125], v[240:243], v[76:79]
	v_mfma_f32_16x16x32_bf16 v[68:71], v[140:143], v[240:243], v[68:71]
	v_mfma_f32_16x16x32_bf16 v[112:115], v[136:139], v[220:223], v[112:115]
	v_mfma_f32_16x16x32_bf16 v[116:119], v[192:195], v[220:223], v[116:119]
	v_mfma_f32_16x16x32_bf16 v[108:111], v[136:139], v[228:231], v[108:111]
	v_mfma_f32_16x16x32_bf16 v[100:103], v[192:195], v[228:231], v[100:103]
	v_mfma_f32_16x16x32_bf16 v[92:95], v[136:139], v[236:239], v[92:95]
	v_mfma_f32_16x16x32_bf16 v[84:87], v[192:195], v[236:239], v[84:87]
	v_mfma_f32_16x16x32_bf16 v[76:79], v[136:139], v[244:247], v[76:79]
	v_mfma_f32_16x16x32_bf16 v[68:71], v[192:195], v[244:247], v[68:71]
	v_mfma_f32_16x16x32_bf16 v[104:107], v[196:199], v[216:219], v[104:107]
	v_mfma_f32_16x16x32_bf16 v[96:99], v[208:211], v[216:219], v[96:99]
	v_mfma_f32_16x16x32_bf16 v[88:91], v[196:199], v[224:227], v[88:91]
	v_mfma_f32_16x16x32_bf16 v[80:83], v[208:211], v[224:227], v[80:83]
	v_mfma_f32_16x16x32_bf16 v[72:75], v[196:199], v[232:235], v[72:75]
	v_mfma_f32_16x16x32_bf16 v[64:67], v[208:211], v[232:235], v[64:67]
	v_mfma_f32_16x16x32_bf16 v[60:63], v[196:199], v[240:243], v[60:63]
	v_mfma_f32_16x16x32_bf16 v[56:59], v[208:211], v[240:243], v[56:59]
	v_mfma_f32_16x16x32_bf16 v[104:107], v[204:207], v[220:223], v[104:107]
	v_mfma_f32_16x16x32_bf16 v[96:99], v[212:215], v[220:223], v[96:99]
	v_mfma_f32_16x16x32_bf16 v[88:91], v[204:207], v[228:231], v[88:91]
	v_mfma_f32_16x16x32_bf16 v[80:83], v[212:215], v[228:231], v[80:83]
	v_mfma_f32_16x16x32_bf16 v[72:75], v[204:207], v[236:239], v[72:75]
	v_mfma_f32_16x16x32_bf16 v[64:67], v[212:215], v[236:239], v[64:67]
	v_mfma_f32_16x16x32_bf16 v[60:63], v[204:207], v[244:247], v[60:63]
	v_mfma_f32_16x16x32_bf16 v[56:59], v[212:215], v[244:247], v[56:59]
	s_setprio 0
	s_barrier
	s_add_i32 s56, s73, s24
	v_lshl_add_u64 v[200:201], s[4:5], 0, v[146:147]
	s_mov_b32 m0, s56
	ds_read_b128 v[216:219], v181 offset:16384
	ds_read_b128 v[220:223], v181 offset:17408
	ds_read_b128 v[224:227], v181 offset:18432
	ds_read_b128 v[228:231], v181 offset:19456
	ds_read_b128 v[232:235], v181 offset:20480
	ds_read_b128 v[236:239], v181 offset:21504
	ds_read_b128 v[240:243], v181 offset:22528
	ds_read_b128 v[244:247], v181 offset:23552
	global_load_lds_dwordx4 v[200:201], off
	s_add_i32 m0, s56, 0x2000
	s_add_u32 s56, s4, 0x80000
	v_lshl_add_u64 v[248:249], s[4:5], 0, v[150:151]
	s_addc_u32 s57, s5, 0
	s_add_i32 s58, s54, s24
	global_load_lds_dwordx4 v[248:249], off
	v_lshl_add_u64 v[126:127], s[56:57], 0, v[146:147]
	s_mov_b32 m0, s58
	v_lshl_add_u64 v[250:251], s[8:9], 0, v[144:145]
	global_load_lds_dwordx4 v[126:127], off
	v_lshl_add_u64 v[126:127], s[56:57], 0, v[150:151]
	s_add_i32 m0, s58, 0x2000
	v_lshl_add_u64 v[252:253], s[8:9], 0, v[148:149]
	global_load_lds_dwordx4 v[126:127], off
	s_mov_b32 m0, s27
	s_nop 0
	global_load_lds_dwordx4 v[250:251], off
	s_mov_b32 m0, s28
	s_nop 0
	global_load_lds_dwordx4 v[252:253], off
	s_waitcnt vmcnt(8)
	s_waitcnt lgkmcnt(0)
	s_barrier
	s_setprio 1
	s_waitcnt lgkmcnt(0)
	v_mfma_f32_16x16x32_bf16 v[52:55], v[122:125], v[216:219], v[52:55]
	v_mfma_f32_16x16x32_bf16 v[48:51], v[140:143], v[216:219], v[48:51]
	v_mfma_f32_16x16x32_bf16 v[44:47], v[122:125], v[224:227], v[44:47]
	v_mfma_f32_16x16x32_bf16 v[36:39], v[140:143], v[224:227], v[36:39]
	v_mfma_f32_16x16x32_bf16 v[28:31], v[122:125], v[232:235], v[28:31]
	v_mfma_f32_16x16x32_bf16 v[20:23], v[140:143], v[232:235], v[20:23]
	v_mfma_f32_16x16x32_bf16 v[126:129], v[140:143], v[240:243], v[128:131]
	v_mfma_f32_16x16x32_bf16 v[52:55], v[136:139], v[220:223], v[52:55]
	v_mfma_f32_16x16x32_bf16 v[48:51], v[192:195], v[220:223], v[48:51]
	v_mfma_f32_16x16x32_bf16 v[44:47], v[136:139], v[228:231], v[44:47]
	v_mfma_f32_16x16x32_bf16 v[36:39], v[192:195], v[228:231], v[36:39]
	v_mfma_f32_16x16x32_bf16 v[28:31], v[136:139], v[236:239], v[28:31]
	v_mfma_f32_16x16x32_bf16 v[20:23], v[192:195], v[236:239], v[20:23]
	v_mfma_f32_16x16x32_bf16 v[122:125], v[122:125], v[240:243], v[132:135]
	v_mfma_f32_16x16x32_bf16 v[126:129], v[192:195], v[244:247], v[126:129]
	v_mfma_f32_16x16x32_bf16 v[122:125], v[136:139], v[244:247], v[122:125]
	v_mfma_f32_16x16x32_bf16 v[40:43], v[196:199], v[216:219], v[40:43]
	v_mfma_f32_16x16x32_bf16 v[32:35], v[208:211], v[216:219], v[32:35]
	v_mfma_f32_16x16x32_bf16 v[24:27], v[196:199], v[224:227], v[24:27]
	v_mfma_f32_16x16x32_bf16 v[16:19], v[208:211], v[224:227], v[16:19]
	v_mfma_f32_16x16x32_bf16 v[12:15], v[196:199], v[232:235], v[12:15]
	v_mfma_f32_16x16x32_bf16 v[8:11], v[208:211], v[232:235], v[8:11]
	v_mfma_f32_16x16x32_bf16 v[4:7], v[196:199], v[240:243], v[4:7]
	v_mfma_f32_16x16x32_bf16 v[0:3], v[208:211], v[240:243], v[0:3]
	v_mfma_f32_16x16x32_bf16 v[40:43], v[204:207], v[220:223], v[40:43]
	v_mfma_f32_16x16x32_bf16 v[32:35], v[212:215], v[220:223], v[32:35]
	v_mfma_f32_16x16x32_bf16 v[24:27], v[204:207], v[228:231], v[24:27]
	v_mfma_f32_16x16x32_bf16 v[16:19], v[212:215], v[228:231], v[16:19]
	v_mfma_f32_16x16x32_bf16 v[12:15], v[204:207], v[236:239], v[12:15]
	v_mfma_f32_16x16x32_bf16 v[8:11], v[212:215], v[236:239], v[8:11]
	v_mfma_f32_16x16x32_bf16 v[4:7], v[204:207], v[244:247], v[4:7]
	v_mfma_f32_16x16x32_bf16 v[0:3], v[212:215], v[244:247], v[0:3]
	s_setprio 0
	s_barrier
	s_add_i32 s56, 16, 0x18000
	v_add_u32_e32 v142, s56, v177
	s_add_i32 s57, 16, 0x1c000
	ds_read_b128 v[130:133], v142
	ds_read_b128 v[134:137], v142 offset:1024
	ds_read_b128 v[138:141], v142 offset:2048
	ds_read_b128 v[192:195], v142 offset:3072
	v_add_u32_e32 v142, s57, v177
	ds_read_b128 v[196:199], v142
	ds_read_b128 v[204:207], v142 offset:1024
	ds_read_b128 v[208:211], v142 offset:2048
	ds_read_b128 v[212:215], v142 offset:3072
	s_add_u32 s8, s8, 0x80000
	s_addc_u32 s9, s9, 0
	s_mov_b32 m0, s29
	v_lshl_add_u64 v[142:143], s[8:9], 0, v[144:145]
	ds_read_b128 v[216:219], v181 offset:32768
	ds_read_b128 v[220:223], v181 offset:33792
	ds_read_b128 v[224:227], v181 offset:34816
	ds_read_b128 v[228:231], v181 offset:35840
	ds_read_b128 v[232:235], v181 offset:36864
	ds_read_b128 v[236:239], v181 offset:37888
	ds_read_b128 v[240:243], v181 offset:38912
	ds_read_b128 v[244:247], v181 offset:39936
	global_load_lds_dwordx4 v[142:143], off
	v_lshl_add_u64 v[142:143], s[8:9], 0, v[148:149]
	s_mov_b32 m0, s97
	s_nop 0
	global_load_lds_dwordx4 v[142:143], off
	s_waitcnt vmcnt(8)
	s_waitcnt lgkmcnt(0)
	s_barrier
	s_setprio 1
	s_waitcnt lgkmcnt(0)
	v_mfma_f32_16x16x32_bf16 v[112:115], v[130:133], v[216:219], v[112:115]
	v_mfma_f32_16x16x32_bf16 v[116:119], v[138:141], v[216:219], v[116:119]
	v_mfma_f32_16x16x32_bf16 v[108:111], v[130:133], v[224:227], v[108:111]
	v_mfma_f32_16x16x32_bf16 v[100:103], v[138:141], v[224:227], v[100:103]
	v_mfma_f32_16x16x32_bf16 v[92:95], v[130:133], v[232:235], v[92:95]
	v_mfma_f32_16x16x32_bf16 v[84:87], v[138:141], v[232:235], v[84:87]
	v_mfma_f32_16x16x32_bf16 v[76:79], v[130:133], v[240:243], v[76:79]
	v_mfma_f32_16x16x32_bf16 v[68:71], v[138:141], v[240:243], v[68:71]
	v_mfma_f32_16x16x32_bf16 v[112:115], v[134:137], v[220:223], v[112:115]
	v_mfma_f32_16x16x32_bf16 v[116:119], v[192:195], v[220:223], v[116:119]
	v_mfma_f32_16x16x32_bf16 v[108:111], v[134:137], v[228:231], v[108:111]
	v_mfma_f32_16x16x32_bf16 v[100:103], v[192:195], v[228:231], v[100:103]
	v_mfma_f32_16x16x32_bf16 v[92:95], v[134:137], v[236:239], v[92:95]
	v_mfma_f32_16x16x32_bf16 v[84:87], v[192:195], v[236:239], v[84:87]
	v_mfma_f32_16x16x32_bf16 v[76:79], v[134:137], v[244:247], v[76:79]
	v_mfma_f32_16x16x32_bf16 v[68:71], v[192:195], v[244:247], v[68:71]
	v_mfma_f32_16x16x32_bf16 v[104:107], v[196:199], v[216:219], v[104:107]
	v_mfma_f32_16x16x32_bf16 v[96:99], v[208:211], v[216:219], v[96:99]
	v_mfma_f32_16x16x32_bf16 v[88:91], v[196:199], v[224:227], v[88:91]
	v_mfma_f32_16x16x32_bf16 v[80:83], v[208:211], v[224:227], v[80:83]
	v_mfma_f32_16x16x32_bf16 v[72:75], v[196:199], v[232:235], v[72:75]
	v_mfma_f32_16x16x32_bf16 v[64:67], v[208:211], v[232:235], v[64:67]
	v_mfma_f32_16x16x32_bf16 v[60:63], v[196:199], v[240:243], v[60:63]
	v_mfma_f32_16x16x32_bf16 v[56:59], v[208:211], v[240:243], v[56:59]
	v_mfma_f32_16x16x32_bf16 v[104:107], v[204:207], v[220:223], v[104:107]
	v_mfma_f32_16x16x32_bf16 v[96:99], v[212:215], v[220:223], v[96:99]
	v_mfma_f32_16x16x32_bf16 v[88:91], v[204:207], v[228:231], v[88:91]
	v_mfma_f32_16x16x32_bf16 v[80:83], v[212:215], v[228:231], v[80:83]
	v_mfma_f32_16x16x32_bf16 v[72:75], v[204:207], v[236:239], v[72:75]
	v_mfma_f32_16x16x32_bf16 v[64:67], v[212:215], v[236:239], v[64:67]
	v_mfma_f32_16x16x32_bf16 v[60:63], v[204:207], v[244:247], v[60:63]
	v_mfma_f32_16x16x32_bf16 v[56:59], v[212:215], v[244:247], v[56:59]
	s_setprio 0
	s_barrier
	s_add_i32 s8, s56, s24
	v_lshl_add_u64 v[142:143], v[200:201], 0, s[88:89]
	s_mov_b32 m0, s8
	ds_read_b128 v[216:219], v181 offset:49152
	ds_read_b128 v[220:223], v181 offset:50176
	ds_read_b128 v[224:227], v181 offset:51200
	ds_read_b128 v[228:231], v181 offset:52224
	ds_read_b128 v[232:235], v181 offset:53248
	ds_read_b128 v[236:239], v181 offset:54272
	ds_read_b128 v[240:243], v181 offset:55296
	ds_read_b128 v[244:247], v181 offset:56320
	global_load_lds_dwordx4 v[142:143], off
	s_add_i32 m0, s8, 0x2000
	s_add_u32 s4, s4, 0x80080
	v_lshl_add_u64 v[142:143], v[248:249], 0, s[88:89]
	s_addc_u32 s5, s5, 0
	s_add_i32 s8, s57, s24
	global_load_lds_dwordx4 v[142:143], off
	v_lshl_add_u64 v[142:143], s[4:5], 0, v[146:147]
	s_mov_b32 m0, s8
	s_nop 0
	global_load_lds_dwordx4 v[142:143], off
	v_lshl_add_u64 v[142:143], s[4:5], 0, v[150:151]
	s_add_i32 m0, s8, 0x2000
	s_nop 0
	global_load_lds_dwordx4 v[142:143], off
	v_lshl_add_u64 v[142:143], v[250:251], 0, s[88:89]
	s_mov_b32 m0, s80
	s_nop 0
	global_load_lds_dwordx4 v[142:143], off
	v_lshl_add_u64 v[142:143], v[252:253], 0, s[88:89]
	s_mov_b32 m0, s81
	s_nop 0
	global_load_lds_dwordx4 v[142:143], off
	s_waitcnt vmcnt(8)
	s_waitcnt lgkmcnt(0)
	s_barrier
	s_setprio 1
	s_waitcnt lgkmcnt(0)
	v_mfma_f32_16x16x32_bf16 v[52:55], v[130:133], v[216:219], v[52:55]
	v_mfma_f32_16x16x32_bf16 v[44:47], v[130:133], v[224:227], v[44:47]
	v_mfma_f32_16x16x32_bf16 v[28:31], v[130:133], v[232:235], v[28:31]
	v_mfma_f32_16x16x32_bf16 v[122:125], v[130:133], v[240:243], v[122:125]
	v_mfma_f32_16x16x32_bf16 v[52:55], v[134:137], v[220:223], v[52:55]
	v_mfma_f32_16x16x32_bf16 v[48:51], v[138:141], v[216:219], v[48:51]
	v_mfma_f32_16x16x32_bf16 v[44:47], v[134:137], v[228:231], v[44:47]
	v_mfma_f32_16x16x32_bf16 v[36:39], v[138:141], v[224:227], v[36:39]
	v_mfma_f32_16x16x32_bf16 v[28:31], v[134:137], v[236:239], v[28:31]
	v_mfma_f32_16x16x32_bf16 v[20:23], v[138:141], v[232:235], v[20:23]
	v_mfma_f32_16x16x32_bf16 v[132:135], v[134:137], v[244:247], v[122:125]
	v_mfma_f32_16x16x32_bf16 v[122:125], v[138:141], v[240:243], v[126:129]
	v_mfma_f32_16x16x32_bf16 v[48:51], v[192:195], v[220:223], v[48:51]
	v_mfma_f32_16x16x32_bf16 v[36:39], v[192:195], v[228:231], v[36:39]
	v_mfma_f32_16x16x32_bf16 v[20:23], v[192:195], v[236:239], v[20:23]
	v_mfma_f32_16x16x32_bf16 v[128:131], v[192:195], v[244:247], v[122:125]
	v_mfma_f32_16x16x32_bf16 v[40:43], v[196:199], v[216:219], v[40:43]
	v_mfma_f32_16x16x32_bf16 v[32:35], v[208:211], v[216:219], v[32:35]
	v_mfma_f32_16x16x32_bf16 v[24:27], v[196:199], v[224:227], v[24:27]
	v_mfma_f32_16x16x32_bf16 v[16:19], v[208:211], v[224:227], v[16:19]
	v_mfma_f32_16x16x32_bf16 v[12:15], v[196:199], v[232:235], v[12:15]
	v_mfma_f32_16x16x32_bf16 v[8:11], v[208:211], v[232:235], v[8:11]
	v_mfma_f32_16x16x32_bf16 v[4:7], v[196:199], v[240:243], v[4:7]
	v_mfma_f32_16x16x32_bf16 v[0:3], v[208:211], v[240:243], v[0:3]
	v_mfma_f32_16x16x32_bf16 v[40:43], v[204:207], v[220:223], v[40:43]
	v_mfma_f32_16x16x32_bf16 v[32:35], v[212:215], v[220:223], v[32:35]
	v_mfma_f32_16x16x32_bf16 v[24:27], v[204:207], v[228:231], v[24:27]
	v_mfma_f32_16x16x32_bf16 v[16:19], v[212:215], v[228:231], v[16:19]
	v_mfma_f32_16x16x32_bf16 v[12:15], v[204:207], v[236:239], v[12:15]
	v_mfma_f32_16x16x32_bf16 v[8:11], v[212:215], v[236:239], v[8:11]
	v_mfma_f32_16x16x32_bf16 v[4:7], v[204:207], v[244:247], v[4:7]
	v_mfma_f32_16x16x32_bf16 v[0:3], v[212:215], v[244:247], v[0:3]
	s_setprio 0
	s_barrier
	s_add_i32 s35, s35, 2
	s_add_u32 s16, s16, 0x100
	s_addc_u32 s17, s17, 0
	s_add_u32 s0, s0, 0x100
	s_addc_u32 s1, s1, 0
	s_cmp_gt_u32 s35, 29
	s_cbranch_scc1 .LBB0_196

.LBB0_532:
	s_add_i32 s92, s26, 2
	s_add_u32 s27, vcc_lo, 0xfffc0080
	s_addc_u32 s28, vcc_hi, -1
	s_add_i32 s52, 16, 0x10000
	s_cmp_eq_u32 s35, s26
	s_cselect_b32 s29, s89, s28
	s_cselect_b32 s28, s91, s27
	s_cselect_b32 s27, s33, s95
	s_cselect_b32 s26, s34, s94
	s_add_i32 s93, 16, 0x14000
	v_add_u32_e32 v140, s52, v184
	v_add_u32_e32 v187, s93, v184
	ds_read_b128 v[128:131], v140
	ds_read_b128 v[132:135], v140 offset:1024
	ds_read_b128 v[136:139], v140 offset:2048
	ds_read_b128 v[140:143], v140 offset:3072
	ds_read_b128 v[174:177], v187
	ds_read_b128 v[178:181], v187 offset:1024
	ds_read_b128 v[188:191], v187 offset:2048
	ds_read_b128 v[192:195], v187 offset:3072
	v_lshl_add_u64 v[228:229], vcc, 0, v[172:173]
	s_add_i32 m0, s63, 0xc000
	ds_read_b128 v[196:199], v153
	ds_read_b128 v[200:203], v153 offset:1024
	ds_read_b128 v[204:207], v153 offset:2048
	ds_read_b128 v[208:211], v153 offset:3072
	ds_read_b128 v[212:215], v153 offset:4096
	ds_read_b128 v[216:219], v153 offset:5120
	ds_read_b128 v[220:223], v153 offset:6144
	ds_read_b128 v[224:227], v153 offset:7168
	global_load_lds_dwordx4 v[228:229], off
	v_lshl_add_u64 v[228:229], vcc, 0, v[170:171]
	s_add_i32 m0, s63, 0xe000
	s_nop 0
	global_load_lds_dwordx4 v[228:229], off
	s_waitcnt vmcnt(8)
	s_waitcnt lgkmcnt(0)
	s_barrier
	s_setprio 1
	s_waitcnt lgkmcnt(0)
	v_mfma_f32_16x16x32_bf16 v[60:63], v[128:131], v[196:199], v[60:63]
	v_mfma_f32_16x16x32_bf16 v[56:59], v[136:139], v[196:199], v[56:59]
	v_mfma_f32_16x16x32_bf16 v[44:47], v[128:131], v[204:207], v[44:47]
	v_mfma_f32_16x16x32_bf16 v[40:43], v[136:139], v[204:207], v[40:43]
	v_mfma_f32_16x16x32_bf16 v[28:31], v[128:131], v[212:215], v[28:31]
	v_mfma_f32_16x16x32_bf16 v[24:27], v[136:139], v[212:215], v[24:27]
	v_mfma_f32_16x16x32_bf16 v[12:15], v[128:131], v[220:223], v[12:15]
	v_mfma_f32_16x16x32_bf16 v[8:11], v[136:139], v[220:223], v[8:11]
	v_mfma_f32_16x16x32_bf16 v[60:63], v[132:135], v[200:203], v[60:63]
	v_mfma_f32_16x16x32_bf16 v[56:59], v[140:143], v[200:203], v[56:59]
	v_mfma_f32_16x16x32_bf16 v[44:47], v[132:135], v[208:211], v[44:47]
	v_mfma_f32_16x16x32_bf16 v[40:43], v[140:143], v[208:211], v[40:43]
	v_mfma_f32_16x16x32_bf16 v[28:31], v[132:135], v[216:219], v[28:31]
	v_mfma_f32_16x16x32_bf16 v[24:27], v[140:143], v[216:219], v[24:27]
	v_mfma_f32_16x16x32_bf16 v[12:15], v[132:135], v[224:227], v[12:15]
	v_mfma_f32_16x16x32_bf16 v[8:11], v[140:143], v[224:227], v[8:11]
	v_mfma_f32_16x16x32_bf16 v[52:55], v[174:177], v[196:199], v[52:55]
	v_mfma_f32_16x16x32_bf16 v[48:51], v[188:191], v[196:199], v[48:51]
	v_mfma_f32_16x16x32_bf16 v[36:39], v[174:177], v[204:207], v[36:39]
	v_mfma_f32_16x16x32_bf16 v[32:35], v[188:191], v[204:207], v[32:35]
	v_mfma_f32_16x16x32_bf16 v[20:23], v[174:177], v[212:215], v[20:23]
	v_mfma_f32_16x16x32_bf16 v[16:19], v[188:191], v[212:215], v[16:19]
	v_mfma_f32_16x16x32_bf16 v[4:7], v[174:177], v[220:223], v[4:7]
	v_mfma_f32_16x16x32_bf16 v[0:3], v[188:191], v[220:223], v[0:3]
	v_mfma_f32_16x16x32_bf16 v[52:55], v[178:181], v[200:203], v[52:55]
	v_mfma_f32_16x16x32_bf16 v[48:51], v[192:195], v[200:203], v[48:51]
	v_mfma_f32_16x16x32_bf16 v[36:39], v[178:181], v[208:211], v[36:39]
	v_mfma_f32_16x16x32_bf16 v[32:35], v[192:195], v[208:211], v[32:35]
	v_mfma_f32_16x16x32_bf16 v[20:23], v[178:181], v[216:219], v[20:23]
	v_mfma_f32_16x16x32_bf16 v[16:19], v[192:195], v[216:219], v[16:19]
	v_mfma_f32_16x16x32_bf16 v[4:7], v[178:181], v[224:227], v[4:7]
	v_mfma_f32_16x16x32_bf16 v[0:3], v[192:195], v[224:227], v[0:3]
	s_setprio 0
	s_barrier
	s_add_i32 s52, s52, s62
	v_lshl_add_u64 v[228:229], s[26:27], 0, v[144:145]
	s_mov_b32 m0, s52
	ds_read_b128 v[196:199], v153 offset:16384
	ds_read_b128 v[200:203], v153 offset:17408
	ds_read_b128 v[204:207], v153 offset:18432
	ds_read_b128 v[208:211], v153 offset:19456
	ds_read_b128 v[212:215], v153 offset:20480
	ds_read_b128 v[216:219], v153 offset:21504
	ds_read_b128 v[220:223], v153 offset:22528
	ds_read_b128 v[224:227], v153 offset:23552
	global_load_lds_dwordx4 v[228:229], off
	s_add_i32 m0, s52, 0x2000
	s_add_u32 s52, s26, 0x40000
	v_lshl_add_u64 v[230:231], s[26:27], 0, v[146:147]
	s_addc_u32 s53, s27, 0
	s_add_i32 s93, s93, s62
	global_load_lds_dwordx4 v[230:231], off
	v_lshl_add_u64 v[232:233], s[52:53], 0, v[144:145]
	s_mov_b32 m0, s93
	v_lshl_add_u64 v[234:235], s[28:29], 0, v[148:149]
	global_load_lds_dwordx4 v[232:233], off
	v_lshl_add_u64 v[232:233], s[52:53], 0, v[146:147]
	s_add_i32 m0, s93, 0x2000
	s_nop 0
	global_load_lds_dwordx4 v[232:233], off
	v_lshl_add_u64 v[232:233], s[28:29], 0, v[150:151]
	s_mov_b32 m0, s63
	s_nop 0
	global_load_lds_dwordx4 v[232:233], off
	s_mov_b32 m0, s64
	s_nop 0
	global_load_lds_dwordx4 v[234:235], off
	s_waitcnt vmcnt(8)
	s_waitcnt lgkmcnt(0)
	s_barrier
	s_setprio 1
	s_waitcnt lgkmcnt(0)
	v_mfma_f32_16x16x32_bf16 v[124:127], v[128:131], v[196:199], v[124:127]
	v_mfma_f32_16x16x32_bf16 v[120:123], v[136:139], v[196:199], v[120:123]
	v_mfma_f32_16x16x32_bf16 v[108:111], v[128:131], v[204:207], v[108:111]
	v_mfma_f32_16x16x32_bf16 v[104:107], v[136:139], v[204:207], v[104:107]
	v_mfma_f32_16x16x32_bf16 v[92:95], v[128:131], v[212:215], v[92:95]
	v_mfma_f32_16x16x32_bf16 v[88:91], v[136:139], v[212:215], v[88:91]
	v_mfma_f32_16x16x32_bf16 v[76:79], v[128:131], v[220:223], v[76:79]
	v_mfma_f32_16x16x32_bf16 v[72:75], v[136:139], v[220:223], v[72:75]
	v_mfma_f32_16x16x32_bf16 v[124:127], v[132:135], v[200:203], v[124:127]
	v_mfma_f32_16x16x32_bf16 v[120:123], v[140:143], v[200:203], v[120:123]
	v_mfma_f32_16x16x32_bf16 v[108:111], v[132:135], v[208:211], v[108:111]
	v_mfma_f32_16x16x32_bf16 v[104:107], v[140:143], v[208:211], v[104:107]
	v_mfma_f32_16x16x32_bf16 v[92:95], v[132:135], v[216:219], v[92:95]
	v_mfma_f32_16x16x32_bf16 v[88:91], v[140:143], v[216:219], v[88:91]
	v_mfma_f32_16x16x32_bf16 v[76:79], v[132:135], v[224:227], v[76:79]
	v_mfma_f32_16x16x32_bf16 v[72:75], v[140:143], v[224:227], v[72:75]
	v_mfma_f32_16x16x32_bf16 v[116:119], v[174:177], v[196:199], v[116:119]
	v_mfma_f32_16x16x32_bf16 v[112:115], v[188:191], v[196:199], v[112:115]
	v_mfma_f32_16x16x32_bf16 v[100:103], v[174:177], v[204:207], v[100:103]
	v_mfma_f32_16x16x32_bf16 v[96:99], v[188:191], v[204:207], v[96:99]
	v_mfma_f32_16x16x32_bf16 v[84:87], v[174:177], v[212:215], v[84:87]
	v_mfma_f32_16x16x32_bf16 v[80:83], v[188:191], v[212:215], v[80:83]
	v_mfma_f32_16x16x32_bf16 v[68:71], v[174:177], v[220:223], v[68:71]
	v_mfma_f32_16x16x32_bf16 v[64:67], v[188:191], v[220:223], v[64:67]
	v_mfma_f32_16x16x32_bf16 v[116:119], v[178:181], v[200:203], v[116:119]
	v_mfma_f32_16x16x32_bf16 v[112:115], v[192:195], v[200:203], v[112:115]
	v_mfma_f32_16x16x32_bf16 v[100:103], v[178:181], v[208:211], v[100:103]
	v_mfma_f32_16x16x32_bf16 v[96:99], v[192:195], v[208:211], v[96:99]
	v_mfma_f32_16x16x32_bf16 v[84:87], v[178:181], v[216:219], v[84:87]
	v_mfma_f32_16x16x32_bf16 v[80:83], v[192:195], v[216:219], v[80:83]
	v_mfma_f32_16x16x32_bf16 v[68:71], v[178:181], v[224:227], v[68:71]
	v_mfma_f32_16x16x32_bf16 v[64:67], v[192:195], v[224:227], v[64:67]
	s_setprio 0
	s_barrier
	s_add_i32 s52, 16, 0x18000
	s_add_i32 s53, 16, 0x1c000
	v_add_u32_e32 v140, s52, v184
	v_add_u32_e32 v187, s53, v184
	ds_read_b128 v[128:131], v140
	ds_read_b128 v[132:135], v140 offset:1024
	ds_read_b128 v[136:139], v140 offset:2048
	ds_read_b128 v[140:143], v140 offset:3072
	ds_read_b128 v[174:177], v187
	ds_read_b128 v[178:181], v187 offset:1024
	ds_read_b128 v[188:191], v187 offset:2048
	ds_read_b128 v[192:195], v187 offset:3072
	s_add_u32 s28, s28, 0x40000
	s_addc_u32 s29, s29, 0
	s_mov_b32 m0, s65
	v_lshl_add_u64 v[236:237], s[28:29], 0, v[150:151]
	ds_read_b128 v[196:199], v153 offset:32768
	ds_read_b128 v[200:203], v153 offset:33792
	ds_read_b128 v[204:207], v153 offset:34816
	ds_read_b128 v[208:211], v153 offset:35840
	ds_read_b128 v[212:215], v153 offset:36864
	ds_read_b128 v[216:219], v153 offset:37888
	ds_read_b128 v[220:223], v153 offset:38912
	ds_read_b128 v[224:227], v153 offset:39936
	global_load_lds_dwordx4 v[236:237], off
	v_lshl_add_u64 v[236:237], s[28:29], 0, v[148:149]
	s_mov_b32 m0, s66
	s_nop 0
	global_load_lds_dwordx4 v[236:237], off
	s_waitcnt vmcnt(8)
	s_waitcnt lgkmcnt(0)
	s_barrier
	s_setprio 1
	s_waitcnt lgkmcnt(0)
	v_mfma_f32_16x16x32_bf16 v[60:63], v[128:131], v[196:199], v[60:63]
	v_mfma_f32_16x16x32_bf16 v[56:59], v[136:139], v[196:199], v[56:59]
	v_mfma_f32_16x16x32_bf16 v[44:47], v[128:131], v[204:207], v[44:47]
	v_mfma_f32_16x16x32_bf16 v[40:43], v[136:139], v[204:207], v[40:43]
	v_mfma_f32_16x16x32_bf16 v[28:31], v[128:131], v[212:215], v[28:31]
	v_mfma_f32_16x16x32_bf16 v[24:27], v[136:139], v[212:215], v[24:27]
	v_mfma_f32_16x16x32_bf16 v[12:15], v[128:131], v[220:223], v[12:15]
	v_mfma_f32_16x16x32_bf16 v[8:11], v[136:139], v[220:223], v[8:11]
	v_mfma_f32_16x16x32_bf16 v[60:63], v[132:135], v[200:203], v[60:63]
	v_mfma_f32_16x16x32_bf16 v[56:59], v[140:143], v[200:203], v[56:59]
	v_mfma_f32_16x16x32_bf16 v[44:47], v[132:135], v[208:211], v[44:47]
	v_mfma_f32_16x16x32_bf16 v[40:43], v[140:143], v[208:211], v[40:43]
	v_mfma_f32_16x16x32_bf16 v[28:31], v[132:135], v[216:219], v[28:31]
	v_mfma_f32_16x16x32_bf16 v[24:27], v[140:143], v[216:219], v[24:27]
	v_mfma_f32_16x16x32_bf16 v[12:15], v[132:135], v[224:227], v[12:15]
	v_mfma_f32_16x16x32_bf16 v[8:11], v[140:143], v[224:227], v[8:11]
	v_mfma_f32_16x16x32_bf16 v[52:55], v[174:177], v[196:199], v[52:55]
	v_mfma_f32_16x16x32_bf16 v[48:51], v[188:191], v[196:199], v[48:51]
	v_mfma_f32_16x16x32_bf16 v[36:39], v[174:177], v[204:207], v[36:39]
	v_mfma_f32_16x16x32_bf16 v[32:35], v[188:191], v[204:207], v[32:35]
	v_mfma_f32_16x16x32_bf16 v[20:23], v[174:177], v[212:215], v[20:23]
	v_mfma_f32_16x16x32_bf16 v[16:19], v[188:191], v[212:215], v[16:19]
	v_mfma_f32_16x16x32_bf16 v[4:7], v[174:177], v[220:223], v[4:7]
	v_mfma_f32_16x16x32_bf16 v[0:3], v[188:191], v[220:223], v[0:3]
	v_mfma_f32_16x16x32_bf16 v[52:55], v[178:181], v[200:203], v[52:55]
	v_mfma_f32_16x16x32_bf16 v[48:51], v[192:195], v[200:203], v[48:51]
	v_mfma_f32_16x16x32_bf16 v[36:39], v[178:181], v[208:211], v[36:39]
	v_mfma_f32_16x16x32_bf16 v[32:35], v[192:195], v[208:211], v[32:35]
	v_mfma_f32_16x16x32_bf16 v[20:23], v[178:181], v[216:219], v[20:23]
	v_mfma_f32_16x16x32_bf16 v[16:19], v[192:195], v[216:219], v[16:19]
	v_mfma_f32_16x16x32_bf16 v[4:7], v[178:181], v[224:227], v[4:7]
	v_mfma_f32_16x16x32_bf16 v[0:3], v[192:195], v[224:227], v[0:3]
	s_setprio 0
	s_barrier
	s_add_i32 s28, s52, s62
	v_lshl_add_u64 v[228:229], v[228:229], 0, s[54:55]
	s_mov_b32 m0, s28
	ds_read_b128 v[196:199], v153 offset:49152
	ds_read_b128 v[200:203], v153 offset:50176
	ds_read_b128 v[204:207], v153 offset:51200
	ds_read_b128 v[208:211], v153 offset:52224
	ds_read_b128 v[212:215], v153 offset:53248
	ds_read_b128 v[216:219], v153 offset:54272
	ds_read_b128 v[220:223], v153 offset:55296
	ds_read_b128 v[224:227], v153 offset:56320
	global_load_lds_dwordx4 v[228:229], off
	s_add_i32 m0, s28, 0x2000
	s_add_u32 s26, s26, 0x40080
	v_lshl_add_u64 v[228:229], v[230:231], 0, s[54:55]
	s_addc_u32 s27, s27, 0
	s_add_i32 s28, s53, s62
	global_load_lds_dwordx4 v[228:229], off
	v_lshl_add_u64 v[228:229], s[26:27], 0, v[144:145]
	s_mov_b32 m0, s28
	s_nop 0
	global_load_lds_dwordx4 v[228:229], off
	v_lshl_add_u64 v[228:229], s[26:27], 0, v[146:147]
	s_add_i32 m0, s28, 0x2000
	s_nop 0
	global_load_lds_dwordx4 v[228:229], off
	v_lshl_add_u64 v[228:229], v[232:233], 0, s[54:55]
	s_mov_b32 m0, s67
	s_nop 0
	global_load_lds_dwordx4 v[228:229], off
	v_lshl_add_u64 v[228:229], v[234:235], 0, s[54:55]
	s_mov_b32 m0, s77
	s_nop 0
	global_load_lds_dwordx4 v[228:229], off
	s_waitcnt vmcnt(8)
	s_waitcnt lgkmcnt(0)
	s_barrier
	s_setprio 1
	s_waitcnt lgkmcnt(0)
	v_mfma_f32_16x16x32_bf16 v[124:127], v[128:131], v[196:199], v[124:127]
	v_mfma_f32_16x16x32_bf16 v[120:123], v[136:139], v[196:199], v[120:123]
	v_mfma_f32_16x16x32_bf16 v[108:111], v[128:131], v[204:207], v[108:111]
	v_mfma_f32_16x16x32_bf16 v[104:107], v[136:139], v[204:207], v[104:107]
	v_mfma_f32_16x16x32_bf16 v[92:95], v[128:131], v[212:215], v[92:95]
	v_mfma_f32_16x16x32_bf16 v[88:91], v[136:139], v[212:215], v[88:91]
	v_mfma_f32_16x16x32_bf16 v[76:79], v[128:131], v[220:223], v[76:79]
	v_mfma_f32_16x16x32_bf16 v[72:75], v[136:139], v[220:223], v[72:75]
	v_mfma_f32_16x16x32_bf16 v[124:127], v[132:135], v[200:203], v[124:127]
	v_mfma_f32_16x16x32_bf16 v[120:123], v[140:143], v[200:203], v[120:123]
	v_mfma_f32_16x16x32_bf16 v[108:111], v[132:135], v[208:211], v[108:111]
	v_mfma_f32_16x16x32_bf16 v[104:107], v[140:143], v[208:211], v[104:107]
	v_mfma_f32_16x16x32_bf16 v[92:95], v[132:135], v[216:219], v[92:95]
	v_mfma_f32_16x16x32_bf16 v[88:91], v[140:143], v[216:219], v[88:91]
	v_mfma_f32_16x16x32_bf16 v[76:79], v[132:135], v[224:227], v[76:79]
	v_mfma_f32_16x16x32_bf16 v[72:75], v[140:143], v[224:227], v[72:75]
	v_mfma_f32_16x16x32_bf16 v[116:119], v[174:177], v[196:199], v[116:119]
	v_mfma_f32_16x16x32_bf16 v[112:115], v[188:191], v[196:199], v[112:115]
	v_mfma_f32_16x16x32_bf16 v[100:103], v[174:177], v[204:207], v[100:103]
	v_mfma_f32_16x16x32_bf16 v[96:99], v[188:191], v[204:207], v[96:99]
	v_mfma_f32_16x16x32_bf16 v[84:87], v[174:177], v[212:215], v[84:87]
	v_mfma_f32_16x16x32_bf16 v[80:83], v[188:191], v[212:215], v[80:83]
	v_mfma_f32_16x16x32_bf16 v[68:71], v[174:177], v[220:223], v[68:71]
	v_mfma_f32_16x16x32_bf16 v[64:67], v[188:191], v[220:223], v[64:67]
	v_mfma_f32_16x16x32_bf16 v[116:119], v[178:181], v[200:203], v[116:119]
	v_mfma_f32_16x16x32_bf16 v[112:115], v[192:195], v[200:203], v[112:115]
	v_mfma_f32_16x16x32_bf16 v[100:103], v[178:181], v[208:211], v[100:103]
	v_mfma_f32_16x16x32_bf16 v[96:99], v[192:195], v[208:211], v[96:99]
	v_mfma_f32_16x16x32_bf16 v[84:87], v[178:181], v[216:219], v[84:87]
	v_mfma_f32_16x16x32_bf16 v[80:83], v[192:195], v[216:219], v[80:83]
	v_mfma_f32_16x16x32_bf16 v[68:71], v[178:181], v[224:227], v[68:71]
	v_mfma_f32_16x16x32_bf16 v[64:67], v[192:195], v[224:227], v[64:67]
	s_setprio 0
	s_barrier
	s_add_u32 s94, s94, 0x100
	s_addc_u32 s95, s95, 0
	s_add_u32 vcc_lo, vcc_lo, 0x100
	s_addc_u32 vcc_hi, vcc_hi, 0
	s_cmp_ge_u32 s92, s57
	s_mov_b32 s26, s92
	s_cbranch_scc0 .LBB0_532
	s_and_b64 vcc, exec, s[80:81]
	s_cbranch_vccz .LBB0_535
	s_barrier

.LBB0_623:
	ds_read_b128 v[158:161], v137
	ds_read_b128 v[162:165], v137 offset:1024
	ds_read_b128 v[166:169], v137 offset:2048
	ds_read_b128 v[170:173], v137 offset:3072
	ds_read_b128 v[186:189], v177
	ds_read_b128 v[190:193], v177 offset:1024
	ds_read_b128 v[194:197], v177 offset:2048
	ds_read_b128 v[198:201], v177 offset:3072
	s_add_i32 s81, s14, 2
	s_add_u32 s15, s8, 0xfffc0080
	s_addc_u32 s24, s9, -1
	s_cmp_eq_u32 s33, s14
	s_cselect_b32 s14, s27, s77
	s_cselect_b32 s25, s83, s24
	s_cselect_b32 s24, s82, s15
	s_cselect_b32 s15, s26, s79
	v_lshl_add_u64 v[180:181], s[8:9], 0, v[156:157]
	s_add_i32 m0, s11, 0xc000
	ds_read_b128 v[202:205], v178
	ds_read_b128 v[206:209], v178 offset:1024
	ds_read_b128 v[210:213], v178 offset:2048
	ds_read_b128 v[214:217], v178 offset:3072
	ds_read_b128 v[218:221], v178 offset:4096
	ds_read_b128 v[222:225], v178 offset:5120
	ds_read_b128 v[226:229], v178 offset:6144
	ds_read_b128 v[230:233], v178 offset:7168
	global_load_lds_dwordx4 v[180:181], off
	v_lshl_add_u64 v[180:181], s[8:9], 0, v[154:155]
	s_add_i32 m0, s11, 0xe000
	s_nop 0
	global_load_lds_dwordx4 v[180:181], off
	s_waitcnt vmcnt(8)
	s_waitcnt lgkmcnt(0)
	s_barrier
	s_setprio 1
	s_waitcnt lgkmcnt(0)
	v_mfma_f32_16x16x32_bf16 v[60:63], v[158:161], v[202:205], v[60:63]
	v_mfma_f32_16x16x32_bf16 v[56:59], v[166:169], v[202:205], v[56:59]
	v_mfma_f32_16x16x32_bf16 v[44:47], v[158:161], v[210:213], v[44:47]
	v_mfma_f32_16x16x32_bf16 v[40:43], v[166:169], v[210:213], v[40:43]
	v_mfma_f32_16x16x32_bf16 v[28:31], v[158:161], v[218:221], v[28:31]
	v_mfma_f32_16x16x32_bf16 v[24:27], v[166:169], v[218:221], v[24:27]
	v_mfma_f32_16x16x32_bf16 v[12:15], v[158:161], v[226:229], v[12:15]
	v_mfma_f32_16x16x32_bf16 v[8:11], v[166:169], v[226:229], v[8:11]
	v_mfma_f32_16x16x32_bf16 v[60:63], v[162:165], v[206:209], v[60:63]
	v_mfma_f32_16x16x32_bf16 v[56:59], v[170:173], v[206:209], v[56:59]
	v_mfma_f32_16x16x32_bf16 v[44:47], v[162:165], v[214:217], v[44:47]
	v_mfma_f32_16x16x32_bf16 v[40:43], v[170:173], v[214:217], v[40:43]
	v_mfma_f32_16x16x32_bf16 v[28:31], v[162:165], v[222:225], v[28:31]
	v_mfma_f32_16x16x32_bf16 v[24:27], v[170:173], v[222:225], v[24:27]
	v_mfma_f32_16x16x32_bf16 v[12:15], v[162:165], v[230:233], v[12:15]
	v_mfma_f32_16x16x32_bf16 v[8:11], v[170:173], v[230:233], v[8:11]
	v_mfma_f32_16x16x32_bf16 v[52:55], v[186:189], v[202:205], v[52:55]
	v_mfma_f32_16x16x32_bf16 v[48:51], v[194:197], v[202:205], v[48:51]
	v_mfma_f32_16x16x32_bf16 v[36:39], v[186:189], v[210:213], v[36:39]
	v_mfma_f32_16x16x32_bf16 v[32:35], v[194:197], v[210:213], v[32:35]
	v_mfma_f32_16x16x32_bf16 v[20:23], v[186:189], v[218:221], v[20:23]
	v_mfma_f32_16x16x32_bf16 v[16:19], v[194:197], v[218:221], v[16:19]
	v_mfma_f32_16x16x32_bf16 v[4:7], v[186:189], v[226:229], v[4:7]
	v_mfma_f32_16x16x32_bf16 v[0:3], v[194:197], v[226:229], v[0:3]
	v_mfma_f32_16x16x32_bf16 v[52:55], v[190:193], v[206:209], v[52:55]
	v_mfma_f32_16x16x32_bf16 v[48:51], v[198:201], v[206:209], v[48:51]
	v_mfma_f32_16x16x32_bf16 v[36:39], v[190:193], v[214:217], v[36:39]
	v_mfma_f32_16x16x32_bf16 v[32:35], v[198:201], v[214:217], v[32:35]
	v_mfma_f32_16x16x32_bf16 v[20:23], v[190:193], v[222:225], v[20:23]
	v_mfma_f32_16x16x32_bf16 v[16:19], v[198:201], v[222:225], v[16:19]
	v_mfma_f32_16x16x32_bf16 v[4:7], v[190:193], v[230:233], v[4:7]
	v_mfma_f32_16x16x32_bf16 v[0:3], v[198:201], v[230:233], v[0:3]
	s_setprio 0
	s_barrier
	s_add_i32 s87, s64, s28
	v_lshl_add_u64 v[180:181], s[14:15], 0, v[130:131]
	s_mov_b32 m0, s87
	ds_read_b128 v[202:205], v178 offset:16384
	ds_read_b128 v[206:209], v178 offset:17408
	ds_read_b128 v[210:213], v178 offset:18432
	ds_read_b128 v[214:217], v178 offset:19456
	ds_read_b128 v[218:221], v178 offset:20480
	ds_read_b128 v[222:225], v178 offset:21504
	ds_read_b128 v[226:229], v178 offset:22528
	ds_read_b128 v[230:233], v178 offset:23552
	global_load_lds_dwordx4 v[180:181], off
	s_add_i32 m0, s87, 0x2000
	s_add_u32 s92, s14, 0x40000
	v_lshl_add_u64 v[234:235], s[14:15], 0, v[134:135]
	s_addc_u32 s93, s15, 0
	s_add_i32 s87, s65, s28
	global_load_lds_dwordx4 v[234:235], off
	v_lshl_add_u64 v[236:237], s[92:93], 0, v[130:131]
	s_mov_b32 m0, s87
	v_lshl_add_u64 v[238:239], s[24:25], 0, v[132:133]
	global_load_lds_dwordx4 v[236:237], off
	v_lshl_add_u64 v[236:237], s[92:93], 0, v[134:135]
	s_add_i32 m0, s87, 0x2000
	s_nop 0
	global_load_lds_dwordx4 v[236:237], off
	v_lshl_add_u64 v[236:237], s[24:25], 0, v[128:129]
	s_mov_b32 m0, s11
	s_nop 0
	global_load_lds_dwordx4 v[236:237], off
	s_mov_b32 m0, s29
	s_nop 0
	global_load_lds_dwordx4 v[238:239], off
	s_waitcnt vmcnt(8)
	s_waitcnt lgkmcnt(0)
	s_barrier
	s_setprio 1
	s_waitcnt lgkmcnt(0)
	v_mfma_f32_16x16x32_bf16 v[124:127], v[158:161], v[202:205], v[124:127]
	v_mfma_f32_16x16x32_bf16 v[120:123], v[166:169], v[202:205], v[120:123]
	v_mfma_f32_16x16x32_bf16 v[108:111], v[158:161], v[210:213], v[108:111]
	v_mfma_f32_16x16x32_bf16 v[104:107], v[166:169], v[210:213], v[104:107]
	v_mfma_f32_16x16x32_bf16 v[92:95], v[158:161], v[218:221], v[92:95]
	v_mfma_f32_16x16x32_bf16 v[88:91], v[166:169], v[218:221], v[88:91]
	v_mfma_f32_16x16x32_bf16 v[76:79], v[158:161], v[226:229], v[76:79]
	v_mfma_f32_16x16x32_bf16 v[72:75], v[166:169], v[226:229], v[72:75]
	v_mfma_f32_16x16x32_bf16 v[124:127], v[162:165], v[206:209], v[124:127]
	v_mfma_f32_16x16x32_bf16 v[120:123], v[170:173], v[206:209], v[120:123]
	v_mfma_f32_16x16x32_bf16 v[108:111], v[162:165], v[214:217], v[108:111]
	v_mfma_f32_16x16x32_bf16 v[104:107], v[170:173], v[214:217], v[104:107]
	v_mfma_f32_16x16x32_bf16 v[92:95], v[162:165], v[222:225], v[92:95]
	v_mfma_f32_16x16x32_bf16 v[88:91], v[170:173], v[222:225], v[88:91]
	v_mfma_f32_16x16x32_bf16 v[76:79], v[162:165], v[230:233], v[76:79]
	v_mfma_f32_16x16x32_bf16 v[72:75], v[170:173], v[230:233], v[72:75]
	v_mfma_f32_16x16x32_bf16 v[116:119], v[186:189], v[202:205], v[116:119]
	v_mfma_f32_16x16x32_bf16 v[112:115], v[194:197], v[202:205], v[112:115]
	v_mfma_f32_16x16x32_bf16 v[100:103], v[186:189], v[210:213], v[100:103]
	v_mfma_f32_16x16x32_bf16 v[96:99], v[194:197], v[210:213], v[96:99]
	v_mfma_f32_16x16x32_bf16 v[84:87], v[186:189], v[218:221], v[84:87]
	v_mfma_f32_16x16x32_bf16 v[80:83], v[194:197], v[218:221], v[80:83]
	v_mfma_f32_16x16x32_bf16 v[68:71], v[186:189], v[226:229], v[68:71]
	v_mfma_f32_16x16x32_bf16 v[64:67], v[194:197], v[226:229], v[64:67]
	v_mfma_f32_16x16x32_bf16 v[116:119], v[190:193], v[206:209], v[116:119]
	v_mfma_f32_16x16x32_bf16 v[112:115], v[198:201], v[206:209], v[112:115]
	v_mfma_f32_16x16x32_bf16 v[100:103], v[190:193], v[214:217], v[100:103]
	v_mfma_f32_16x16x32_bf16 v[96:99], v[198:201], v[214:217], v[96:99]
	v_mfma_f32_16x16x32_bf16 v[84:87], v[190:193], v[222:225], v[84:87]
	v_mfma_f32_16x16x32_bf16 v[80:83], v[198:201], v[222:225], v[80:83]
	v_mfma_f32_16x16x32_bf16 v[68:71], v[190:193], v[230:233], v[68:71]
	v_mfma_f32_16x16x32_bf16 v[64:67], v[198:201], v[230:233], v[64:67]
	s_setprio 0
	s_barrier
	s_add_i32 s87, 16, 0x18000
	s_add_i32 s92, 16, 0x1c000
	v_add_u32_e32 v170, s87, v175
	v_add_u32_e32 v179, s92, v175
	ds_read_b128 v[158:161], v170
	ds_read_b128 v[162:165], v170 offset:1024
	ds_read_b128 v[166:169], v170 offset:2048
	ds_read_b128 v[170:173], v170 offset:3072
	ds_read_b128 v[186:189], v179
	ds_read_b128 v[190:193], v179 offset:1024
	ds_read_b128 v[194:197], v179 offset:2048
	ds_read_b128 v[198:201], v179 offset:3072
	s_add_u32 s24, s24, 0x40000
	s_addc_u32 s25, s25, 0
	s_mov_b32 m0, s30
	v_lshl_add_u64 v[240:241], s[24:25], 0, v[128:129]
	ds_read_b128 v[202:205], v178 offset:32768
	ds_read_b128 v[206:209], v178 offset:33792
	ds_read_b128 v[210:213], v178 offset:34816
	ds_read_b128 v[214:217], v178 offset:35840
	ds_read_b128 v[218:221], v178 offset:36864
	ds_read_b128 v[222:225], v178 offset:37888
	ds_read_b128 v[226:229], v178 offset:38912
	ds_read_b128 v[230:233], v178 offset:39936
	global_load_lds_dwordx4 v[240:241], off
	v_lshl_add_u64 v[240:241], s[24:25], 0, v[132:133]
	s_mov_b32 m0, s56
	s_nop 0
	global_load_lds_dwordx4 v[240:241], off
	s_waitcnt vmcnt(8)
	s_waitcnt lgkmcnt(0)
	s_barrier
	s_setprio 1
	s_waitcnt lgkmcnt(0)
	v_mfma_f32_16x16x32_bf16 v[60:63], v[158:161], v[202:205], v[60:63]
	v_mfma_f32_16x16x32_bf16 v[56:59], v[166:169], v[202:205], v[56:59]
	v_mfma_f32_16x16x32_bf16 v[44:47], v[158:161], v[210:213], v[44:47]
	v_mfma_f32_16x16x32_bf16 v[40:43], v[166:169], v[210:213], v[40:43]
	v_mfma_f32_16x16x32_bf16 v[28:31], v[158:161], v[218:221], v[28:31]
	v_mfma_f32_16x16x32_bf16 v[24:27], v[166:169], v[218:221], v[24:27]
	v_mfma_f32_16x16x32_bf16 v[12:15], v[158:161], v[226:229], v[12:15]
	v_mfma_f32_16x16x32_bf16 v[8:11], v[166:169], v[226:229], v[8:11]
	v_mfma_f32_16x16x32_bf16 v[60:63], v[162:165], v[206:209], v[60:63]
	v_mfma_f32_16x16x32_bf16 v[56:59], v[170:173], v[206:209], v[56:59]
	v_mfma_f32_16x16x32_bf16 v[44:47], v[162:165], v[214:217], v[44:47]
	v_mfma_f32_16x16x32_bf16 v[40:43], v[170:173], v[214:217], v[40:43]
	v_mfma_f32_16x16x32_bf16 v[28:31], v[162:165], v[222:225], v[28:31]
	v_mfma_f32_16x16x32_bf16 v[24:27], v[170:173], v[222:225], v[24:27]
	v_mfma_f32_16x16x32_bf16 v[12:15], v[162:165], v[230:233], v[12:15]
	v_mfma_f32_16x16x32_bf16 v[8:11], v[170:173], v[230:233], v[8:11]
	v_mfma_f32_16x16x32_bf16 v[52:55], v[186:189], v[202:205], v[52:55]
	v_mfma_f32_16x16x32_bf16 v[48:51], v[194:197], v[202:205], v[48:51]
	v_mfma_f32_16x16x32_bf16 v[36:39], v[186:189], v[210:213], v[36:39]
	v_mfma_f32_16x16x32_bf16 v[32:35], v[194:197], v[210:213], v[32:35]
	v_mfma_f32_16x16x32_bf16 v[20:23], v[186:189], v[218:221], v[20:23]
	v_mfma_f32_16x16x32_bf16 v[16:19], v[194:197], v[218:221], v[16:19]
	v_mfma_f32_16x16x32_bf16 v[4:7], v[186:189], v[226:229], v[4:7]
	v_mfma_f32_16x16x32_bf16 v[0:3], v[194:197], v[226:229], v[0:3]
	v_mfma_f32_16x16x32_bf16 v[52:55], v[190:193], v[206:209], v[52:55]
	v_mfma_f32_16x16x32_bf16 v[48:51], v[198:201], v[206:209], v[48:51]
	v_mfma_f32_16x16x32_bf16 v[36:39], v[190:193], v[214:217], v[36:39]
	v_mfma_f32_16x16x32_bf16 v[32:35], v[198:201], v[214:217], v[32:35]
	v_mfma_f32_16x16x32_bf16 v[20:23], v[190:193], v[222:225], v[20:23]
	v_mfma_f32_16x16x32_bf16 v[16:19], v[198:201], v[222:225], v[16:19]
	v_mfma_f32_16x16x32_bf16 v[4:7], v[190:193], v[230:233], v[4:7]
	v_mfma_f32_16x16x32_bf16 v[0:3], v[198:201], v[230:233], v[0:3]
	s_setprio 0
	s_barrier
	s_add_i32 s24, s87, s28
	v_lshl_add_u64 v[180:181], v[180:181], 0, s[16:17]
	s_mov_b32 m0, s24
	ds_read_b128 v[202:205], v178 offset:49152
	ds_read_b128 v[206:209], v178 offset:50176
	ds_read_b128 v[210:213], v178 offset:51200
	ds_read_b128 v[214:217], v178 offset:52224
	ds_read_b128 v[218:221], v178 offset:53248
	ds_read_b128 v[222:225], v178 offset:54272
	ds_read_b128 v[226:229], v178 offset:55296
	ds_read_b128 v[230:233], v178 offset:56320
	global_load_lds_dwordx4 v[180:181], off
	s_add_i32 m0, s24, 0x2000
	s_add_u32 s14, s14, 0x40080
	v_lshl_add_u64 v[180:181], v[234:235], 0, s[16:17]
	s_addc_u32 s15, s15, 0
	s_add_i32 s24, s92, s28
	global_load_lds_dwordx4 v[180:181], off
	v_lshl_add_u64 v[180:181], s[14:15], 0, v[130:131]
	s_mov_b32 m0, s24
	s_nop 0
	global_load_lds_dwordx4 v[180:181], off
	v_lshl_add_u64 v[180:181], s[14:15], 0, v[134:135]
	s_add_i32 m0, s24, 0x2000
	s_nop 0
	global_load_lds_dwordx4 v[180:181], off
	v_lshl_add_u64 v[180:181], v[236:237], 0, s[16:17]
	s_mov_b32 m0, s57
	s_nop 0
	global_load_lds_dwordx4 v[180:181], off
	v_lshl_add_u64 v[180:181], v[238:239], 0, s[16:17]
	s_mov_b32 m0, s58
	s_nop 0
	global_load_lds_dwordx4 v[180:181], off
	s_waitcnt vmcnt(8)
	s_waitcnt lgkmcnt(0)
	s_barrier
	s_setprio 1
	s_waitcnt lgkmcnt(0)
	v_mfma_f32_16x16x32_bf16 v[124:127], v[158:161], v[202:205], v[124:127]
	v_mfma_f32_16x16x32_bf16 v[120:123], v[166:169], v[202:205], v[120:123]
	v_mfma_f32_16x16x32_bf16 v[108:111], v[158:161], v[210:213], v[108:111]
	v_mfma_f32_16x16x32_bf16 v[104:107], v[166:169], v[210:213], v[104:107]
	v_mfma_f32_16x16x32_bf16 v[92:95], v[158:161], v[218:221], v[92:95]
	v_mfma_f32_16x16x32_bf16 v[88:91], v[166:169], v[218:221], v[88:91]
	v_mfma_f32_16x16x32_bf16 v[76:79], v[158:161], v[226:229], v[76:79]
	v_mfma_f32_16x16x32_bf16 v[72:75], v[166:169], v[226:229], v[72:75]
	v_mfma_f32_16x16x32_bf16 v[124:127], v[162:165], v[206:209], v[124:127]
	v_mfma_f32_16x16x32_bf16 v[120:123], v[170:173], v[206:209], v[120:123]
	v_mfma_f32_16x16x32_bf16 v[108:111], v[162:165], v[214:217], v[108:111]
	v_mfma_f32_16x16x32_bf16 v[104:107], v[170:173], v[214:217], v[104:107]
	v_mfma_f32_16x16x32_bf16 v[92:95], v[162:165], v[222:225], v[92:95]
	v_mfma_f32_16x16x32_bf16 v[88:91], v[170:173], v[222:225], v[88:91]
	v_mfma_f32_16x16x32_bf16 v[76:79], v[162:165], v[230:233], v[76:79]
	v_mfma_f32_16x16x32_bf16 v[72:75], v[170:173], v[230:233], v[72:75]
	v_mfma_f32_16x16x32_bf16 v[116:119], v[186:189], v[202:205], v[116:119]
	v_mfma_f32_16x16x32_bf16 v[112:115], v[194:197], v[202:205], v[112:115]
	v_mfma_f32_16x16x32_bf16 v[100:103], v[186:189], v[210:213], v[100:103]
	v_mfma_f32_16x16x32_bf16 v[96:99], v[194:197], v[210:213], v[96:99]
	v_mfma_f32_16x16x32_bf16 v[84:87], v[186:189], v[218:221], v[84:87]
	v_mfma_f32_16x16x32_bf16 v[80:83], v[194:197], v[218:221], v[80:83]
	v_mfma_f32_16x16x32_bf16 v[68:71], v[186:189], v[226:229], v[68:71]
	v_mfma_f32_16x16x32_bf16 v[64:67], v[194:197], v[226:229], v[64:67]
	v_mfma_f32_16x16x32_bf16 v[116:119], v[190:193], v[206:209], v[116:119]
	v_mfma_f32_16x16x32_bf16 v[112:115], v[198:201], v[206:209], v[112:115]
	v_mfma_f32_16x16x32_bf16 v[100:103], v[190:193], v[214:217], v[100:103]
	v_mfma_f32_16x16x32_bf16 v[96:99], v[198:201], v[214:217], v[96:99]
	v_mfma_f32_16x16x32_bf16 v[84:87], v[190:193], v[222:225], v[84:87]
	v_mfma_f32_16x16x32_bf16 v[80:83], v[198:201], v[222:225], v[80:83]
	v_mfma_f32_16x16x32_bf16 v[68:71], v[190:193], v[230:233], v[68:71]
	v_mfma_f32_16x16x32_bf16 v[64:67], v[198:201], v[230:233], v[64:67]
	s_setprio 0
	s_barrier
	s_add_u32 s77, s77, 0x100
	s_addc_u32 s79, s79, 0
	s_add_u32 s8, s8, 0x100
	s_addc_u32 s9, s9, 0
	s_cmp_ge_u32 s81, s86
	s_mov_b32 s14, s81
	s_cbranch_scc0 .LBB0_623
	s_and_b64 vcc, exec, s[34:35]
	s_cbranch_vccz .LBB0_626
	s_barrier

.LBB0_778:
	ds_read_b128 v[152:155], v139
	ds_read_b128 v[166:169], v139 offset:1024
	ds_read_b128 v[170:173], v139 offset:2048
	ds_read_b128 v[174:177], v139 offset:3072
	ds_read_b128 v[178:181], v161
	ds_read_b128 v[186:189], v161 offset:1024
	ds_read_b128 v[190:193], v161 offset:2048
	ds_read_b128 v[194:197], v161 offset:3072
	s_add_i32 s94, s14, 2
	s_add_u32 s15, s92, 0xfff80080
	s_addc_u32 s24, s93, -1
	s_cmp_eq_u32 vcc_lo, s14
	s_cselect_b32 s14, s85, vcc_hi
	s_cselect_b32 s25, s1, s24
	s_cselect_b32 s24, s11, s15
	s_cselect_b32 s15, s83, s53
	v_lshl_add_u64 v[156:157], s[92:93], 0, v[150:151]
	s_add_i32 m0, s30, 0xc000
	ds_read_b128 v[198:201], v162
	ds_read_b128 v[202:205], v162 offset:1024
	ds_read_b128 v[206:209], v162 offset:2048
	ds_read_b128 v[210:213], v162 offset:3072
	ds_read_b128 v[214:217], v162 offset:4096
	ds_read_b128 v[218:221], v162 offset:5120
	ds_read_b128 v[222:225], v162 offset:6144
	ds_read_b128 v[226:229], v162 offset:7168
	global_load_lds_dwordx4 v[156:157], off
	v_lshl_add_u64 v[156:157], s[92:93], 0, v[148:149]
	s_add_i32 m0, s30, 0xe000
	s_nop 0
	global_load_lds_dwordx4 v[156:157], off
	s_waitcnt vmcnt(8)
	s_waitcnt lgkmcnt(0)
	s_barrier
	s_setprio 1
	s_waitcnt lgkmcnt(0)
	v_mfma_f32_16x16x32_bf16 v[60:63], v[152:155], v[198:201], v[60:63]
	v_mfma_f32_16x16x32_bf16 v[56:59], v[170:173], v[198:201], v[56:59]
	v_mfma_f32_16x16x32_bf16 v[52:55], v[152:155], v[206:209], v[52:55]
	v_mfma_f32_16x16x32_bf16 v[48:51], v[170:173], v[206:209], v[48:51]
	v_mfma_f32_16x16x32_bf16 v[44:47], v[152:155], v[214:217], v[44:47]
	v_mfma_f32_16x16x32_bf16 v[40:43], v[170:173], v[214:217], v[40:43]
	v_mfma_f32_16x16x32_bf16 v[28:31], v[152:155], v[222:225], v[28:31]
	v_mfma_f32_16x16x32_bf16 v[24:27], v[170:173], v[222:225], v[24:27]
	v_mfma_f32_16x16x32_bf16 v[60:63], v[166:169], v[202:205], v[60:63]
	v_mfma_f32_16x16x32_bf16 v[56:59], v[174:177], v[202:205], v[56:59]
	v_mfma_f32_16x16x32_bf16 v[52:55], v[166:169], v[210:213], v[52:55]
	v_mfma_f32_16x16x32_bf16 v[48:51], v[174:177], v[210:213], v[48:51]
	v_mfma_f32_16x16x32_bf16 v[44:47], v[166:169], v[218:221], v[44:47]
	v_mfma_f32_16x16x32_bf16 v[40:43], v[174:177], v[218:221], v[40:43]
	v_mfma_f32_16x16x32_bf16 v[28:31], v[166:169], v[226:229], v[28:31]
	v_mfma_f32_16x16x32_bf16 v[24:27], v[174:177], v[226:229], v[24:27]
	v_mfma_f32_16x16x32_bf16 v[36:39], v[178:181], v[198:201], v[36:39]
	v_mfma_f32_16x16x32_bf16 v[32:35], v[190:193], v[198:201], v[32:35]
	v_mfma_f32_16x16x32_bf16 v[20:23], v[178:181], v[206:209], v[20:23]
	v_mfma_f32_16x16x32_bf16 v[16:19], v[190:193], v[206:209], v[16:19]
	v_mfma_f32_16x16x32_bf16 v[12:15], v[178:181], v[214:217], v[12:15]
	v_mfma_f32_16x16x32_bf16 v[8:11], v[190:193], v[214:217], v[8:11]
	v_mfma_f32_16x16x32_bf16 v[4:7], v[178:181], v[222:225], v[4:7]
	v_mfma_f32_16x16x32_bf16 v[0:3], v[190:193], v[222:225], v[0:3]
	v_mfma_f32_16x16x32_bf16 v[36:39], v[186:189], v[202:205], v[36:39]
	v_mfma_f32_16x16x32_bf16 v[32:35], v[194:197], v[202:205], v[32:35]
	v_mfma_f32_16x16x32_bf16 v[20:23], v[186:189], v[210:213], v[20:23]
	v_mfma_f32_16x16x32_bf16 v[16:19], v[194:197], v[210:213], v[16:19]
	v_mfma_f32_16x16x32_bf16 v[12:15], v[186:189], v[218:221], v[12:15]
	v_mfma_f32_16x16x32_bf16 v[8:11], v[194:197], v[218:221], v[8:11]
	v_mfma_f32_16x16x32_bf16 v[4:7], v[186:189], v[226:229], v[4:7]
	v_mfma_f32_16x16x32_bf16 v[0:3], v[194:197], v[226:229], v[0:3]
	s_setprio 0
	s_barrier
	s_add_i32 s54, s60, s29
	v_lshl_add_u64 v[156:157], s[14:15], 0, v[130:131]
	s_mov_b32 m0, s54
	ds_read_b128 v[198:201], v162 offset:16384
	ds_read_b128 v[202:205], v162 offset:17408
	ds_read_b128 v[206:209], v162 offset:18432
	ds_read_b128 v[210:213], v162 offset:19456
	ds_read_b128 v[214:217], v162 offset:20480
	ds_read_b128 v[218:221], v162 offset:21504
	ds_read_b128 v[222:225], v162 offset:22528
	ds_read_b128 v[226:229], v162 offset:23552
	global_load_lds_dwordx4 v[156:157], off
	s_add_i32 m0, s54, 0x2000
	s_add_u32 s54, s14, 0x80000
	v_lshl_add_u64 v[230:231], s[14:15], 0, v[134:135]
	s_addc_u32 s55, s15, 0
	s_add_i32 s95, s61, s29
	global_load_lds_dwordx4 v[230:231], off
	v_lshl_add_u64 v[232:233], s[54:55], 0, v[130:131]
	s_mov_b32 m0, s95
	v_lshl_add_u64 v[234:235], s[24:25], 0, v[132:133]
	global_load_lds_dwordx4 v[232:233], off
	v_lshl_add_u64 v[232:233], s[54:55], 0, v[134:135]
	s_add_i32 m0, s95, 0x2000
	s_nop 0
	global_load_lds_dwordx4 v[232:233], off
	v_lshl_add_u64 v[232:233], s[24:25], 0, v[128:129]
	s_mov_b32 m0, s30
	s_nop 0
	global_load_lds_dwordx4 v[232:233], off
	s_mov_b32 m0, s31
	s_nop 0
	global_load_lds_dwordx4 v[234:235], off
	s_waitcnt vmcnt(8)
	s_waitcnt lgkmcnt(0)
	s_barrier
	s_setprio 1
	s_waitcnt lgkmcnt(0)
	v_mfma_f32_16x16x32_bf16 v[120:123], v[152:155], v[198:201], v[120:123]
	v_mfma_f32_16x16x32_bf16 v[124:127], v[170:173], v[198:201], v[124:127]
	v_mfma_f32_16x16x32_bf16 v[104:107], v[152:155], v[206:209], v[104:107]
	v_mfma_f32_16x16x32_bf16 v[108:111], v[170:173], v[206:209], v[108:111]
	v_mfma_f32_16x16x32_bf16 v[88:91], v[152:155], v[214:217], v[88:91]
	v_mfma_f32_16x16x32_bf16 v[92:95], v[170:173], v[214:217], v[92:95]
	v_mfma_f32_16x16x32_bf16 v[72:75], v[152:155], v[222:225], v[72:75]
	v_mfma_f32_16x16x32_bf16 v[76:79], v[170:173], v[222:225], v[76:79]
	v_mfma_f32_16x16x32_bf16 v[120:123], v[166:169], v[202:205], v[120:123]
	v_mfma_f32_16x16x32_bf16 v[124:127], v[174:177], v[202:205], v[124:127]
	v_mfma_f32_16x16x32_bf16 v[104:107], v[166:169], v[210:213], v[104:107]
	v_mfma_f32_16x16x32_bf16 v[108:111], v[174:177], v[210:213], v[108:111]
	v_mfma_f32_16x16x32_bf16 v[88:91], v[166:169], v[218:221], v[88:91]
	v_mfma_f32_16x16x32_bf16 v[92:95], v[174:177], v[218:221], v[92:95]
	v_mfma_f32_16x16x32_bf16 v[72:75], v[166:169], v[226:229], v[72:75]
	v_mfma_f32_16x16x32_bf16 v[76:79], v[174:177], v[226:229], v[76:79]
	v_mfma_f32_16x16x32_bf16 v[116:119], v[178:181], v[198:201], v[116:119]
	v_mfma_f32_16x16x32_bf16 v[112:115], v[190:193], v[198:201], v[112:115]
	v_mfma_f32_16x16x32_bf16 v[100:103], v[178:181], v[206:209], v[100:103]
	v_mfma_f32_16x16x32_bf16 v[96:99], v[190:193], v[206:209], v[96:99]
	v_mfma_f32_16x16x32_bf16 v[84:87], v[178:181], v[214:217], v[84:87]
	v_mfma_f32_16x16x32_bf16 v[80:83], v[190:193], v[214:217], v[80:83]
	v_mfma_f32_16x16x32_bf16 v[68:71], v[178:181], v[222:225], v[68:71]
	v_mfma_f32_16x16x32_bf16 v[64:67], v[190:193], v[222:225], v[64:67]
	v_mfma_f32_16x16x32_bf16 v[116:119], v[186:189], v[202:205], v[116:119]
	v_mfma_f32_16x16x32_bf16 v[112:115], v[194:197], v[202:205], v[112:115]
	v_mfma_f32_16x16x32_bf16 v[100:103], v[186:189], v[210:213], v[100:103]
	v_mfma_f32_16x16x32_bf16 v[96:99], v[194:197], v[210:213], v[96:99]
	v_mfma_f32_16x16x32_bf16 v[84:87], v[186:189], v[218:221], v[84:87]
	v_mfma_f32_16x16x32_bf16 v[80:83], v[194:197], v[218:221], v[80:83]
	v_mfma_f32_16x16x32_bf16 v[68:71], v[186:189], v[226:229], v[68:71]
	v_mfma_f32_16x16x32_bf16 v[64:67], v[194:197], v[226:229], v[64:67]
	s_setprio 0
	s_barrier
	s_add_i32 s54, 16, 0x18000
	v_add_u32_e32 v136, s54, v159
	s_add_i32 s55, 16, 0x1c000
	ds_read_b128 v[152:155], v136
	ds_read_b128 v[166:169], v136 offset:1024
	ds_read_b128 v[170:173], v136 offset:2048
	ds_read_b128 v[174:177], v136 offset:3072
	v_add_u32_e32 v136, s55, v159
	ds_read_b128 v[178:181], v136
	ds_read_b128 v[186:189], v136 offset:1024
	ds_read_b128 v[190:193], v136 offset:2048
	ds_read_b128 v[194:197], v136 offset:3072
	s_add_u32 s24, s24, 0x80000
	s_addc_u32 s25, s25, 0
	s_mov_b32 m0, s33
	v_lshl_add_u64 v[236:237], s[24:25], 0, v[128:129]
	ds_read_b128 v[198:201], v162 offset:32768
	ds_read_b128 v[202:205], v162 offset:33792
	ds_read_b128 v[206:209], v162 offset:34816
	ds_read_b128 v[210:213], v162 offset:35840
	ds_read_b128 v[214:217], v162 offset:36864
	ds_read_b128 v[218:221], v162 offset:37888
	ds_read_b128 v[222:225], v162 offset:38912
	ds_read_b128 v[226:229], v162 offset:39936
	global_load_lds_dwordx4 v[236:237], off
	v_lshl_add_u64 v[236:237], s[24:25], 0, v[132:133]
	s_mov_b32 m0, s52
	s_nop 0
	global_load_lds_dwordx4 v[236:237], off
	s_waitcnt vmcnt(8)
	s_waitcnt lgkmcnt(0)
	s_barrier
	s_setprio 1
	s_waitcnt lgkmcnt(0)
	v_mfma_f32_16x16x32_bf16 v[60:63], v[152:155], v[198:201], v[60:63]
	v_mfma_f32_16x16x32_bf16 v[56:59], v[170:173], v[198:201], v[56:59]
	v_mfma_f32_16x16x32_bf16 v[52:55], v[152:155], v[206:209], v[52:55]
	v_mfma_f32_16x16x32_bf16 v[48:51], v[170:173], v[206:209], v[48:51]
	v_mfma_f32_16x16x32_bf16 v[44:47], v[152:155], v[214:217], v[44:47]
	v_mfma_f32_16x16x32_bf16 v[40:43], v[170:173], v[214:217], v[40:43]
	v_mfma_f32_16x16x32_bf16 v[28:31], v[152:155], v[222:225], v[28:31]
	v_mfma_f32_16x16x32_bf16 v[24:27], v[170:173], v[222:225], v[24:27]
	v_mfma_f32_16x16x32_bf16 v[60:63], v[166:169], v[202:205], v[60:63]
	v_mfma_f32_16x16x32_bf16 v[56:59], v[174:177], v[202:205], v[56:59]
	v_mfma_f32_16x16x32_bf16 v[52:55], v[166:169], v[210:213], v[52:55]
	v_mfma_f32_16x16x32_bf16 v[48:51], v[174:177], v[210:213], v[48:51]
	v_mfma_f32_16x16x32_bf16 v[44:47], v[166:169], v[218:221], v[44:47]
	v_mfma_f32_16x16x32_bf16 v[40:43], v[174:177], v[218:221], v[40:43]
	v_mfma_f32_16x16x32_bf16 v[28:31], v[166:169], v[226:229], v[28:31]
	v_mfma_f32_16x16x32_bf16 v[24:27], v[174:177], v[226:229], v[24:27]
	v_mfma_f32_16x16x32_bf16 v[36:39], v[178:181], v[198:201], v[36:39]
	v_mfma_f32_16x16x32_bf16 v[32:35], v[190:193], v[198:201], v[32:35]
	v_mfma_f32_16x16x32_bf16 v[20:23], v[178:181], v[206:209], v[20:23]
	v_mfma_f32_16x16x32_bf16 v[16:19], v[190:193], v[206:209], v[16:19]
	v_mfma_f32_16x16x32_bf16 v[12:15], v[178:181], v[214:217], v[12:15]
	v_mfma_f32_16x16x32_bf16 v[8:11], v[190:193], v[214:217], v[8:11]
	v_mfma_f32_16x16x32_bf16 v[4:7], v[178:181], v[222:225], v[4:7]
	v_mfma_f32_16x16x32_bf16 v[0:3], v[190:193], v[222:225], v[0:3]
	v_mfma_f32_16x16x32_bf16 v[36:39], v[186:189], v[202:205], v[36:39]
	v_mfma_f32_16x16x32_bf16 v[32:35], v[194:197], v[202:205], v[32:35]
	v_mfma_f32_16x16x32_bf16 v[20:23], v[186:189], v[210:213], v[20:23]
	v_mfma_f32_16x16x32_bf16 v[16:19], v[194:197], v[210:213], v[16:19]
	v_mfma_f32_16x16x32_bf16 v[12:15], v[186:189], v[218:221], v[12:15]
	v_mfma_f32_16x16x32_bf16 v[8:11], v[194:197], v[218:221], v[8:11]
	v_mfma_f32_16x16x32_bf16 v[4:7], v[186:189], v[226:229], v[4:7]
	v_mfma_f32_16x16x32_bf16 v[0:3], v[194:197], v[226:229], v[0:3]
	s_setprio 0
	s_barrier
	s_add_i32 s24, s54, s29
	v_lshl_add_u64 v[156:157], v[156:157], 0, s[72:73]
	s_mov_b32 m0, s24
	ds_read_b128 v[198:201], v162 offset:49152
	ds_read_b128 v[202:205], v162 offset:50176
	ds_read_b128 v[206:209], v162 offset:51200
	ds_read_b128 v[210:213], v162 offset:52224
	ds_read_b128 v[214:217], v162 offset:53248
	ds_read_b128 v[218:221], v162 offset:54272
	ds_read_b128 v[222:225], v162 offset:55296
	ds_read_b128 v[226:229], v162 offset:56320
	global_load_lds_dwordx4 v[156:157], off
	s_add_i32 m0, s24, 0x2000
	s_add_u32 s14, s14, 0x80080
	v_lshl_add_u64 v[156:157], v[230:231], 0, s[72:73]
	s_addc_u32 s15, s15, 0
	s_add_i32 s24, s55, s29
	global_load_lds_dwordx4 v[156:157], off
	v_lshl_add_u64 v[156:157], s[14:15], 0, v[130:131]
	s_mov_b32 m0, s24
	s_nop 0
	global_load_lds_dwordx4 v[156:157], off
	v_lshl_add_u64 v[156:157], s[14:15], 0, v[134:135]
	s_add_i32 m0, s24, 0x2000
	s_nop 0
	global_load_lds_dwordx4 v[156:157], off
	v_lshl_add_u64 v[156:157], v[232:233], 0, s[72:73]
	s_mov_b32 m0, s58
	s_nop 0
	global_load_lds_dwordx4 v[156:157], off
	v_lshl_add_u64 v[156:157], v[234:235], 0, s[72:73]
	s_mov_b32 m0, s59
	s_nop 0
	global_load_lds_dwordx4 v[156:157], off
	s_waitcnt vmcnt(8)
	s_waitcnt lgkmcnt(0)
	s_barrier
	s_setprio 1
	s_waitcnt lgkmcnt(0)
	v_mfma_f32_16x16x32_bf16 v[120:123], v[152:155], v[198:201], v[120:123]
	v_mfma_f32_16x16x32_bf16 v[124:127], v[170:173], v[198:201], v[124:127]
	v_mfma_f32_16x16x32_bf16 v[104:107], v[152:155], v[206:209], v[104:107]
	v_mfma_f32_16x16x32_bf16 v[108:111], v[170:173], v[206:209], v[108:111]
	v_mfma_f32_16x16x32_bf16 v[88:91], v[152:155], v[214:217], v[88:91]
	v_mfma_f32_16x16x32_bf16 v[92:95], v[170:173], v[214:217], v[92:95]
	v_mfma_f32_16x16x32_bf16 v[72:75], v[152:155], v[222:225], v[72:75]
	v_mfma_f32_16x16x32_bf16 v[76:79], v[170:173], v[222:225], v[76:79]
	v_mfma_f32_16x16x32_bf16 v[120:123], v[166:169], v[202:205], v[120:123]
	v_mfma_f32_16x16x32_bf16 v[124:127], v[174:177], v[202:205], v[124:127]
	v_mfma_f32_16x16x32_bf16 v[104:107], v[166:169], v[210:213], v[104:107]
	v_mfma_f32_16x16x32_bf16 v[108:111], v[174:177], v[210:213], v[108:111]
	v_mfma_f32_16x16x32_bf16 v[88:91], v[166:169], v[218:221], v[88:91]
	v_mfma_f32_16x16x32_bf16 v[92:95], v[174:177], v[218:221], v[92:95]
	v_mfma_f32_16x16x32_bf16 v[72:75], v[166:169], v[226:229], v[72:75]
	v_mfma_f32_16x16x32_bf16 v[76:79], v[174:177], v[226:229], v[76:79]
	v_mfma_f32_16x16x32_bf16 v[116:119], v[178:181], v[198:201], v[116:119]
	v_mfma_f32_16x16x32_bf16 v[112:115], v[190:193], v[198:201], v[112:115]
	v_mfma_f32_16x16x32_bf16 v[100:103], v[178:181], v[206:209], v[100:103]
	v_mfma_f32_16x16x32_bf16 v[96:99], v[190:193], v[206:209], v[96:99]
	v_mfma_f32_16x16x32_bf16 v[84:87], v[178:181], v[214:217], v[84:87]
	v_mfma_f32_16x16x32_bf16 v[80:83], v[190:193], v[214:217], v[80:83]
	v_mfma_f32_16x16x32_bf16 v[68:71], v[178:181], v[222:225], v[68:71]
	v_mfma_f32_16x16x32_bf16 v[64:67], v[190:193], v[222:225], v[64:67]
	v_mfma_f32_16x16x32_bf16 v[116:119], v[186:189], v[202:205], v[116:119]
	v_mfma_f32_16x16x32_bf16 v[112:115], v[194:197], v[202:205], v[112:115]
	v_mfma_f32_16x16x32_bf16 v[100:103], v[186:189], v[210:213], v[100:103]
	v_mfma_f32_16x16x32_bf16 v[96:99], v[194:197], v[210:213], v[96:99]
	v_mfma_f32_16x16x32_bf16 v[84:87], v[186:189], v[218:221], v[84:87]
	v_mfma_f32_16x16x32_bf16 v[80:83], v[194:197], v[218:221], v[80:83]
	v_mfma_f32_16x16x32_bf16 v[68:71], v[186:189], v[226:229], v[68:71]
	v_mfma_f32_16x16x32_bf16 v[64:67], v[194:197], v[226:229], v[64:67]
	s_setprio 0
	s_barrier
	s_add_u32 vcc_hi, vcc_hi, 0x100
	s_addc_u32 s53, s53, 0
	s_add_u32 s92, s92, 0x100
	s_addc_u32 s93, s93, 0
	s_cmp_ge_u32 s94, s97
	s_mov_b32 s14, s94
	s_cbranch_scc0 .LBB0_778
	s_and_b64 vcc, exec, s[76:77]
	s_cbranch_vccz .LBB0_781
	s_barrier

.LBB0_910:
	v_add_u32_e32 v155, s62, v149
	ds_read_b128 v[164:167], v155
	ds_read_b128 v[168:171], v155 offset:1024
	ds_read_b128 v[172:175], v155 offset:2048
	ds_read_b128 v[176:179], v155 offset:3072
	v_add_u32_e32 v155, s63, v149
	ds_read_b128 v[186:189], v155
	ds_read_b128 v[190:193], v155 offset:1024
	ds_read_b128 v[194:197], v155 offset:2048
	ds_read_b128 v[198:201], v155 offset:3072
	s_add_u32 s24, s78, 0xfff80080
	s_addc_u32 s25, s79, -1
	s_and_b64 s[14:15], s[14:15], exec
	s_cselect_b32 s25, s26, s25
	s_cselect_b32 s24, s27, s24
	s_cselect_b32 s15, s17, s67
	s_cselect_b32 s14, s35, s66
	v_lshl_add_u64 v[180:181], s[78:79], 0, v[138:139]
	s_add_i32 m0, s53, 0xc000
	ds_read_b128 v[202:205], v153
	ds_read_b128 v[206:209], v153 offset:1024
	ds_read_b128 v[210:213], v153 offset:2048
	ds_read_b128 v[214:217], v153 offset:3072
	ds_read_b128 v[218:221], v153 offset:4096
	ds_read_b128 v[222:225], v153 offset:5120
	ds_read_b128 v[226:229], v153 offset:6144
	ds_read_b128 v[230:233], v153 offset:7168
	global_load_lds_dwordx4 v[180:181], off
	v_lshl_add_u64 v[180:181], s[78:79], 0, v[136:137]
	s_add_i32 m0, s53, 0xe000
	s_nop 0
	global_load_lds_dwordx4 v[180:181], off
	s_waitcnt vmcnt(8)
	s_waitcnt lgkmcnt(0)
	s_barrier
	s_setprio 1
	s_waitcnt lgkmcnt(0)
	v_mfma_f32_16x16x32_bf16 v[124:127], v[164:167], v[202:205], v[124:127]
	v_mfma_f32_16x16x32_bf16 v[120:123], v[172:175], v[202:205], v[120:123]
	v_mfma_f32_16x16x32_bf16 v[116:119], v[164:167], v[210:213], v[116:119]
	v_mfma_f32_16x16x32_bf16 v[112:115], v[172:175], v[210:213], v[112:115]
	v_mfma_f32_16x16x32_bf16 v[100:103], v[164:167], v[218:221], v[100:103]
	v_mfma_f32_16x16x32_bf16 v[96:99], v[172:175], v[218:221], v[96:99]
	v_mfma_f32_16x16x32_bf16 v[84:87], v[164:167], v[226:229], v[84:87]
	v_mfma_f32_16x16x32_bf16 v[80:83], v[172:175], v[226:229], v[80:83]
	v_mfma_f32_16x16x32_bf16 v[124:127], v[168:171], v[206:209], v[124:127]
	v_mfma_f32_16x16x32_bf16 v[120:123], v[176:179], v[206:209], v[120:123]
	v_mfma_f32_16x16x32_bf16 v[116:119], v[168:171], v[214:217], v[116:119]
	v_mfma_f32_16x16x32_bf16 v[112:115], v[176:179], v[214:217], v[112:115]
	v_mfma_f32_16x16x32_bf16 v[100:103], v[168:171], v[222:225], v[100:103]
	v_mfma_f32_16x16x32_bf16 v[96:99], v[176:179], v[222:225], v[96:99]
	v_mfma_f32_16x16x32_bf16 v[84:87], v[168:171], v[230:233], v[84:87]
	v_mfma_f32_16x16x32_bf16 v[80:83], v[176:179], v[230:233], v[80:83]
	v_mfma_f32_16x16x32_bf16 v[108:111], v[186:189], v[202:205], v[108:111]
	v_mfma_f32_16x16x32_bf16 v[104:107], v[194:197], v[202:205], v[104:107]
	v_mfma_f32_16x16x32_bf16 v[92:95], v[186:189], v[210:213], v[92:95]
	v_mfma_f32_16x16x32_bf16 v[88:91], v[194:197], v[210:213], v[88:91]
	v_mfma_f32_16x16x32_bf16 v[76:79], v[186:189], v[218:221], v[76:79]
	v_mfma_f32_16x16x32_bf16 v[72:75], v[194:197], v[218:221], v[72:75]
	v_mfma_f32_16x16x32_bf16 v[68:71], v[186:189], v[226:229], v[68:71]
	v_mfma_f32_16x16x32_bf16 v[64:67], v[194:197], v[226:229], v[64:67]
	v_mfma_f32_16x16x32_bf16 v[108:111], v[190:193], v[206:209], v[108:111]
	v_mfma_f32_16x16x32_bf16 v[104:107], v[198:201], v[206:209], v[104:107]
	v_mfma_f32_16x16x32_bf16 v[92:95], v[190:193], v[214:217], v[92:95]
	v_mfma_f32_16x16x32_bf16 v[88:91], v[198:201], v[214:217], v[88:91]
	v_mfma_f32_16x16x32_bf16 v[76:79], v[190:193], v[222:225], v[76:79]
	v_mfma_f32_16x16x32_bf16 v[72:75], v[198:201], v[222:225], v[72:75]
	v_mfma_f32_16x16x32_bf16 v[68:71], v[190:193], v[230:233], v[68:71]
	v_mfma_f32_16x16x32_bf16 v[64:67], v[198:201], v[230:233], v[64:67]
	s_setprio 0
	s_barrier
	s_add_i32 s75, s62, s52
	v_lshl_add_u64 v[180:181], s[14:15], 0, v[130:131]
	s_mov_b32 m0, s75
	ds_read_b128 v[202:205], v153 offset:16384
	ds_read_b128 v[206:209], v153 offset:17408
	ds_read_b128 v[210:213], v153 offset:18432
	ds_read_b128 v[214:217], v153 offset:19456
	ds_read_b128 v[218:221], v153 offset:20480
	ds_read_b128 v[222:225], v153 offset:21504
	ds_read_b128 v[226:229], v153 offset:22528
	ds_read_b128 v[230:233], v153 offset:23552
	global_load_lds_dwordx4 v[180:181], off
	s_add_i32 m0, s75, 0x2000
	s_add_u32 s80, s14, 0x80000
	v_lshl_add_u64 v[234:235], s[14:15], 0, v[134:135]
	s_addc_u32 s81, s15, 0
	s_add_i32 s75, s63, s52
	global_load_lds_dwordx4 v[234:235], off
	v_lshl_add_u64 v[236:237], s[80:81], 0, v[130:131]
	s_mov_b32 m0, s75
	v_lshl_add_u64 v[238:239], s[24:25], 0, v[132:133]
	global_load_lds_dwordx4 v[236:237], off
	v_lshl_add_u64 v[236:237], s[80:81], 0, v[134:135]
	s_add_i32 m0, s75, 0x2000
	s_nop 0
	global_load_lds_dwordx4 v[236:237], off
	v_lshl_add_u64 v[236:237], s[24:25], 0, v[128:129]
	s_mov_b32 m0, s53
	s_nop 0
	global_load_lds_dwordx4 v[236:237], off
	s_mov_b32 m0, s54
	s_nop 0
	global_load_lds_dwordx4 v[238:239], off
	s_waitcnt vmcnt(8)
	s_waitcnt lgkmcnt(0)
	s_barrier
	s_setprio 1
	s_waitcnt lgkmcnt(0)
	v_mfma_f32_16x16x32_bf16 v[60:63], v[164:167], v[202:205], v[60:63]
	v_mfma_f32_16x16x32_bf16 v[56:59], v[172:175], v[202:205], v[56:59]
	v_mfma_f32_16x16x32_bf16 v[52:55], v[164:167], v[210:213], v[52:55]
	v_mfma_f32_16x16x32_bf16 v[48:51], v[172:175], v[210:213], v[48:51]
	v_mfma_f32_16x16x32_bf16 v[36:39], v[164:167], v[218:221], v[36:39]
	v_mfma_f32_16x16x32_bf16 v[32:35], v[172:175], v[218:221], v[32:35]
	v_mfma_f32_16x16x32_bf16 v[20:23], v[164:167], v[226:229], v[20:23]
	v_mfma_f32_16x16x32_bf16 v[16:19], v[172:175], v[226:229], v[16:19]
	v_mfma_f32_16x16x32_bf16 v[60:63], v[168:171], v[206:209], v[60:63]
	v_mfma_f32_16x16x32_bf16 v[56:59], v[176:179], v[206:209], v[56:59]
	v_mfma_f32_16x16x32_bf16 v[52:55], v[168:171], v[214:217], v[52:55]
	v_mfma_f32_16x16x32_bf16 v[48:51], v[176:179], v[214:217], v[48:51]
	v_mfma_f32_16x16x32_bf16 v[36:39], v[168:171], v[222:225], v[36:39]
	v_mfma_f32_16x16x32_bf16 v[32:35], v[176:179], v[222:225], v[32:35]
	v_mfma_f32_16x16x32_bf16 v[20:23], v[168:171], v[230:233], v[20:23]
	v_mfma_f32_16x16x32_bf16 v[16:19], v[176:179], v[230:233], v[16:19]
	v_mfma_f32_16x16x32_bf16 v[44:47], v[186:189], v[202:205], v[44:47]
	v_mfma_f32_16x16x32_bf16 v[40:43], v[194:197], v[202:205], v[40:43]
	v_mfma_f32_16x16x32_bf16 v[28:31], v[186:189], v[210:213], v[28:31]
	v_mfma_f32_16x16x32_bf16 v[24:27], v[194:197], v[210:213], v[24:27]
	v_mfma_f32_16x16x32_bf16 v[12:15], v[186:189], v[218:221], v[12:15]
	v_mfma_f32_16x16x32_bf16 v[8:11], v[194:197], v[218:221], v[8:11]
	v_mfma_f32_16x16x32_bf16 v[4:7], v[186:189], v[226:229], v[4:7]
	v_mfma_f32_16x16x32_bf16 v[0:3], v[194:197], v[226:229], v[0:3]
	v_mfma_f32_16x16x32_bf16 v[44:47], v[190:193], v[206:209], v[44:47]
	v_mfma_f32_16x16x32_bf16 v[40:43], v[198:201], v[206:209], v[40:43]
	v_mfma_f32_16x16x32_bf16 v[28:31], v[190:193], v[214:217], v[28:31]
	v_mfma_f32_16x16x32_bf16 v[24:27], v[198:201], v[214:217], v[24:27]
	v_mfma_f32_16x16x32_bf16 v[12:15], v[190:193], v[222:225], v[12:15]
	v_mfma_f32_16x16x32_bf16 v[8:11], v[198:201], v[222:225], v[8:11]
	v_mfma_f32_16x16x32_bf16 v[4:7], v[190:193], v[230:233], v[4:7]
	v_mfma_f32_16x16x32_bf16 v[0:3], v[198:201], v[230:233], v[0:3]
	s_setprio 0
	s_barrier
	s_add_i32 s75, 16, 0x18000
	v_add_u32_e32 v155, s75, v149
	s_add_i32 s80, 16, 0x1c000
	ds_read_b128 v[164:167], v155
	ds_read_b128 v[168:171], v155 offset:1024
	ds_read_b128 v[172:175], v155 offset:2048
	ds_read_b128 v[176:179], v155 offset:3072
	v_add_u32_e32 v155, s80, v149
	ds_read_b128 v[186:189], v155
	ds_read_b128 v[190:193], v155 offset:1024
	ds_read_b128 v[194:197], v155 offset:2048
	ds_read_b128 v[198:201], v155 offset:3072
	s_add_u32 s24, s24, 0x80000
	s_addc_u32 s25, s25, 0
	s_mov_b32 m0, s55
	v_lshl_add_u64 v[240:241], s[24:25], 0, v[128:129]
	ds_read_b128 v[202:205], v153 offset:32768
	ds_read_b128 v[206:209], v153 offset:33792
	ds_read_b128 v[210:213], v153 offset:34816
	ds_read_b128 v[214:217], v153 offset:35840
	ds_read_b128 v[218:221], v153 offset:36864
	ds_read_b128 v[222:225], v153 offset:37888
	ds_read_b128 v[226:229], v153 offset:38912
	ds_read_b128 v[230:233], v153 offset:39936
	global_load_lds_dwordx4 v[240:241], off
	v_lshl_add_u64 v[240:241], s[24:25], 0, v[132:133]
	s_mov_b32 m0, s56
	s_nop 0
	global_load_lds_dwordx4 v[240:241], off
	s_waitcnt vmcnt(8)
	s_waitcnt lgkmcnt(0)
	s_barrier
	s_setprio 1
	s_waitcnt lgkmcnt(0)
	v_mfma_f32_16x16x32_bf16 v[124:127], v[164:167], v[202:205], v[124:127]
	v_mfma_f32_16x16x32_bf16 v[120:123], v[172:175], v[202:205], v[120:123]
	v_mfma_f32_16x16x32_bf16 v[116:119], v[164:167], v[210:213], v[116:119]
	v_mfma_f32_16x16x32_bf16 v[112:115], v[172:175], v[210:213], v[112:115]
	v_mfma_f32_16x16x32_bf16 v[100:103], v[164:167], v[218:221], v[100:103]
	v_mfma_f32_16x16x32_bf16 v[96:99], v[172:175], v[218:221], v[96:99]
	v_mfma_f32_16x16x32_bf16 v[84:87], v[164:167], v[226:229], v[84:87]
	v_mfma_f32_16x16x32_bf16 v[80:83], v[172:175], v[226:229], v[80:83]
	v_mfma_f32_16x16x32_bf16 v[124:127], v[168:171], v[206:209], v[124:127]
	v_mfma_f32_16x16x32_bf16 v[120:123], v[176:179], v[206:209], v[120:123]
	v_mfma_f32_16x16x32_bf16 v[116:119], v[168:171], v[214:217], v[116:119]
	v_mfma_f32_16x16x32_bf16 v[112:115], v[176:179], v[214:217], v[112:115]
	v_mfma_f32_16x16x32_bf16 v[100:103], v[168:171], v[222:225], v[100:103]
	v_mfma_f32_16x16x32_bf16 v[96:99], v[176:179], v[222:225], v[96:99]
	v_mfma_f32_16x16x32_bf16 v[84:87], v[168:171], v[230:233], v[84:87]
	v_mfma_f32_16x16x32_bf16 v[80:83], v[176:179], v[230:233], v[80:83]
	v_mfma_f32_16x16x32_bf16 v[108:111], v[186:189], v[202:205], v[108:111]
	v_mfma_f32_16x16x32_bf16 v[104:107], v[194:197], v[202:205], v[104:107]
	v_mfma_f32_16x16x32_bf16 v[92:95], v[186:189], v[210:213], v[92:95]
	v_mfma_f32_16x16x32_bf16 v[88:91], v[194:197], v[210:213], v[88:91]
	v_mfma_f32_16x16x32_bf16 v[76:79], v[186:189], v[218:221], v[76:79]
	v_mfma_f32_16x16x32_bf16 v[72:75], v[194:197], v[218:221], v[72:75]
	v_mfma_f32_16x16x32_bf16 v[68:71], v[186:189], v[226:229], v[68:71]
	v_mfma_f32_16x16x32_bf16 v[64:67], v[194:197], v[226:229], v[64:67]
	v_mfma_f32_16x16x32_bf16 v[108:111], v[190:193], v[206:209], v[108:111]
	v_mfma_f32_16x16x32_bf16 v[104:107], v[198:201], v[206:209], v[104:107]
	v_mfma_f32_16x16x32_bf16 v[92:95], v[190:193], v[214:217], v[92:95]
	v_mfma_f32_16x16x32_bf16 v[88:91], v[198:201], v[214:217], v[88:91]
	v_mfma_f32_16x16x32_bf16 v[76:79], v[190:193], v[222:225], v[76:79]
	v_mfma_f32_16x16x32_bf16 v[72:75], v[198:201], v[222:225], v[72:75]
	v_mfma_f32_16x16x32_bf16 v[68:71], v[190:193], v[230:233], v[68:71]
	v_mfma_f32_16x16x32_bf16 v[64:67], v[198:201], v[230:233], v[64:67]
	s_setprio 0
	s_barrier
	s_add_i32 s24, s75, s52
	v_lshl_add_u64 v[180:181], v[180:181], 0, s[10:11]
	s_mov_b32 m0, s24
	ds_read_b128 v[202:205], v153 offset:49152
	ds_read_b128 v[206:209], v153 offset:50176
	ds_read_b128 v[210:213], v153 offset:51200
	ds_read_b128 v[214:217], v153 offset:52224
	ds_read_b128 v[218:221], v153 offset:53248
	ds_read_b128 v[222:225], v153 offset:54272
	ds_read_b128 v[226:229], v153 offset:55296
	ds_read_b128 v[230:233], v153 offset:56320
	global_load_lds_dwordx4 v[180:181], off
	s_add_i32 m0, s24, 0x2000
	s_add_u32 s14, s14, 0x80080
	v_lshl_add_u64 v[180:181], v[234:235], 0, s[10:11]
	s_addc_u32 s15, s15, 0
	s_add_i32 s24, s80, s52
	global_load_lds_dwordx4 v[180:181], off
	v_lshl_add_u64 v[180:181], s[14:15], 0, v[130:131]
	s_mov_b32 m0, s24
	s_nop 0
	global_load_lds_dwordx4 v[180:181], off
	v_lshl_add_u64 v[180:181], s[14:15], 0, v[134:135]
	s_add_i32 m0, s24, 0x2000
	s_nop 0
	global_load_lds_dwordx4 v[180:181], off
	v_lshl_add_u64 v[180:181], v[236:237], 0, s[10:11]
	s_mov_b32 m0, s58
	s_nop 0
	global_load_lds_dwordx4 v[180:181], off
	v_lshl_add_u64 v[180:181], v[238:239], 0, s[10:11]
	s_mov_b32 m0, s59
	s_nop 0
	global_load_lds_dwordx4 v[180:181], off
	s_waitcnt vmcnt(8)
	s_waitcnt lgkmcnt(0)
	s_barrier
	s_setprio 1
	s_waitcnt lgkmcnt(0)
	v_mfma_f32_16x16x32_bf16 v[60:63], v[164:167], v[202:205], v[60:63]
	v_mfma_f32_16x16x32_bf16 v[56:59], v[172:175], v[202:205], v[56:59]
	v_mfma_f32_16x16x32_bf16 v[52:55], v[164:167], v[210:213], v[52:55]
	v_mfma_f32_16x16x32_bf16 v[48:51], v[172:175], v[210:213], v[48:51]
	v_mfma_f32_16x16x32_bf16 v[36:39], v[164:167], v[218:221], v[36:39]
	v_mfma_f32_16x16x32_bf16 v[32:35], v[172:175], v[218:221], v[32:35]
	v_mfma_f32_16x16x32_bf16 v[20:23], v[164:167], v[226:229], v[20:23]
	v_mfma_f32_16x16x32_bf16 v[16:19], v[172:175], v[226:229], v[16:19]
	v_mfma_f32_16x16x32_bf16 v[60:63], v[168:171], v[206:209], v[60:63]
	v_mfma_f32_16x16x32_bf16 v[56:59], v[176:179], v[206:209], v[56:59]
	v_mfma_f32_16x16x32_bf16 v[52:55], v[168:171], v[214:217], v[52:55]
	v_mfma_f32_16x16x32_bf16 v[48:51], v[176:179], v[214:217], v[48:51]
	v_mfma_f32_16x16x32_bf16 v[36:39], v[168:171], v[222:225], v[36:39]
	v_mfma_f32_16x16x32_bf16 v[32:35], v[176:179], v[222:225], v[32:35]
	v_mfma_f32_16x16x32_bf16 v[20:23], v[168:171], v[230:233], v[20:23]
	v_mfma_f32_16x16x32_bf16 v[16:19], v[176:179], v[230:233], v[16:19]
	v_mfma_f32_16x16x32_bf16 v[44:47], v[186:189], v[202:205], v[44:47]
	v_mfma_f32_16x16x32_bf16 v[40:43], v[194:197], v[202:205], v[40:43]
	v_mfma_f32_16x16x32_bf16 v[28:31], v[186:189], v[210:213], v[28:31]
	v_mfma_f32_16x16x32_bf16 v[24:27], v[194:197], v[210:213], v[24:27]
	v_mfma_f32_16x16x32_bf16 v[12:15], v[186:189], v[218:221], v[12:15]
	v_mfma_f32_16x16x32_bf16 v[8:11], v[194:197], v[218:221], v[8:11]
	v_mfma_f32_16x16x32_bf16 v[4:7], v[186:189], v[226:229], v[4:7]
	v_mfma_f32_16x16x32_bf16 v[0:3], v[194:197], v[226:229], v[0:3]
	v_mfma_f32_16x16x32_bf16 v[44:47], v[190:193], v[206:209], v[44:47]
	v_mfma_f32_16x16x32_bf16 v[40:43], v[198:201], v[206:209], v[40:43]
	v_mfma_f32_16x16x32_bf16 v[28:31], v[190:193], v[214:217], v[28:31]
	v_mfma_f32_16x16x32_bf16 v[24:27], v[198:201], v[214:217], v[24:27]
	v_mfma_f32_16x16x32_bf16 v[12:15], v[190:193], v[222:225], v[12:15]
	v_mfma_f32_16x16x32_bf16 v[8:11], v[198:201], v[222:225], v[8:11]
	v_mfma_f32_16x16x32_bf16 v[4:7], v[190:193], v[230:233], v[4:7]
	v_mfma_f32_16x16x32_bf16 v[0:3], v[198:201], v[230:233], v[0:3]
	s_setprio 0
	s_barrier
	s_add_i32 s74, s74, 2
	s_add_u32 s66, s66, 0x100
	s_addc_u32 s67, s67, 0
	s_add_u32 s78, s78, 0x100
	s_addc_u32 s79, s79, 0
	s_cmp_gt_u32 s74, 29
	s_cbranch_scc1 .LBB0_913

.LBB0_1042:
	ds_read_b128 v[152:155], v139
	ds_read_b128 v[166:169], v139 offset:1024
	ds_read_b128 v[170:173], v139 offset:2048
	ds_read_b128 v[174:177], v139 offset:3072
	ds_read_b128 v[178:181], v161
	ds_read_b128 v[186:189], v161 offset:1024
	ds_read_b128 v[190:193], v161 offset:2048
	ds_read_b128 v[194:197], v161 offset:3072
	s_add_i32 s67, s14, 2
	s_add_u32 s8, s0, 0x100
	s_addc_u32 s9, s1, 0
	s_cmp_eq_u32 s60, s14
	s_cselect_b32 s14, s72, s61
	s_cselect_b32 s77, s65, s9
	s_cselect_b32 s76, s64, s8
	s_cselect_b32 s15, s73, s66
	v_lshl_add_u64 v[156:157], s[0:1], 0, v[150:151]
	s_add_i32 m0, s54, 0xc000
	ds_read_b128 v[198:201], v162
	ds_read_b128 v[202:205], v162 offset:1024
	ds_read_b128 v[206:209], v162 offset:2048
	ds_read_b128 v[210:213], v162 offset:3072
	ds_read_b128 v[214:217], v162 offset:4096
	ds_read_b128 v[218:221], v162 offset:5120
	ds_read_b128 v[222:225], v162 offset:6144
	ds_read_b128 v[226:229], v162 offset:7168
	global_load_lds_dwordx4 v[156:157], off
	v_lshl_add_u64 v[156:157], s[0:1], 0, v[148:149]
	s_add_i32 m0, s54, 0xe000
	s_nop 0
	global_load_lds_dwordx4 v[156:157], off
	s_waitcnt vmcnt(8)
	s_waitcnt lgkmcnt(0)
	s_barrier
	s_setprio 1
	s_waitcnt lgkmcnt(0)
	v_mfma_f32_16x16x32_bf16 v[60:63], v[152:155], v[198:201], v[60:63]
	v_mfma_f32_16x16x32_bf16 v[56:59], v[170:173], v[198:201], v[56:59]
	v_mfma_f32_16x16x32_bf16 v[52:55], v[152:155], v[206:209], v[52:55]
	v_mfma_f32_16x16x32_bf16 v[48:51], v[170:173], v[206:209], v[48:51]
	v_mfma_f32_16x16x32_bf16 v[44:47], v[152:155], v[214:217], v[44:47]
	v_mfma_f32_16x16x32_bf16 v[40:43], v[170:173], v[214:217], v[40:43]
	v_mfma_f32_16x16x32_bf16 v[28:31], v[152:155], v[222:225], v[28:31]
	v_mfma_f32_16x16x32_bf16 v[24:27], v[170:173], v[222:225], v[24:27]
	v_mfma_f32_16x16x32_bf16 v[60:63], v[166:169], v[202:205], v[60:63]
	v_mfma_f32_16x16x32_bf16 v[56:59], v[174:177], v[202:205], v[56:59]
	v_mfma_f32_16x16x32_bf16 v[52:55], v[166:169], v[210:213], v[52:55]
	v_mfma_f32_16x16x32_bf16 v[48:51], v[174:177], v[210:213], v[48:51]
	v_mfma_f32_16x16x32_bf16 v[44:47], v[166:169], v[218:221], v[44:47]
	v_mfma_f32_16x16x32_bf16 v[40:43], v[174:177], v[218:221], v[40:43]
	v_mfma_f32_16x16x32_bf16 v[28:31], v[166:169], v[226:229], v[28:31]
	v_mfma_f32_16x16x32_bf16 v[24:27], v[174:177], v[226:229], v[24:27]
	v_mfma_f32_16x16x32_bf16 v[36:39], v[178:181], v[198:201], v[36:39]
	v_mfma_f32_16x16x32_bf16 v[32:35], v[190:193], v[198:201], v[32:35]
	v_mfma_f32_16x16x32_bf16 v[20:23], v[178:181], v[206:209], v[20:23]
	v_mfma_f32_16x16x32_bf16 v[16:19], v[190:193], v[206:209], v[16:19]
	v_mfma_f32_16x16x32_bf16 v[12:15], v[178:181], v[214:217], v[12:15]
	v_mfma_f32_16x16x32_bf16 v[8:11], v[190:193], v[214:217], v[8:11]
	v_mfma_f32_16x16x32_bf16 v[4:7], v[178:181], v[222:225], v[4:7]
	v_mfma_f32_16x16x32_bf16 v[0:3], v[190:193], v[222:225], v[0:3]
	v_mfma_f32_16x16x32_bf16 v[36:39], v[186:189], v[202:205], v[36:39]
	v_mfma_f32_16x16x32_bf16 v[32:35], v[194:197], v[202:205], v[32:35]
	v_mfma_f32_16x16x32_bf16 v[20:23], v[186:189], v[210:213], v[20:23]
	v_mfma_f32_16x16x32_bf16 v[16:19], v[194:197], v[210:213], v[16:19]
	v_mfma_f32_16x16x32_bf16 v[12:15], v[186:189], v[218:221], v[12:15]
	v_mfma_f32_16x16x32_bf16 v[8:11], v[194:197], v[218:221], v[8:11]
	v_mfma_f32_16x16x32_bf16 v[4:7], v[186:189], v[226:229], v[4:7]
	v_mfma_f32_16x16x32_bf16 v[0:3], v[194:197], v[226:229], v[0:3]
	s_setprio 0
	s_barrier
	s_add_i32 s0, s85, s53
	v_lshl_add_u64 v[156:157], s[14:15], 0, v[130:131]
	s_mov_b32 m0, s0
	ds_read_b128 v[198:201], v162 offset:16384
	ds_read_b128 v[202:205], v162 offset:17408
	ds_read_b128 v[206:209], v162 offset:18432
	ds_read_b128 v[210:213], v162 offset:19456
	ds_read_b128 v[214:217], v162 offset:20480
	ds_read_b128 v[218:221], v162 offset:21504
	ds_read_b128 v[222:225], v162 offset:22528
	ds_read_b128 v[226:229], v162 offset:23552
	global_load_lds_dwordx4 v[156:157], off
	s_add_i32 m0, s0, 0x2000
	s_add_u32 s0, s14, 0x160000
	v_lshl_add_u64 v[230:231], s[14:15], 0, v[134:135]
	s_addc_u32 s1, s15, 0
	s_add_i32 vcc_lo, s86, s53
	global_load_lds_dwordx4 v[230:231], off
	v_lshl_add_u64 v[232:233], s[0:1], 0, v[130:131]
	s_mov_b32 m0, vcc_lo
	v_lshl_add_u64 v[234:235], s[76:77], 0, v[132:133]
	global_load_lds_dwordx4 v[232:233], off
	v_lshl_add_u64 v[232:233], s[0:1], 0, v[134:135]
	s_add_i32 m0, vcc_lo, 0x2000
	s_nop 0
	global_load_lds_dwordx4 v[232:233], off
	v_lshl_add_u64 v[232:233], s[76:77], 0, v[128:129]
	s_mov_b32 m0, s54
	s_nop 0
	global_load_lds_dwordx4 v[232:233], off
	s_mov_b32 m0, s55
	s_nop 0
	global_load_lds_dwordx4 v[234:235], off
	s_waitcnt vmcnt(8)
	s_waitcnt lgkmcnt(0)
	s_barrier
	s_setprio 1
	s_waitcnt lgkmcnt(0)
	v_mfma_f32_16x16x32_bf16 v[120:123], v[152:155], v[198:201], v[120:123]
	v_mfma_f32_16x16x32_bf16 v[124:127], v[170:173], v[198:201], v[124:127]
	v_mfma_f32_16x16x32_bf16 v[104:107], v[152:155], v[206:209], v[104:107]
	v_mfma_f32_16x16x32_bf16 v[108:111], v[170:173], v[206:209], v[108:111]
	v_mfma_f32_16x16x32_bf16 v[88:91], v[152:155], v[214:217], v[88:91]
	v_mfma_f32_16x16x32_bf16 v[92:95], v[170:173], v[214:217], v[92:95]
	v_mfma_f32_16x16x32_bf16 v[72:75], v[152:155], v[222:225], v[72:75]
	v_mfma_f32_16x16x32_bf16 v[76:79], v[170:173], v[222:225], v[76:79]
	v_mfma_f32_16x16x32_bf16 v[120:123], v[166:169], v[202:205], v[120:123]
	v_mfma_f32_16x16x32_bf16 v[124:127], v[174:177], v[202:205], v[124:127]
	v_mfma_f32_16x16x32_bf16 v[104:107], v[166:169], v[210:213], v[104:107]
	v_mfma_f32_16x16x32_bf16 v[108:111], v[174:177], v[210:213], v[108:111]
	v_mfma_f32_16x16x32_bf16 v[88:91], v[166:169], v[218:221], v[88:91]
	v_mfma_f32_16x16x32_bf16 v[92:95], v[174:177], v[218:221], v[92:95]
	v_mfma_f32_16x16x32_bf16 v[72:75], v[166:169], v[226:229], v[72:75]
	v_mfma_f32_16x16x32_bf16 v[76:79], v[174:177], v[226:229], v[76:79]
	v_mfma_f32_16x16x32_bf16 v[116:119], v[178:181], v[198:201], v[116:119]
	v_mfma_f32_16x16x32_bf16 v[112:115], v[190:193], v[198:201], v[112:115]
	v_mfma_f32_16x16x32_bf16 v[100:103], v[178:181], v[206:209], v[100:103]
	v_mfma_f32_16x16x32_bf16 v[96:99], v[190:193], v[206:209], v[96:99]
	v_mfma_f32_16x16x32_bf16 v[84:87], v[178:181], v[214:217], v[84:87]
	v_mfma_f32_16x16x32_bf16 v[80:83], v[190:193], v[214:217], v[80:83]
	v_mfma_f32_16x16x32_bf16 v[68:71], v[178:181], v[222:225], v[68:71]
	v_mfma_f32_16x16x32_bf16 v[64:67], v[190:193], v[222:225], v[64:67]
	v_mfma_f32_16x16x32_bf16 v[116:119], v[186:189], v[202:205], v[116:119]
	v_mfma_f32_16x16x32_bf16 v[112:115], v[194:197], v[202:205], v[112:115]
	v_mfma_f32_16x16x32_bf16 v[100:103], v[186:189], v[210:213], v[100:103]
	v_mfma_f32_16x16x32_bf16 v[96:99], v[194:197], v[210:213], v[96:99]
	v_mfma_f32_16x16x32_bf16 v[84:87], v[186:189], v[218:221], v[84:87]
	v_mfma_f32_16x16x32_bf16 v[80:83], v[194:197], v[218:221], v[80:83]
	v_mfma_f32_16x16x32_bf16 v[68:71], v[186:189], v[226:229], v[68:71]
	v_mfma_f32_16x16x32_bf16 v[64:67], v[194:197], v[226:229], v[64:67]
	s_setprio 0
	s_barrier
	s_add_i32 vcc_lo, 16, 0x18000
	v_add_u32_e32 v136, vcc_lo, v159
	s_add_i32 vcc_hi, 16, 0x1c000
	ds_read_b128 v[152:155], v136
	ds_read_b128 v[166:169], v136 offset:1024
	ds_read_b128 v[170:173], v136 offset:2048
	ds_read_b128 v[174:177], v136 offset:3072
	v_add_u32_e32 v136, vcc_hi, v159
	ds_read_b128 v[178:181], v136
	ds_read_b128 v[186:189], v136 offset:1024
	ds_read_b128 v[190:193], v136 offset:2048
	ds_read_b128 v[194:197], v136 offset:3072
	s_add_u32 s0, s76, 0x160000
	s_addc_u32 s1, s77, 0
	s_mov_b32 m0, s74
	v_lshl_add_u64 v[236:237], s[0:1], 0, v[128:129]
	ds_read_b128 v[198:201], v162 offset:32768
	ds_read_b128 v[202:205], v162 offset:33792
	ds_read_b128 v[206:209], v162 offset:34816
	ds_read_b128 v[210:213], v162 offset:35840
	ds_read_b128 v[214:217], v162 offset:36864
	ds_read_b128 v[218:221], v162 offset:37888
	ds_read_b128 v[222:225], v162 offset:38912
	ds_read_b128 v[226:229], v162 offset:39936
	global_load_lds_dwordx4 v[236:237], off
	v_lshl_add_u64 v[236:237], s[0:1], 0, v[132:133]
	s_mov_b32 m0, s75
	s_nop 0
	global_load_lds_dwordx4 v[236:237], off
	s_waitcnt vmcnt(8)
	s_waitcnt lgkmcnt(0)
	s_barrier
	s_setprio 1
	s_waitcnt lgkmcnt(0)
	v_mfma_f32_16x16x32_bf16 v[60:63], v[152:155], v[198:201], v[60:63]
	v_mfma_f32_16x16x32_bf16 v[56:59], v[170:173], v[198:201], v[56:59]
	v_mfma_f32_16x16x32_bf16 v[52:55], v[152:155], v[206:209], v[52:55]
	v_mfma_f32_16x16x32_bf16 v[48:51], v[170:173], v[206:209], v[48:51]
	v_mfma_f32_16x16x32_bf16 v[44:47], v[152:155], v[214:217], v[44:47]
	v_mfma_f32_16x16x32_bf16 v[40:43], v[170:173], v[214:217], v[40:43]
	v_mfma_f32_16x16x32_bf16 v[28:31], v[152:155], v[222:225], v[28:31]
	v_mfma_f32_16x16x32_bf16 v[24:27], v[170:173], v[222:225], v[24:27]
	v_mfma_f32_16x16x32_bf16 v[60:63], v[166:169], v[202:205], v[60:63]
	v_mfma_f32_16x16x32_bf16 v[56:59], v[174:177], v[202:205], v[56:59]
	v_mfma_f32_16x16x32_bf16 v[52:55], v[166:169], v[210:213], v[52:55]
	v_mfma_f32_16x16x32_bf16 v[48:51], v[174:177], v[210:213], v[48:51]
	v_mfma_f32_16x16x32_bf16 v[44:47], v[166:169], v[218:221], v[44:47]
	v_mfma_f32_16x16x32_bf16 v[40:43], v[174:177], v[218:221], v[40:43]
	v_mfma_f32_16x16x32_bf16 v[28:31], v[166:169], v[226:229], v[28:31]
	v_mfma_f32_16x16x32_bf16 v[24:27], v[174:177], v[226:229], v[24:27]
	v_mfma_f32_16x16x32_bf16 v[36:39], v[178:181], v[198:201], v[36:39]
	v_mfma_f32_16x16x32_bf16 v[32:35], v[190:193], v[198:201], v[32:35]
	v_mfma_f32_16x16x32_bf16 v[20:23], v[178:181], v[206:209], v[20:23]
	v_mfma_f32_16x16x32_bf16 v[16:19], v[190:193], v[206:209], v[16:19]
	v_mfma_f32_16x16x32_bf16 v[12:15], v[178:181], v[214:217], v[12:15]
	v_mfma_f32_16x16x32_bf16 v[8:11], v[190:193], v[214:217], v[8:11]
	v_mfma_f32_16x16x32_bf16 v[4:7], v[178:181], v[222:225], v[4:7]
	v_mfma_f32_16x16x32_bf16 v[0:3], v[190:193], v[222:225], v[0:3]
	v_mfma_f32_16x16x32_bf16 v[36:39], v[186:189], v[202:205], v[36:39]
	v_mfma_f32_16x16x32_bf16 v[32:35], v[194:197], v[202:205], v[32:35]
	v_mfma_f32_16x16x32_bf16 v[20:23], v[186:189], v[210:213], v[20:23]
	v_mfma_f32_16x16x32_bf16 v[16:19], v[194:197], v[210:213], v[16:19]
	v_mfma_f32_16x16x32_bf16 v[12:15], v[186:189], v[218:221], v[12:15]
	v_mfma_f32_16x16x32_bf16 v[8:11], v[194:197], v[218:221], v[8:11]
	v_mfma_f32_16x16x32_bf16 v[4:7], v[186:189], v[226:229], v[4:7]
	v_mfma_f32_16x16x32_bf16 v[0:3], v[194:197], v[226:229], v[0:3]
	s_setprio 0
	s_barrier
	s_add_i32 s0, vcc_lo, s53
	v_lshl_add_u64 v[156:157], v[156:157], 0, s[30:31]
	s_mov_b32 m0, s0
	ds_read_b128 v[198:201], v162 offset:49152
	ds_read_b128 v[202:205], v162 offset:50176
	ds_read_b128 v[206:209], v162 offset:51200
	ds_read_b128 v[210:213], v162 offset:52224
	ds_read_b128 v[214:217], v162 offset:53248
	ds_read_b128 v[218:221], v162 offset:54272
	ds_read_b128 v[222:225], v162 offset:55296
	ds_read_b128 v[226:229], v162 offset:56320
	global_load_lds_dwordx4 v[156:157], off
	s_add_i32 m0, s0, 0x2000
	s_add_u32 s0, s14, 0x160080
	v_lshl_add_u64 v[156:157], v[230:231], 0, s[30:31]
	s_addc_u32 s1, s15, 0
	s_add_i32 s14, vcc_hi, s53
	global_load_lds_dwordx4 v[156:157], off
	v_lshl_add_u64 v[156:157], s[0:1], 0, v[130:131]
	s_mov_b32 m0, s14
	s_nop 0
	global_load_lds_dwordx4 v[156:157], off
	v_lshl_add_u64 v[156:157], s[0:1], 0, v[134:135]
	s_add_i32 m0, s14, 0x2000
	s_nop 0
	global_load_lds_dwordx4 v[156:157], off
	v_lshl_add_u64 v[156:157], v[232:233], 0, s[30:31]
	s_mov_b32 m0, s83
	s_nop 0
	global_load_lds_dwordx4 v[156:157], off
	v_lshl_add_u64 v[156:157], v[234:235], 0, s[30:31]
	s_mov_b32 m0, s84
	s_nop 0
	global_load_lds_dwordx4 v[156:157], off
	s_waitcnt vmcnt(8)
	s_waitcnt lgkmcnt(0)
	s_barrier
	s_setprio 1
	s_waitcnt lgkmcnt(0)
	v_mfma_f32_16x16x32_bf16 v[120:123], v[152:155], v[198:201], v[120:123]
	v_mfma_f32_16x16x32_bf16 v[124:127], v[170:173], v[198:201], v[124:127]
	v_mfma_f32_16x16x32_bf16 v[104:107], v[152:155], v[206:209], v[104:107]
	v_mfma_f32_16x16x32_bf16 v[108:111], v[170:173], v[206:209], v[108:111]
	v_mfma_f32_16x16x32_bf16 v[88:91], v[152:155], v[214:217], v[88:91]
	v_mfma_f32_16x16x32_bf16 v[92:95], v[170:173], v[214:217], v[92:95]
	v_mfma_f32_16x16x32_bf16 v[72:75], v[152:155], v[222:225], v[72:75]
	v_mfma_f32_16x16x32_bf16 v[76:79], v[170:173], v[222:225], v[76:79]
	v_mfma_f32_16x16x32_bf16 v[120:123], v[166:169], v[202:205], v[120:123]
	v_mfma_f32_16x16x32_bf16 v[124:127], v[174:177], v[202:205], v[124:127]
	v_mfma_f32_16x16x32_bf16 v[104:107], v[166:169], v[210:213], v[104:107]
	v_mfma_f32_16x16x32_bf16 v[108:111], v[174:177], v[210:213], v[108:111]
	v_mfma_f32_16x16x32_bf16 v[88:91], v[166:169], v[218:221], v[88:91]
	v_mfma_f32_16x16x32_bf16 v[92:95], v[174:177], v[218:221], v[92:95]
	v_mfma_f32_16x16x32_bf16 v[72:75], v[166:169], v[226:229], v[72:75]
	v_mfma_f32_16x16x32_bf16 v[76:79], v[174:177], v[226:229], v[76:79]
	v_mfma_f32_16x16x32_bf16 v[116:119], v[178:181], v[198:201], v[116:119]
	v_mfma_f32_16x16x32_bf16 v[112:115], v[190:193], v[198:201], v[112:115]
	v_mfma_f32_16x16x32_bf16 v[100:103], v[178:181], v[206:209], v[100:103]
	v_mfma_f32_16x16x32_bf16 v[96:99], v[190:193], v[206:209], v[96:99]
	v_mfma_f32_16x16x32_bf16 v[84:87], v[178:181], v[214:217], v[84:87]
	v_mfma_f32_16x16x32_bf16 v[80:83], v[190:193], v[214:217], v[80:83]
	v_mfma_f32_16x16x32_bf16 v[68:71], v[178:181], v[222:225], v[68:71]
	v_mfma_f32_16x16x32_bf16 v[64:67], v[190:193], v[222:225], v[64:67]
	v_mfma_f32_16x16x32_bf16 v[116:119], v[186:189], v[202:205], v[116:119]
	v_mfma_f32_16x16x32_bf16 v[112:115], v[194:197], v[202:205], v[112:115]
	v_mfma_f32_16x16x32_bf16 v[100:103], v[186:189], v[210:213], v[100:103]
	v_mfma_f32_16x16x32_bf16 v[96:99], v[194:197], v[210:213], v[96:99]
	v_mfma_f32_16x16x32_bf16 v[84:87], v[186:189], v[218:221], v[84:87]
	v_mfma_f32_16x16x32_bf16 v[80:83], v[194:197], v[218:221], v[80:83]
	v_mfma_f32_16x16x32_bf16 v[68:71], v[186:189], v[226:229], v[68:71]
	v_mfma_f32_16x16x32_bf16 v[64:67], v[194:197], v[226:229], v[64:67]
	s_setprio 0
	s_barrier
	s_add_u32 s61, s61, 0x100
	s_addc_u32 s66, s66, 0
	s_cmp_ge_u32 s67, s59
	s_mov_b64 s[0:1], s[8:9]
	s_mov_b32 s14, s67
	s_cbranch_scc0 .LBB0_1042
	s_and_b64 vcc, exec, s[34:35]
	s_cbranch_vccz .LBB0_1045
	s_barrier

.LBB0_1176:
	v_add_u32_e32 v126, s21, v157
	ds_read_b128 v[122:125], v126
	ds_read_b128 v[136:139], v126 offset:1024
	ds_read_b128 v[140:143], v126 offset:2048
	ds_read_b128 v[192:195], v126 offset:3072
	v_add_u32_e32 v126, s33, v157
	ds_read_b128 v[196:199], v126
	ds_read_b128 v[200:203], v126 offset:1024
	ds_read_b128 v[204:207], v126 offset:2048
	ds_read_b128 v[208:211], v126 offset:3072
	s_add_u32 s12, s0, 0xfff80080
	s_addc_u32 s13, s1, -1
	s_and_b64 s[8:9], s[8:9], exec
	s_cselect_b32 s13, s5, s13
	s_cselect_b32 s12, s15, s12
	s_cselect_b32 s9, s34, s56
	s_cselect_b32 s8, s35, s52
	v_lshl_add_u64 v[126:127], s[0:1], 0, v[168:169]
	s_add_i32 m0, s96, 0xc000
	ds_read_b128 v[212:215], v177
	ds_read_b128 v[216:219], v177 offset:1024
	ds_read_b128 v[220:223], v177 offset:2048
	ds_read_b128 v[224:227], v177 offset:3072
	ds_read_b128 v[228:231], v177 offset:4096
	ds_read_b128 v[232:235], v177 offset:5120
	ds_read_b128 v[236:239], v177 offset:6144
	ds_read_b128 v[240:243], v177 offset:7168
	global_load_lds_dwordx4 v[126:127], off
	v_lshl_add_u64 v[126:127], s[0:1], 0, v[166:167]
	s_add_i32 m0, s96, 0xe000
	s_nop 0
	global_load_lds_dwordx4 v[126:127], off
	s_waitcnt vmcnt(8)
	s_waitcnt lgkmcnt(0)
	s_barrier
	s_setprio 1
	s_waitcnt lgkmcnt(0)
	v_mfma_f32_16x16x32_bf16 v[112:115], v[122:125], v[212:215], v[112:115]
	v_mfma_f32_16x16x32_bf16 v[116:119], v[140:143], v[212:215], v[116:119]
	v_mfma_f32_16x16x32_bf16 v[108:111], v[122:125], v[220:223], v[108:111]
	v_mfma_f32_16x16x32_bf16 v[100:103], v[140:143], v[220:223], v[100:103]
	v_mfma_f32_16x16x32_bf16 v[92:95], v[122:125], v[228:231], v[92:95]
	v_mfma_f32_16x16x32_bf16 v[84:87], v[140:143], v[228:231], v[84:87]
	v_mfma_f32_16x16x32_bf16 v[76:79], v[122:125], v[236:239], v[76:79]
	v_mfma_f32_16x16x32_bf16 v[68:71], v[140:143], v[236:239], v[68:71]
	v_mfma_f32_16x16x32_bf16 v[112:115], v[136:139], v[216:219], v[112:115]
	v_mfma_f32_16x16x32_bf16 v[116:119], v[192:195], v[216:219], v[116:119]
	v_mfma_f32_16x16x32_bf16 v[108:111], v[136:139], v[224:227], v[108:111]
	v_mfma_f32_16x16x32_bf16 v[100:103], v[192:195], v[224:227], v[100:103]
	v_mfma_f32_16x16x32_bf16 v[92:95], v[136:139], v[232:235], v[92:95]
	v_mfma_f32_16x16x32_bf16 v[84:87], v[192:195], v[232:235], v[84:87]
	v_mfma_f32_16x16x32_bf16 v[76:79], v[136:139], v[240:243], v[76:79]
	v_mfma_f32_16x16x32_bf16 v[68:71], v[192:195], v[240:243], v[68:71]
	v_mfma_f32_16x16x32_bf16 v[104:107], v[196:199], v[212:215], v[104:107]
	v_mfma_f32_16x16x32_bf16 v[96:99], v[204:207], v[212:215], v[96:99]
	v_mfma_f32_16x16x32_bf16 v[88:91], v[196:199], v[220:223], v[88:91]
	v_mfma_f32_16x16x32_bf16 v[80:83], v[204:207], v[220:223], v[80:83]
	v_mfma_f32_16x16x32_bf16 v[72:75], v[196:199], v[228:231], v[72:75]
	v_mfma_f32_16x16x32_bf16 v[64:67], v[204:207], v[228:231], v[64:67]
	v_mfma_f32_16x16x32_bf16 v[60:63], v[196:199], v[236:239], v[60:63]
	v_mfma_f32_16x16x32_bf16 v[56:59], v[204:207], v[236:239], v[56:59]
	v_mfma_f32_16x16x32_bf16 v[104:107], v[200:203], v[216:219], v[104:107]
	v_mfma_f32_16x16x32_bf16 v[96:99], v[208:211], v[216:219], v[96:99]
	v_mfma_f32_16x16x32_bf16 v[88:91], v[200:203], v[224:227], v[88:91]
	v_mfma_f32_16x16x32_bf16 v[80:83], v[208:211], v[224:227], v[80:83]
	v_mfma_f32_16x16x32_bf16 v[72:75], v[200:203], v[232:235], v[72:75]
	v_mfma_f32_16x16x32_bf16 v[64:67], v[208:211], v[232:235], v[64:67]
	v_mfma_f32_16x16x32_bf16 v[60:63], v[200:203], v[240:243], v[60:63]
	v_mfma_f32_16x16x32_bf16 v[56:59], v[208:211], v[240:243], v[56:59]
	s_setprio 0
	s_barrier
	s_add_i32 s58, s21, s74
	v_lshl_add_u64 v[244:245], s[8:9], 0, v[146:147]
	s_mov_b32 m0, s58
	ds_read_b128 v[212:215], v177 offset:16384
	ds_read_b128 v[216:219], v177 offset:17408
	ds_read_b128 v[220:223], v177 offset:18432
	ds_read_b128 v[224:227], v177 offset:19456
	ds_read_b128 v[228:231], v177 offset:20480
	ds_read_b128 v[232:235], v177 offset:21504
	ds_read_b128 v[236:239], v177 offset:22528
	ds_read_b128 v[240:243], v177 offset:23552
	global_load_lds_dwordx4 v[244:245], off
	s_add_i32 m0, s58, 0x2000
	s_add_u32 s58, s8, 0x80000
	v_lshl_add_u64 v[246:247], s[8:9], 0, v[150:151]
	s_addc_u32 s59, s9, 0
	s_add_i32 s60, s33, s74
	global_load_lds_dwordx4 v[246:247], off
	v_lshl_add_u64 v[126:127], s[58:59], 0, v[146:147]
	s_mov_b32 m0, s60
	v_lshl_add_u64 v[248:249], s[12:13], 0, v[144:145]
	global_load_lds_dwordx4 v[126:127], off
	v_lshl_add_u64 v[126:127], s[58:59], 0, v[150:151]
	s_add_i32 m0, s60, 0x2000
	v_lshl_add_u64 v[250:251], s[12:13], 0, v[148:149]
	global_load_lds_dwordx4 v[126:127], off
	s_mov_b32 m0, s96
	s_nop 0
	global_load_lds_dwordx4 v[248:249], off
	s_mov_b32 m0, s97
	s_nop 0
	global_load_lds_dwordx4 v[250:251], off
	s_waitcnt vmcnt(8)
	s_waitcnt lgkmcnt(0)
	s_barrier
	s_setprio 1
	s_waitcnt lgkmcnt(0)
	v_mfma_f32_16x16x32_bf16 v[52:55], v[122:125], v[212:215], v[52:55]
	v_mfma_f32_16x16x32_bf16 v[48:51], v[140:143], v[212:215], v[48:51]
	v_mfma_f32_16x16x32_bf16 v[44:47], v[122:125], v[220:223], v[44:47]
	v_mfma_f32_16x16x32_bf16 v[36:39], v[140:143], v[220:223], v[36:39]
	v_mfma_f32_16x16x32_bf16 v[28:31], v[122:125], v[228:231], v[28:31]
	v_mfma_f32_16x16x32_bf16 v[20:23], v[140:143], v[228:231], v[20:23]
	v_mfma_f32_16x16x32_bf16 v[126:129], v[140:143], v[236:239], v[128:131]
	v_mfma_f32_16x16x32_bf16 v[52:55], v[136:139], v[216:219], v[52:55]
	v_mfma_f32_16x16x32_bf16 v[48:51], v[192:195], v[216:219], v[48:51]
	v_mfma_f32_16x16x32_bf16 v[44:47], v[136:139], v[224:227], v[44:47]
	v_mfma_f32_16x16x32_bf16 v[36:39], v[192:195], v[224:227], v[36:39]
	v_mfma_f32_16x16x32_bf16 v[28:31], v[136:139], v[232:235], v[28:31]
	v_mfma_f32_16x16x32_bf16 v[20:23], v[192:195], v[232:235], v[20:23]
	v_mfma_f32_16x16x32_bf16 v[122:125], v[122:125], v[236:239], v[132:135]
	v_mfma_f32_16x16x32_bf16 v[126:129], v[192:195], v[240:243], v[126:129]
	v_mfma_f32_16x16x32_bf16 v[122:125], v[136:139], v[240:243], v[122:125]
	v_mfma_f32_16x16x32_bf16 v[40:43], v[196:199], v[212:215], v[40:43]
	v_mfma_f32_16x16x32_bf16 v[32:35], v[204:207], v[212:215], v[32:35]
	v_mfma_f32_16x16x32_bf16 v[24:27], v[196:199], v[220:223], v[24:27]
	v_mfma_f32_16x16x32_bf16 v[16:19], v[204:207], v[220:223], v[16:19]
	v_mfma_f32_16x16x32_bf16 v[12:15], v[196:199], v[228:231], v[12:15]
	v_mfma_f32_16x16x32_bf16 v[8:11], v[204:207], v[228:231], v[8:11]
	v_mfma_f32_16x16x32_bf16 v[4:7], v[196:199], v[236:239], v[4:7]
	v_mfma_f32_16x16x32_bf16 v[0:3], v[204:207], v[236:239], v[0:3]
	v_mfma_f32_16x16x32_bf16 v[40:43], v[200:203], v[216:219], v[40:43]
	v_mfma_f32_16x16x32_bf16 v[32:35], v[208:211], v[216:219], v[32:35]
	v_mfma_f32_16x16x32_bf16 v[24:27], v[200:203], v[224:227], v[24:27]
	v_mfma_f32_16x16x32_bf16 v[16:19], v[208:211], v[224:227], v[16:19]
	v_mfma_f32_16x16x32_bf16 v[12:15], v[200:203], v[232:235], v[12:15]
	v_mfma_f32_16x16x32_bf16 v[8:11], v[208:211], v[232:235], v[8:11]
	v_mfma_f32_16x16x32_bf16 v[4:7], v[200:203], v[240:243], v[4:7]
	v_mfma_f32_16x16x32_bf16 v[0:3], v[208:211], v[240:243], v[0:3]
	s_setprio 0
	s_barrier
	s_add_i32 s58, 16, 0x18000
	v_add_u32_e32 v142, s58, v157
	s_add_i32 s59, 16, 0x1c000
	ds_read_b128 v[130:133], v142
	ds_read_b128 v[134:137], v142 offset:1024
	ds_read_b128 v[138:141], v142 offset:2048
	ds_read_b128 v[192:195], v142 offset:3072
	v_add_u32_e32 v142, s59, v157
	ds_read_b128 v[196:199], v142
	ds_read_b128 v[200:203], v142 offset:1024
	ds_read_b128 v[204:207], v142 offset:2048
	ds_read_b128 v[208:211], v142 offset:3072
	s_add_u32 s12, s12, 0x80000
	s_addc_u32 s13, s13, 0
	s_mov_b32 m0, s84
	v_lshl_add_u64 v[142:143], s[12:13], 0, v[144:145]
	ds_read_b128 v[212:215], v177 offset:32768
	ds_read_b128 v[216:219], v177 offset:33792
	ds_read_b128 v[220:223], v177 offset:34816
	ds_read_b128 v[224:227], v177 offset:35840
	ds_read_b128 v[228:231], v177 offset:36864
	ds_read_b128 v[232:235], v177 offset:37888
	ds_read_b128 v[236:239], v177 offset:38912
	ds_read_b128 v[240:243], v177 offset:39936
	global_load_lds_dwordx4 v[142:143], off
	v_lshl_add_u64 v[142:143], s[12:13], 0, v[148:149]
	s_mov_b32 m0, s85
	s_nop 0
	global_load_lds_dwordx4 v[142:143], off
	s_waitcnt vmcnt(8)
	s_waitcnt lgkmcnt(0)
	s_barrier
	s_setprio 1
	s_waitcnt lgkmcnt(0)
	v_mfma_f32_16x16x32_bf16 v[112:115], v[130:133], v[212:215], v[112:115]
	v_mfma_f32_16x16x32_bf16 v[116:119], v[138:141], v[212:215], v[116:119]
	v_mfma_f32_16x16x32_bf16 v[108:111], v[130:133], v[220:223], v[108:111]
	v_mfma_f32_16x16x32_bf16 v[100:103], v[138:141], v[220:223], v[100:103]
	v_mfma_f32_16x16x32_bf16 v[92:95], v[130:133], v[228:231], v[92:95]
	v_mfma_f32_16x16x32_bf16 v[84:87], v[138:141], v[228:231], v[84:87]
	v_mfma_f32_16x16x32_bf16 v[76:79], v[130:133], v[236:239], v[76:79]
	v_mfma_f32_16x16x32_bf16 v[68:71], v[138:141], v[236:239], v[68:71]
	v_mfma_f32_16x16x32_bf16 v[112:115], v[134:137], v[216:219], v[112:115]
	v_mfma_f32_16x16x32_bf16 v[116:119], v[192:195], v[216:219], v[116:119]
	v_mfma_f32_16x16x32_bf16 v[108:111], v[134:137], v[224:227], v[108:111]
	v_mfma_f32_16x16x32_bf16 v[100:103], v[192:195], v[224:227], v[100:103]
	v_mfma_f32_16x16x32_bf16 v[92:95], v[134:137], v[232:235], v[92:95]
	v_mfma_f32_16x16x32_bf16 v[84:87], v[192:195], v[232:235], v[84:87]
	v_mfma_f32_16x16x32_bf16 v[76:79], v[134:137], v[240:243], v[76:79]
	v_mfma_f32_16x16x32_bf16 v[68:71], v[192:195], v[240:243], v[68:71]
	v_mfma_f32_16x16x32_bf16 v[104:107], v[196:199], v[212:215], v[104:107]
	v_mfma_f32_16x16x32_bf16 v[96:99], v[204:207], v[212:215], v[96:99]
	v_mfma_f32_16x16x32_bf16 v[88:91], v[196:199], v[220:223], v[88:91]
	v_mfma_f32_16x16x32_bf16 v[80:83], v[204:207], v[220:223], v[80:83]
	v_mfma_f32_16x16x32_bf16 v[72:75], v[196:199], v[228:231], v[72:75]
	v_mfma_f32_16x16x32_bf16 v[64:67], v[204:207], v[228:231], v[64:67]
	v_mfma_f32_16x16x32_bf16 v[60:63], v[196:199], v[236:239], v[60:63]
	v_mfma_f32_16x16x32_bf16 v[56:59], v[204:207], v[236:239], v[56:59]
	v_mfma_f32_16x16x32_bf16 v[104:107], v[200:203], v[216:219], v[104:107]
	v_mfma_f32_16x16x32_bf16 v[96:99], v[208:211], v[216:219], v[96:99]
	v_mfma_f32_16x16x32_bf16 v[88:91], v[200:203], v[224:227], v[88:91]
	v_mfma_f32_16x16x32_bf16 v[80:83], v[208:211], v[224:227], v[80:83]
	v_mfma_f32_16x16x32_bf16 v[72:75], v[200:203], v[232:235], v[72:75]
	v_mfma_f32_16x16x32_bf16 v[64:67], v[208:211], v[232:235], v[64:67]
	v_mfma_f32_16x16x32_bf16 v[60:63], v[200:203], v[240:243], v[60:63]
	v_mfma_f32_16x16x32_bf16 v[56:59], v[208:211], v[240:243], v[56:59]
	s_setprio 0
	s_barrier
	s_add_i32 s12, s58, s74
	v_lshl_add_u64 v[142:143], v[244:245], 0, s[88:89]
	s_mov_b32 m0, s12
	ds_read_b128 v[212:215], v177 offset:49152
	ds_read_b128 v[216:219], v177 offset:50176
	ds_read_b128 v[220:223], v177 offset:51200
	ds_read_b128 v[224:227], v177 offset:52224
	ds_read_b128 v[228:231], v177 offset:53248
	ds_read_b128 v[232:235], v177 offset:54272
	ds_read_b128 v[236:239], v177 offset:55296
	ds_read_b128 v[240:243], v177 offset:56320
	global_load_lds_dwordx4 v[142:143], off
	s_add_i32 m0, s12, 0x2000
	s_add_u32 s8, s8, 0x80080
	v_lshl_add_u64 v[142:143], v[246:247], 0, s[88:89]
	s_addc_u32 s9, s9, 0
	s_add_i32 s12, s59, s74
	global_load_lds_dwordx4 v[142:143], off
	v_lshl_add_u64 v[142:143], s[8:9], 0, v[146:147]
	s_mov_b32 m0, s12
	s_nop 0
	global_load_lds_dwordx4 v[142:143], off
	v_lshl_add_u64 v[142:143], s[8:9], 0, v[150:151]
	s_add_i32 m0, s12, 0x2000
	s_nop 0
	global_load_lds_dwordx4 v[142:143], off
	v_lshl_add_u64 v[142:143], v[248:249], 0, s[88:89]
	s_mov_b32 m0, s53
	s_nop 0
	global_load_lds_dwordx4 v[142:143], off
	v_lshl_add_u64 v[142:143], v[250:251], 0, s[88:89]
	s_mov_b32 m0, s54
	s_nop 0
	global_load_lds_dwordx4 v[142:143], off
	s_waitcnt vmcnt(8)
	s_waitcnt lgkmcnt(0)
	s_barrier
	s_setprio 1
	s_waitcnt lgkmcnt(0)
	v_mfma_f32_16x16x32_bf16 v[52:55], v[130:133], v[212:215], v[52:55]
	v_mfma_f32_16x16x32_bf16 v[44:47], v[130:133], v[220:223], v[44:47]
	v_mfma_f32_16x16x32_bf16 v[28:31], v[130:133], v[228:231], v[28:31]
	v_mfma_f32_16x16x32_bf16 v[122:125], v[130:133], v[236:239], v[122:125]
	v_mfma_f32_16x16x32_bf16 v[52:55], v[134:137], v[216:219], v[52:55]
	v_mfma_f32_16x16x32_bf16 v[48:51], v[138:141], v[212:215], v[48:51]
	v_mfma_f32_16x16x32_bf16 v[44:47], v[134:137], v[224:227], v[44:47]
	v_mfma_f32_16x16x32_bf16 v[36:39], v[138:141], v[220:223], v[36:39]
	v_mfma_f32_16x16x32_bf16 v[28:31], v[134:137], v[232:235], v[28:31]
	v_mfma_f32_16x16x32_bf16 v[20:23], v[138:141], v[228:231], v[20:23]
	v_mfma_f32_16x16x32_bf16 v[132:135], v[134:137], v[240:243], v[122:125]
	v_mfma_f32_16x16x32_bf16 v[122:125], v[138:141], v[236:239], v[126:129]
	v_mfma_f32_16x16x32_bf16 v[48:51], v[192:195], v[216:219], v[48:51]
	v_mfma_f32_16x16x32_bf16 v[36:39], v[192:195], v[224:227], v[36:39]
	v_mfma_f32_16x16x32_bf16 v[20:23], v[192:195], v[232:235], v[20:23]
	v_mfma_f32_16x16x32_bf16 v[128:131], v[192:195], v[240:243], v[122:125]
	v_mfma_f32_16x16x32_bf16 v[40:43], v[196:199], v[212:215], v[40:43]
	v_mfma_f32_16x16x32_bf16 v[32:35], v[204:207], v[212:215], v[32:35]
	v_mfma_f32_16x16x32_bf16 v[24:27], v[196:199], v[220:223], v[24:27]
	v_mfma_f32_16x16x32_bf16 v[16:19], v[204:207], v[220:223], v[16:19]
	v_mfma_f32_16x16x32_bf16 v[12:15], v[196:199], v[228:231], v[12:15]
	v_mfma_f32_16x16x32_bf16 v[8:11], v[204:207], v[228:231], v[8:11]
	v_mfma_f32_16x16x32_bf16 v[4:7], v[196:199], v[236:239], v[4:7]
	v_mfma_f32_16x16x32_bf16 v[0:3], v[204:207], v[236:239], v[0:3]
	v_mfma_f32_16x16x32_bf16 v[40:43], v[200:203], v[216:219], v[40:43]
	v_mfma_f32_16x16x32_bf16 v[32:35], v[208:211], v[216:219], v[32:35]
	v_mfma_f32_16x16x32_bf16 v[24:27], v[200:203], v[224:227], v[24:27]
	v_mfma_f32_16x16x32_bf16 v[16:19], v[208:211], v[224:227], v[16:19]
	v_mfma_f32_16x16x32_bf16 v[12:15], v[200:203], v[232:235], v[12:15]
	v_mfma_f32_16x16x32_bf16 v[8:11], v[208:211], v[232:235], v[8:11]
	v_mfma_f32_16x16x32_bf16 v[4:7], v[200:203], v[240:243], v[4:7]
	v_mfma_f32_16x16x32_bf16 v[0:3], v[208:211], v[240:243], v[0:3]
	s_setprio 0
	s_barrier
	s_add_i32 s57, s57, 2
	s_add_u32 s52, s52, 0x100
	s_addc_u32 s56, s56, 0
	s_add_u32 s0, s0, 0x100
	s_addc_u32 s1, s1, 0
	s_cmp_gt_u32 s57, 29
	s_cbranch_scc1 .LBB0_1179

.LBB0_1467:
	s_add_i32 s92, s66, 2
	s_add_u32 s8, s64, 0xfffc0080
	s_addc_u32 s9, s65, -1
	s_add_i32 s93, 16, 0x10000
	s_cmp_eq_u32 s89, s66
	s_cselect_b32 s67, s51, s9
	s_cselect_b32 s66, s57, s8
	s_cselect_b32 s9, s87, s91
	s_cselect_b32 s8, s88, s90
	s_add_i32 s96, 16, 0x14000
	v_add_u32_e32 v140, s93, v184
	v_add_u32_e32 v187, s96, v184
	ds_read_b128 v[128:131], v140
	ds_read_b128 v[132:135], v140 offset:1024
	ds_read_b128 v[136:139], v140 offset:2048
	ds_read_b128 v[140:143], v140 offset:3072
	ds_read_b128 v[174:177], v187
	ds_read_b128 v[178:181], v187 offset:1024
	ds_read_b128 v[188:191], v187 offset:2048
	ds_read_b128 v[192:195], v187 offset:3072
	v_lshl_add_u64 v[228:229], s[64:65], 0, v[172:173]
	s_add_i32 m0, s74, 0xc000
	ds_read_b128 v[196:199], v153
	ds_read_b128 v[200:203], v153 offset:1024
	ds_read_b128 v[204:207], v153 offset:2048
	ds_read_b128 v[208:211], v153 offset:3072
	ds_read_b128 v[212:215], v153 offset:4096
	ds_read_b128 v[216:219], v153 offset:5120
	ds_read_b128 v[220:223], v153 offset:6144
	ds_read_b128 v[224:227], v153 offset:7168
	global_load_lds_dwordx4 v[228:229], off
	v_lshl_add_u64 v[228:229], s[64:65], 0, v[170:171]
	s_add_i32 m0, s74, 0xe000
	s_nop 0
	global_load_lds_dwordx4 v[228:229], off
	s_waitcnt vmcnt(8)
	s_waitcnt lgkmcnt(0)
	s_barrier
	s_setprio 1
	s_waitcnt lgkmcnt(0)
	v_mfma_f32_16x16x32_bf16 v[60:63], v[128:131], v[196:199], v[60:63]
	v_mfma_f32_16x16x32_bf16 v[56:59], v[136:139], v[196:199], v[56:59]
	v_mfma_f32_16x16x32_bf16 v[44:47], v[128:131], v[204:207], v[44:47]
	v_mfma_f32_16x16x32_bf16 v[40:43], v[136:139], v[204:207], v[40:43]
	v_mfma_f32_16x16x32_bf16 v[28:31], v[128:131], v[212:215], v[28:31]
	v_mfma_f32_16x16x32_bf16 v[24:27], v[136:139], v[212:215], v[24:27]
	v_mfma_f32_16x16x32_bf16 v[12:15], v[128:131], v[220:223], v[12:15]
	v_mfma_f32_16x16x32_bf16 v[8:11], v[136:139], v[220:223], v[8:11]
	v_mfma_f32_16x16x32_bf16 v[60:63], v[132:135], v[200:203], v[60:63]
	v_mfma_f32_16x16x32_bf16 v[56:59], v[140:143], v[200:203], v[56:59]
	v_mfma_f32_16x16x32_bf16 v[44:47], v[132:135], v[208:211], v[44:47]
	v_mfma_f32_16x16x32_bf16 v[40:43], v[140:143], v[208:211], v[40:43]
	v_mfma_f32_16x16x32_bf16 v[28:31], v[132:135], v[216:219], v[28:31]
	v_mfma_f32_16x16x32_bf16 v[24:27], v[140:143], v[216:219], v[24:27]
	v_mfma_f32_16x16x32_bf16 v[12:15], v[132:135], v[224:227], v[12:15]
	v_mfma_f32_16x16x32_bf16 v[8:11], v[140:143], v[224:227], v[8:11]
	v_mfma_f32_16x16x32_bf16 v[52:55], v[174:177], v[196:199], v[52:55]
	v_mfma_f32_16x16x32_bf16 v[48:51], v[188:191], v[196:199], v[48:51]
	v_mfma_f32_16x16x32_bf16 v[36:39], v[174:177], v[204:207], v[36:39]
	v_mfma_f32_16x16x32_bf16 v[32:35], v[188:191], v[204:207], v[32:35]
	v_mfma_f32_16x16x32_bf16 v[20:23], v[174:177], v[212:215], v[20:23]
	v_mfma_f32_16x16x32_bf16 v[16:19], v[188:191], v[212:215], v[16:19]
	v_mfma_f32_16x16x32_bf16 v[4:7], v[174:177], v[220:223], v[4:7]
	v_mfma_f32_16x16x32_bf16 v[0:3], v[188:191], v[220:223], v[0:3]
	v_mfma_f32_16x16x32_bf16 v[52:55], v[178:181], v[200:203], v[52:55]
	v_mfma_f32_16x16x32_bf16 v[48:51], v[192:195], v[200:203], v[48:51]
	v_mfma_f32_16x16x32_bf16 v[36:39], v[178:181], v[208:211], v[36:39]
	v_mfma_f32_16x16x32_bf16 v[32:35], v[192:195], v[208:211], v[32:35]
	v_mfma_f32_16x16x32_bf16 v[20:23], v[178:181], v[216:219], v[20:23]
	v_mfma_f32_16x16x32_bf16 v[16:19], v[192:195], v[216:219], v[16:19]
	v_mfma_f32_16x16x32_bf16 v[4:7], v[178:181], v[224:227], v[4:7]
	v_mfma_f32_16x16x32_bf16 v[0:3], v[192:195], v[224:227], v[0:3]
	s_setprio 0
	s_barrier
	s_add_i32 s93, s93, s73
	v_lshl_add_u64 v[228:229], s[8:9], 0, v[144:145]
	s_mov_b32 m0, s93
	ds_read_b128 v[196:199], v153 offset:16384
	ds_read_b128 v[200:203], v153 offset:17408
	ds_read_b128 v[204:207], v153 offset:18432
	ds_read_b128 v[208:211], v153 offset:19456
	ds_read_b128 v[212:215], v153 offset:20480
	ds_read_b128 v[216:219], v153 offset:21504
	ds_read_b128 v[220:223], v153 offset:22528
	ds_read_b128 v[224:227], v153 offset:23552
	global_load_lds_dwordx4 v[228:229], off
	s_add_i32 m0, s93, 0x2000
	s_add_u32 s94, s8, 0x40000
	v_lshl_add_u64 v[230:231], s[8:9], 0, v[146:147]
	s_addc_u32 s95, s9, 0
	s_add_i32 s93, s96, s73
	global_load_lds_dwordx4 v[230:231], off
	v_lshl_add_u64 v[232:233], s[94:95], 0, v[144:145]
	s_mov_b32 m0, s93
	v_lshl_add_u64 v[234:235], s[66:67], 0, v[148:149]
	global_load_lds_dwordx4 v[232:233], off
	v_lshl_add_u64 v[232:233], s[94:95], 0, v[146:147]
	s_add_i32 m0, s93, 0x2000
	s_nop 0
	global_load_lds_dwordx4 v[232:233], off
	v_lshl_add_u64 v[232:233], s[66:67], 0, v[150:151]
	s_mov_b32 m0, s74
	s_nop 0
	global_load_lds_dwordx4 v[232:233], off
	s_mov_b32 m0, s75
	s_nop 0
	global_load_lds_dwordx4 v[234:235], off
	s_waitcnt vmcnt(8)
	s_waitcnt lgkmcnt(0)
	s_barrier
	s_setprio 1
	s_waitcnt lgkmcnt(0)
	v_mfma_f32_16x16x32_bf16 v[124:127], v[128:131], v[196:199], v[124:127]
	v_mfma_f32_16x16x32_bf16 v[120:123], v[136:139], v[196:199], v[120:123]
	v_mfma_f32_16x16x32_bf16 v[108:111], v[128:131], v[204:207], v[108:111]
	v_mfma_f32_16x16x32_bf16 v[104:107], v[136:139], v[204:207], v[104:107]
	v_mfma_f32_16x16x32_bf16 v[92:95], v[128:131], v[212:215], v[92:95]
	v_mfma_f32_16x16x32_bf16 v[88:91], v[136:139], v[212:215], v[88:91]
	v_mfma_f32_16x16x32_bf16 v[76:79], v[128:131], v[220:223], v[76:79]
	v_mfma_f32_16x16x32_bf16 v[72:75], v[136:139], v[220:223], v[72:75]
	v_mfma_f32_16x16x32_bf16 v[124:127], v[132:135], v[200:203], v[124:127]
	v_mfma_f32_16x16x32_bf16 v[120:123], v[140:143], v[200:203], v[120:123]
	v_mfma_f32_16x16x32_bf16 v[108:111], v[132:135], v[208:211], v[108:111]
	v_mfma_f32_16x16x32_bf16 v[104:107], v[140:143], v[208:211], v[104:107]
	v_mfma_f32_16x16x32_bf16 v[92:95], v[132:135], v[216:219], v[92:95]
	v_mfma_f32_16x16x32_bf16 v[88:91], v[140:143], v[216:219], v[88:91]
	v_mfma_f32_16x16x32_bf16 v[76:79], v[132:135], v[224:227], v[76:79]
	v_mfma_f32_16x16x32_bf16 v[72:75], v[140:143], v[224:227], v[72:75]
	v_mfma_f32_16x16x32_bf16 v[116:119], v[174:177], v[196:199], v[116:119]
	v_mfma_f32_16x16x32_bf16 v[112:115], v[188:191], v[196:199], v[112:115]
	v_mfma_f32_16x16x32_bf16 v[100:103], v[174:177], v[204:207], v[100:103]
	v_mfma_f32_16x16x32_bf16 v[96:99], v[188:191], v[204:207], v[96:99]
	v_mfma_f32_16x16x32_bf16 v[84:87], v[174:177], v[212:215], v[84:87]
	v_mfma_f32_16x16x32_bf16 v[80:83], v[188:191], v[212:215], v[80:83]
	v_mfma_f32_16x16x32_bf16 v[68:71], v[174:177], v[220:223], v[68:71]
	v_mfma_f32_16x16x32_bf16 v[64:67], v[188:191], v[220:223], v[64:67]
	v_mfma_f32_16x16x32_bf16 v[116:119], v[178:181], v[200:203], v[116:119]
	v_mfma_f32_16x16x32_bf16 v[112:115], v[192:195], v[200:203], v[112:115]
	v_mfma_f32_16x16x32_bf16 v[100:103], v[178:181], v[208:211], v[100:103]
	v_mfma_f32_16x16x32_bf16 v[96:99], v[192:195], v[208:211], v[96:99]
	v_mfma_f32_16x16x32_bf16 v[84:87], v[178:181], v[216:219], v[84:87]
	v_mfma_f32_16x16x32_bf16 v[80:83], v[192:195], v[216:219], v[80:83]
	v_mfma_f32_16x16x32_bf16 v[68:71], v[178:181], v[224:227], v[68:71]
	v_mfma_f32_16x16x32_bf16 v[64:67], v[192:195], v[224:227], v[64:67]
	s_setprio 0
	s_barrier
	s_add_i32 s93, 16, 0x18000
	s_add_i32 s94, 16, 0x1c000
	v_add_u32_e32 v140, s93, v184
	v_add_u32_e32 v187, s94, v184
	ds_read_b128 v[128:131], v140
	ds_read_b128 v[132:135], v140 offset:1024
	ds_read_b128 v[136:139], v140 offset:2048
	ds_read_b128 v[140:143], v140 offset:3072
	ds_read_b128 v[174:177], v187
	ds_read_b128 v[178:181], v187 offset:1024
	ds_read_b128 v[188:191], v187 offset:2048
	ds_read_b128 v[192:195], v187 offset:3072
	s_add_u32 s66, s66, 0x40000
	s_addc_u32 s67, s67, 0
	s_mov_b32 m0, s76
	v_lshl_add_u64 v[236:237], s[66:67], 0, v[150:151]
	ds_read_b128 v[196:199], v153 offset:32768
	ds_read_b128 v[200:203], v153 offset:33792
	ds_read_b128 v[204:207], v153 offset:34816
	ds_read_b128 v[208:211], v153 offset:35840
	ds_read_b128 v[212:215], v153 offset:36864
	ds_read_b128 v[216:219], v153 offset:37888
	ds_read_b128 v[220:223], v153 offset:38912
	ds_read_b128 v[224:227], v153 offset:39936
	global_load_lds_dwordx4 v[236:237], off
	v_lshl_add_u64 v[236:237], s[66:67], 0, v[148:149]
	s_mov_b32 m0, s77
	s_nop 0
	global_load_lds_dwordx4 v[236:237], off
	s_waitcnt vmcnt(8)
	s_waitcnt lgkmcnt(0)
	s_barrier
	s_setprio 1
	s_waitcnt lgkmcnt(0)
	v_mfma_f32_16x16x32_bf16 v[60:63], v[128:131], v[196:199], v[60:63]
	v_mfma_f32_16x16x32_bf16 v[56:59], v[136:139], v[196:199], v[56:59]
	v_mfma_f32_16x16x32_bf16 v[44:47], v[128:131], v[204:207], v[44:47]
	v_mfma_f32_16x16x32_bf16 v[40:43], v[136:139], v[204:207], v[40:43]
	v_mfma_f32_16x16x32_bf16 v[28:31], v[128:131], v[212:215], v[28:31]
	v_mfma_f32_16x16x32_bf16 v[24:27], v[136:139], v[212:215], v[24:27]
	v_mfma_f32_16x16x32_bf16 v[12:15], v[128:131], v[220:223], v[12:15]
	v_mfma_f32_16x16x32_bf16 v[8:11], v[136:139], v[220:223], v[8:11]
	v_mfma_f32_16x16x32_bf16 v[60:63], v[132:135], v[200:203], v[60:63]
	v_mfma_f32_16x16x32_bf16 v[56:59], v[140:143], v[200:203], v[56:59]
	v_mfma_f32_16x16x32_bf16 v[44:47], v[132:135], v[208:211], v[44:47]
	v_mfma_f32_16x16x32_bf16 v[40:43], v[140:143], v[208:211], v[40:43]
	v_mfma_f32_16x16x32_bf16 v[28:31], v[132:135], v[216:219], v[28:31]
	v_mfma_f32_16x16x32_bf16 v[24:27], v[140:143], v[216:219], v[24:27]
	v_mfma_f32_16x16x32_bf16 v[12:15], v[132:135], v[224:227], v[12:15]
	v_mfma_f32_16x16x32_bf16 v[8:11], v[140:143], v[224:227], v[8:11]
	v_mfma_f32_16x16x32_bf16 v[52:55], v[174:177], v[196:199], v[52:55]
	v_mfma_f32_16x16x32_bf16 v[48:51], v[188:191], v[196:199], v[48:51]
	v_mfma_f32_16x16x32_bf16 v[36:39], v[174:177], v[204:207], v[36:39]
	v_mfma_f32_16x16x32_bf16 v[32:35], v[188:191], v[204:207], v[32:35]
	v_mfma_f32_16x16x32_bf16 v[20:23], v[174:177], v[212:215], v[20:23]
	v_mfma_f32_16x16x32_bf16 v[16:19], v[188:191], v[212:215], v[16:19]
	v_mfma_f32_16x16x32_bf16 v[4:7], v[174:177], v[220:223], v[4:7]
	v_mfma_f32_16x16x32_bf16 v[0:3], v[188:191], v[220:223], v[0:3]
	v_mfma_f32_16x16x32_bf16 v[52:55], v[178:181], v[200:203], v[52:55]
	v_mfma_f32_16x16x32_bf16 v[48:51], v[192:195], v[200:203], v[48:51]
	v_mfma_f32_16x16x32_bf16 v[36:39], v[178:181], v[208:211], v[36:39]
	v_mfma_f32_16x16x32_bf16 v[32:35], v[192:195], v[208:211], v[32:35]
	v_mfma_f32_16x16x32_bf16 v[20:23], v[178:181], v[216:219], v[20:23]
	v_mfma_f32_16x16x32_bf16 v[16:19], v[192:195], v[216:219], v[16:19]
	v_mfma_f32_16x16x32_bf16 v[4:7], v[178:181], v[224:227], v[4:7]
	v_mfma_f32_16x16x32_bf16 v[0:3], v[192:195], v[224:227], v[0:3]
	s_setprio 0
	s_barrier
	s_add_i32 s66, s93, s73
	v_lshl_add_u64 v[228:229], v[228:229], 0, s[30:31]
	s_mov_b32 m0, s66
	ds_read_b128 v[196:199], v153 offset:49152
	ds_read_b128 v[200:203], v153 offset:50176
	ds_read_b128 v[204:207], v153 offset:51200
	ds_read_b128 v[208:211], v153 offset:52224
	ds_read_b128 v[212:215], v153 offset:53248
	ds_read_b128 v[216:219], v153 offset:54272
	ds_read_b128 v[220:223], v153 offset:55296
	ds_read_b128 v[224:227], v153 offset:56320
	global_load_lds_dwordx4 v[228:229], off
	s_add_i32 m0, s66, 0x2000
	s_add_u32 s8, s8, 0x40080
	v_lshl_add_u64 v[228:229], v[230:231], 0, s[30:31]
	s_addc_u32 s9, s9, 0
	s_add_i32 s66, s94, s73
	global_load_lds_dwordx4 v[228:229], off
	v_lshl_add_u64 v[228:229], s[8:9], 0, v[144:145]
	s_mov_b32 m0, s66
	s_nop 0
	global_load_lds_dwordx4 v[228:229], off
	v_lshl_add_u64 v[228:229], s[8:9], 0, v[146:147]
	s_add_i32 m0, s66, 0x2000
	s_nop 0
	global_load_lds_dwordx4 v[228:229], off
	v_lshl_add_u64 v[228:229], v[232:233], 0, s[30:31]
	s_mov_b32 m0, s78
	s_nop 0
	global_load_lds_dwordx4 v[228:229], off
	v_lshl_add_u64 v[228:229], v[234:235], 0, s[30:31]
	s_mov_b32 m0, s79
	s_nop 0
	global_load_lds_dwordx4 v[228:229], off
	s_waitcnt vmcnt(8)
	s_waitcnt lgkmcnt(0)
	s_barrier
	s_setprio 1
	s_waitcnt lgkmcnt(0)
	v_mfma_f32_16x16x32_bf16 v[124:127], v[128:131], v[196:199], v[124:127]
	v_mfma_f32_16x16x32_bf16 v[120:123], v[136:139], v[196:199], v[120:123]
	v_mfma_f32_16x16x32_bf16 v[108:111], v[128:131], v[204:207], v[108:111]
	v_mfma_f32_16x16x32_bf16 v[104:107], v[136:139], v[204:207], v[104:107]
	v_mfma_f32_16x16x32_bf16 v[92:95], v[128:131], v[212:215], v[92:95]
	v_mfma_f32_16x16x32_bf16 v[88:91], v[136:139], v[212:215], v[88:91]
	v_mfma_f32_16x16x32_bf16 v[76:79], v[128:131], v[220:223], v[76:79]
	v_mfma_f32_16x16x32_bf16 v[72:75], v[136:139], v[220:223], v[72:75]
	v_mfma_f32_16x16x32_bf16 v[124:127], v[132:135], v[200:203], v[124:127]
	v_mfma_f32_16x16x32_bf16 v[120:123], v[140:143], v[200:203], v[120:123]
	v_mfma_f32_16x16x32_bf16 v[108:111], v[132:135], v[208:211], v[108:111]
	v_mfma_f32_16x16x32_bf16 v[104:107], v[140:143], v[208:211], v[104:107]
	v_mfma_f32_16x16x32_bf16 v[92:95], v[132:135], v[216:219], v[92:95]
	v_mfma_f32_16x16x32_bf16 v[88:91], v[140:143], v[216:219], v[88:91]
	v_mfma_f32_16x16x32_bf16 v[76:79], v[132:135], v[224:227], v[76:79]
	v_mfma_f32_16x16x32_bf16 v[72:75], v[140:143], v[224:227], v[72:75]
	v_mfma_f32_16x16x32_bf16 v[116:119], v[174:177], v[196:199], v[116:119]
	v_mfma_f32_16x16x32_bf16 v[112:115], v[188:191], v[196:199], v[112:115]
	v_mfma_f32_16x16x32_bf16 v[100:103], v[174:177], v[204:207], v[100:103]
	v_mfma_f32_16x16x32_bf16 v[96:99], v[188:191], v[204:207], v[96:99]
	v_mfma_f32_16x16x32_bf16 v[84:87], v[174:177], v[212:215], v[84:87]
	v_mfma_f32_16x16x32_bf16 v[80:83], v[188:191], v[212:215], v[80:83]
	v_mfma_f32_16x16x32_bf16 v[68:71], v[174:177], v[220:223], v[68:71]
	v_mfma_f32_16x16x32_bf16 v[64:67], v[188:191], v[220:223], v[64:67]
	v_mfma_f32_16x16x32_bf16 v[116:119], v[178:181], v[200:203], v[116:119]
	v_mfma_f32_16x16x32_bf16 v[112:115], v[192:195], v[200:203], v[112:115]
	v_mfma_f32_16x16x32_bf16 v[100:103], v[178:181], v[208:211], v[100:103]
	v_mfma_f32_16x16x32_bf16 v[96:99], v[192:195], v[208:211], v[96:99]
	v_mfma_f32_16x16x32_bf16 v[84:87], v[178:181], v[216:219], v[84:87]
	v_mfma_f32_16x16x32_bf16 v[80:83], v[192:195], v[216:219], v[80:83]
	v_mfma_f32_16x16x32_bf16 v[68:71], v[178:181], v[224:227], v[68:71]
	v_mfma_f32_16x16x32_bf16 v[64:67], v[192:195], v[224:227], v[64:67]
	s_setprio 0
	s_barrier
	s_add_u32 s90, s90, 0x100
	s_addc_u32 s91, s91, 0
	s_add_u32 s64, s64, 0x100
	s_addc_u32 s65, s65, 0
	s_cmp_ge_u32 s92, s86
	s_mov_b32 s66, s92
	s_cbranch_scc0 .LBB0_1467
	s_and_b64 vcc, exec, s[42:43]
	s_cbranch_vccz .LBB0_1470
	s_barrier

.LBB0_1558:
	ds_read_b128 v[158:161], v137
	ds_read_b128 v[162:165], v137 offset:1024
	ds_read_b128 v[166:169], v137 offset:2048
	ds_read_b128 v[170:173], v137 offset:3072
	ds_read_b128 v[186:189], v177
	ds_read_b128 v[190:193], v177 offset:1024
	ds_read_b128 v[194:197], v177 offset:2048
	ds_read_b128 v[198:201], v177 offset:3072
	s_add_i32 s78, s8, 2
	s_add_u32 s9, s4, 0xfffc0080
	s_addc_u32 s48, s5, -1
	s_cmp_eq_u32 s43, s8
	s_cselect_b32 s8, s41, s76
	s_cselect_b32 s49, s45, s48
	s_cselect_b32 s48, s44, s9
	s_cselect_b32 s9, s39, s77
	v_lshl_add_u64 v[180:181], s[4:5], 0, v[156:157]
	s_add_i32 m0, s13, 0xc000
	ds_read_b128 v[202:205], v178
	ds_read_b128 v[206:209], v178 offset:1024
	ds_read_b128 v[210:213], v178 offset:2048
	ds_read_b128 v[214:217], v178 offset:3072
	ds_read_b128 v[218:221], v178 offset:4096
	ds_read_b128 v[222:225], v178 offset:5120
	ds_read_b128 v[226:229], v178 offset:6144
	ds_read_b128 v[230:233], v178 offset:7168
	global_load_lds_dwordx4 v[180:181], off
	v_lshl_add_u64 v[180:181], s[4:5], 0, v[154:155]
	s_add_i32 m0, s13, 0xe000
	s_nop 0
	global_load_lds_dwordx4 v[180:181], off
	s_waitcnt vmcnt(8)
	s_waitcnt lgkmcnt(0)
	s_barrier
	s_setprio 1
	s_waitcnt lgkmcnt(0)
	v_mfma_f32_16x16x32_bf16 v[60:63], v[158:161], v[202:205], v[60:63]
	v_mfma_f32_16x16x32_bf16 v[56:59], v[166:169], v[202:205], v[56:59]
	v_mfma_f32_16x16x32_bf16 v[44:47], v[158:161], v[210:213], v[44:47]
	v_mfma_f32_16x16x32_bf16 v[40:43], v[166:169], v[210:213], v[40:43]
	v_mfma_f32_16x16x32_bf16 v[28:31], v[158:161], v[218:221], v[28:31]
	v_mfma_f32_16x16x32_bf16 v[24:27], v[166:169], v[218:221], v[24:27]
	v_mfma_f32_16x16x32_bf16 v[12:15], v[158:161], v[226:229], v[12:15]
	v_mfma_f32_16x16x32_bf16 v[8:11], v[166:169], v[226:229], v[8:11]
	v_mfma_f32_16x16x32_bf16 v[60:63], v[162:165], v[206:209], v[60:63]
	v_mfma_f32_16x16x32_bf16 v[56:59], v[170:173], v[206:209], v[56:59]
	v_mfma_f32_16x16x32_bf16 v[44:47], v[162:165], v[214:217], v[44:47]
	v_mfma_f32_16x16x32_bf16 v[40:43], v[170:173], v[214:217], v[40:43]
	v_mfma_f32_16x16x32_bf16 v[28:31], v[162:165], v[222:225], v[28:31]
	v_mfma_f32_16x16x32_bf16 v[24:27], v[170:173], v[222:225], v[24:27]
	v_mfma_f32_16x16x32_bf16 v[12:15], v[162:165], v[230:233], v[12:15]
	v_mfma_f32_16x16x32_bf16 v[8:11], v[170:173], v[230:233], v[8:11]
	v_mfma_f32_16x16x32_bf16 v[52:55], v[186:189], v[202:205], v[52:55]
	v_mfma_f32_16x16x32_bf16 v[48:51], v[194:197], v[202:205], v[48:51]
	v_mfma_f32_16x16x32_bf16 v[36:39], v[186:189], v[210:213], v[36:39]
	v_mfma_f32_16x16x32_bf16 v[32:35], v[194:197], v[210:213], v[32:35]
	v_mfma_f32_16x16x32_bf16 v[20:23], v[186:189], v[218:221], v[20:23]
	v_mfma_f32_16x16x32_bf16 v[16:19], v[194:197], v[218:221], v[16:19]
	v_mfma_f32_16x16x32_bf16 v[4:7], v[186:189], v[226:229], v[4:7]
	v_mfma_f32_16x16x32_bf16 v[0:3], v[194:197], v[226:229], v[0:3]
	v_mfma_f32_16x16x32_bf16 v[52:55], v[190:193], v[206:209], v[52:55]
	v_mfma_f32_16x16x32_bf16 v[48:51], v[198:201], v[206:209], v[48:51]
	v_mfma_f32_16x16x32_bf16 v[36:39], v[190:193], v[214:217], v[36:39]
	v_mfma_f32_16x16x32_bf16 v[32:35], v[198:201], v[214:217], v[32:35]
	v_mfma_f32_16x16x32_bf16 v[20:23], v[190:193], v[222:225], v[20:23]
	v_mfma_f32_16x16x32_bf16 v[16:19], v[198:201], v[222:225], v[16:19]
	v_mfma_f32_16x16x32_bf16 v[4:7], v[190:193], v[230:233], v[4:7]
	v_mfma_f32_16x16x32_bf16 v[0:3], v[198:201], v[230:233], v[0:3]
	s_setprio 0
	s_barrier
	s_add_i32 s79, s62, s50
	v_lshl_add_u64 v[180:181], s[8:9], 0, v[130:131]
	s_mov_b32 m0, s79
	ds_read_b128 v[202:205], v178 offset:16384
	ds_read_b128 v[206:209], v178 offset:17408
	ds_read_b128 v[210:213], v178 offset:18432
	ds_read_b128 v[214:217], v178 offset:19456
	ds_read_b128 v[218:221], v178 offset:20480
	ds_read_b128 v[222:225], v178 offset:21504
	ds_read_b128 v[226:229], v178 offset:22528
	ds_read_b128 v[230:233], v178 offset:23552
	global_load_lds_dwordx4 v[180:181], off
	s_add_i32 m0, s79, 0x2000
	s_add_u32 s80, s8, 0x40000
	v_lshl_add_u64 v[234:235], s[8:9], 0, v[134:135]
	s_addc_u32 s81, s9, 0
	s_add_i32 s79, s63, s50
	global_load_lds_dwordx4 v[234:235], off
	v_lshl_add_u64 v[236:237], s[80:81], 0, v[130:131]
	s_mov_b32 m0, s79
	v_lshl_add_u64 v[238:239], s[48:49], 0, v[132:133]
	global_load_lds_dwordx4 v[236:237], off
	v_lshl_add_u64 v[236:237], s[80:81], 0, v[134:135]
	s_add_i32 m0, s79, 0x2000
	s_nop 0
	global_load_lds_dwordx4 v[236:237], off
	v_lshl_add_u64 v[236:237], s[48:49], 0, v[128:129]
	s_mov_b32 m0, s13
	s_nop 0
	global_load_lds_dwordx4 v[236:237], off
	s_mov_b32 m0, s51
	s_nop 0
	global_load_lds_dwordx4 v[238:239], off
	s_waitcnt vmcnt(8)
	s_waitcnt lgkmcnt(0)
	s_barrier
	s_setprio 1
	s_waitcnt lgkmcnt(0)
	v_mfma_f32_16x16x32_bf16 v[124:127], v[158:161], v[202:205], v[124:127]
	v_mfma_f32_16x16x32_bf16 v[120:123], v[166:169], v[202:205], v[120:123]
	v_mfma_f32_16x16x32_bf16 v[108:111], v[158:161], v[210:213], v[108:111]
	v_mfma_f32_16x16x32_bf16 v[104:107], v[166:169], v[210:213], v[104:107]
	v_mfma_f32_16x16x32_bf16 v[92:95], v[158:161], v[218:221], v[92:95]
	v_mfma_f32_16x16x32_bf16 v[88:91], v[166:169], v[218:221], v[88:91]
	v_mfma_f32_16x16x32_bf16 v[76:79], v[158:161], v[226:229], v[76:79]
	v_mfma_f32_16x16x32_bf16 v[72:75], v[166:169], v[226:229], v[72:75]
	v_mfma_f32_16x16x32_bf16 v[124:127], v[162:165], v[206:209], v[124:127]
	v_mfma_f32_16x16x32_bf16 v[120:123], v[170:173], v[206:209], v[120:123]
	v_mfma_f32_16x16x32_bf16 v[108:111], v[162:165], v[214:217], v[108:111]
	v_mfma_f32_16x16x32_bf16 v[104:107], v[170:173], v[214:217], v[104:107]
	v_mfma_f32_16x16x32_bf16 v[92:95], v[162:165], v[222:225], v[92:95]
	v_mfma_f32_16x16x32_bf16 v[88:91], v[170:173], v[222:225], v[88:91]
	v_mfma_f32_16x16x32_bf16 v[76:79], v[162:165], v[230:233], v[76:79]
	v_mfma_f32_16x16x32_bf16 v[72:75], v[170:173], v[230:233], v[72:75]
	v_mfma_f32_16x16x32_bf16 v[116:119], v[186:189], v[202:205], v[116:119]
	v_mfma_f32_16x16x32_bf16 v[112:115], v[194:197], v[202:205], v[112:115]
	v_mfma_f32_16x16x32_bf16 v[100:103], v[186:189], v[210:213], v[100:103]
	v_mfma_f32_16x16x32_bf16 v[96:99], v[194:197], v[210:213], v[96:99]
	v_mfma_f32_16x16x32_bf16 v[84:87], v[186:189], v[218:221], v[84:87]
	v_mfma_f32_16x16x32_bf16 v[80:83], v[194:197], v[218:221], v[80:83]
	v_mfma_f32_16x16x32_bf16 v[68:71], v[186:189], v[226:229], v[68:71]
	v_mfma_f32_16x16x32_bf16 v[64:67], v[194:197], v[226:229], v[64:67]
	v_mfma_f32_16x16x32_bf16 v[116:119], v[190:193], v[206:209], v[116:119]
	v_mfma_f32_16x16x32_bf16 v[112:115], v[198:201], v[206:209], v[112:115]
	v_mfma_f32_16x16x32_bf16 v[100:103], v[190:193], v[214:217], v[100:103]
	v_mfma_f32_16x16x32_bf16 v[96:99], v[198:201], v[214:217], v[96:99]
	v_mfma_f32_16x16x32_bf16 v[84:87], v[190:193], v[222:225], v[84:87]
	v_mfma_f32_16x16x32_bf16 v[80:83], v[198:201], v[222:225], v[80:83]
	v_mfma_f32_16x16x32_bf16 v[68:71], v[190:193], v[230:233], v[68:71]
	v_mfma_f32_16x16x32_bf16 v[64:67], v[198:201], v[230:233], v[64:67]
	s_setprio 0
	s_barrier
	s_add_i32 s79, 16, 0x18000
	s_add_i32 s80, 16, 0x1c000
	v_add_u32_e32 v170, s79, v175
	v_add_u32_e32 v179, s80, v175
	ds_read_b128 v[158:161], v170
	ds_read_b128 v[162:165], v170 offset:1024
	ds_read_b128 v[166:169], v170 offset:2048
	ds_read_b128 v[170:173], v170 offset:3072
	ds_read_b128 v[186:189], v179
	ds_read_b128 v[190:193], v179 offset:1024
	ds_read_b128 v[194:197], v179 offset:2048
	ds_read_b128 v[198:201], v179 offset:3072
	s_add_u32 s48, s48, 0x40000
	s_addc_u32 s49, s49, 0
	s_mov_b32 m0, s52
	v_lshl_add_u64 v[240:241], s[48:49], 0, v[128:129]
	ds_read_b128 v[202:205], v178 offset:32768
	ds_read_b128 v[206:209], v178 offset:33792
	ds_read_b128 v[210:213], v178 offset:34816
	ds_read_b128 v[214:217], v178 offset:35840
	ds_read_b128 v[218:221], v178 offset:36864
	ds_read_b128 v[222:225], v178 offset:37888
	ds_read_b128 v[226:229], v178 offset:38912
	ds_read_b128 v[230:233], v178 offset:39936
	global_load_lds_dwordx4 v[240:241], off
	v_lshl_add_u64 v[240:241], s[48:49], 0, v[132:133]
	s_mov_b32 m0, s54
	s_nop 0
	global_load_lds_dwordx4 v[240:241], off
	s_waitcnt vmcnt(8)
	s_waitcnt lgkmcnt(0)
	s_barrier
	s_setprio 1
	s_waitcnt lgkmcnt(0)
	v_mfma_f32_16x16x32_bf16 v[60:63], v[158:161], v[202:205], v[60:63]
	v_mfma_f32_16x16x32_bf16 v[56:59], v[166:169], v[202:205], v[56:59]
	v_mfma_f32_16x16x32_bf16 v[44:47], v[158:161], v[210:213], v[44:47]
	v_mfma_f32_16x16x32_bf16 v[40:43], v[166:169], v[210:213], v[40:43]
	v_mfma_f32_16x16x32_bf16 v[28:31], v[158:161], v[218:221], v[28:31]
	v_mfma_f32_16x16x32_bf16 v[24:27], v[166:169], v[218:221], v[24:27]
	v_mfma_f32_16x16x32_bf16 v[12:15], v[158:161], v[226:229], v[12:15]
	v_mfma_f32_16x16x32_bf16 v[8:11], v[166:169], v[226:229], v[8:11]
	v_mfma_f32_16x16x32_bf16 v[60:63], v[162:165], v[206:209], v[60:63]
	v_mfma_f32_16x16x32_bf16 v[56:59], v[170:173], v[206:209], v[56:59]
	v_mfma_f32_16x16x32_bf16 v[44:47], v[162:165], v[214:217], v[44:47]
	v_mfma_f32_16x16x32_bf16 v[40:43], v[170:173], v[214:217], v[40:43]
	v_mfma_f32_16x16x32_bf16 v[28:31], v[162:165], v[222:225], v[28:31]
	v_mfma_f32_16x16x32_bf16 v[24:27], v[170:173], v[222:225], v[24:27]
	v_mfma_f32_16x16x32_bf16 v[12:15], v[162:165], v[230:233], v[12:15]
	v_mfma_f32_16x16x32_bf16 v[8:11], v[170:173], v[230:233], v[8:11]
	v_mfma_f32_16x16x32_bf16 v[52:55], v[186:189], v[202:205], v[52:55]
	v_mfma_f32_16x16x32_bf16 v[48:51], v[194:197], v[202:205], v[48:51]
	v_mfma_f32_16x16x32_bf16 v[36:39], v[186:189], v[210:213], v[36:39]
	v_mfma_f32_16x16x32_bf16 v[32:35], v[194:197], v[210:213], v[32:35]
	v_mfma_f32_16x16x32_bf16 v[20:23], v[186:189], v[218:221], v[20:23]
	v_mfma_f32_16x16x32_bf16 v[16:19], v[194:197], v[218:221], v[16:19]
	v_mfma_f32_16x16x32_bf16 v[4:7], v[186:189], v[226:229], v[4:7]
	v_mfma_f32_16x16x32_bf16 v[0:3], v[194:197], v[226:229], v[0:3]
	v_mfma_f32_16x16x32_bf16 v[52:55], v[190:193], v[206:209], v[52:55]
	v_mfma_f32_16x16x32_bf16 v[48:51], v[198:201], v[206:209], v[48:51]
	v_mfma_f32_16x16x32_bf16 v[36:39], v[190:193], v[214:217], v[36:39]
	v_mfma_f32_16x16x32_bf16 v[32:35], v[198:201], v[214:217], v[32:35]
	v_mfma_f32_16x16x32_bf16 v[20:23], v[190:193], v[222:225], v[20:23]
	v_mfma_f32_16x16x32_bf16 v[16:19], v[198:201], v[222:225], v[16:19]
	v_mfma_f32_16x16x32_bf16 v[4:7], v[190:193], v[230:233], v[4:7]
	v_mfma_f32_16x16x32_bf16 v[0:3], v[198:201], v[230:233], v[0:3]
	s_setprio 0
	s_barrier
	s_add_i32 s48, s79, s50
	v_lshl_add_u64 v[180:181], v[180:181], 0, s[16:17]
	s_mov_b32 m0, s48
	ds_read_b128 v[202:205], v178 offset:49152
	ds_read_b128 v[206:209], v178 offset:50176
	ds_read_b128 v[210:213], v178 offset:51200
	ds_read_b128 v[214:217], v178 offset:52224
	ds_read_b128 v[218:221], v178 offset:53248
	ds_read_b128 v[222:225], v178 offset:54272
	ds_read_b128 v[226:229], v178 offset:55296
	ds_read_b128 v[230:233], v178 offset:56320
	global_load_lds_dwordx4 v[180:181], off
	s_add_i32 m0, s48, 0x2000
	s_add_u32 s8, s8, 0x40080
	v_lshl_add_u64 v[180:181], v[234:235], 0, s[16:17]
	s_addc_u32 s9, s9, 0
	s_add_i32 s48, s80, s50
	global_load_lds_dwordx4 v[180:181], off
	v_lshl_add_u64 v[180:181], s[8:9], 0, v[130:131]
	s_mov_b32 m0, s48
	s_nop 0
	global_load_lds_dwordx4 v[180:181], off
	v_lshl_add_u64 v[180:181], s[8:9], 0, v[134:135]
	s_add_i32 m0, s48, 0x2000
	s_nop 0
	global_load_lds_dwordx4 v[180:181], off
	v_lshl_add_u64 v[180:181], v[236:237], 0, s[16:17]
	s_mov_b32 m0, s55
	s_nop 0
	global_load_lds_dwordx4 v[180:181], off
	v_lshl_add_u64 v[180:181], v[238:239], 0, s[16:17]
	s_mov_b32 m0, s56
	s_nop 0
	global_load_lds_dwordx4 v[180:181], off
	s_waitcnt vmcnt(8)
	s_waitcnt lgkmcnt(0)
	s_barrier
	s_setprio 1
	s_waitcnt lgkmcnt(0)
	v_mfma_f32_16x16x32_bf16 v[124:127], v[158:161], v[202:205], v[124:127]
	v_mfma_f32_16x16x32_bf16 v[120:123], v[166:169], v[202:205], v[120:123]
	v_mfma_f32_16x16x32_bf16 v[108:111], v[158:161], v[210:213], v[108:111]
	v_mfma_f32_16x16x32_bf16 v[104:107], v[166:169], v[210:213], v[104:107]
	v_mfma_f32_16x16x32_bf16 v[92:95], v[158:161], v[218:221], v[92:95]
	v_mfma_f32_16x16x32_bf16 v[88:91], v[166:169], v[218:221], v[88:91]
	v_mfma_f32_16x16x32_bf16 v[76:79], v[158:161], v[226:229], v[76:79]
	v_mfma_f32_16x16x32_bf16 v[72:75], v[166:169], v[226:229], v[72:75]
	v_mfma_f32_16x16x32_bf16 v[124:127], v[162:165], v[206:209], v[124:127]
	v_mfma_f32_16x16x32_bf16 v[120:123], v[170:173], v[206:209], v[120:123]
	v_mfma_f32_16x16x32_bf16 v[108:111], v[162:165], v[214:217], v[108:111]
	v_mfma_f32_16x16x32_bf16 v[104:107], v[170:173], v[214:217], v[104:107]
	v_mfma_f32_16x16x32_bf16 v[92:95], v[162:165], v[222:225], v[92:95]
	v_mfma_f32_16x16x32_bf16 v[88:91], v[170:173], v[222:225], v[88:91]
	v_mfma_f32_16x16x32_bf16 v[76:79], v[162:165], v[230:233], v[76:79]
	v_mfma_f32_16x16x32_bf16 v[72:75], v[170:173], v[230:233], v[72:75]
	v_mfma_f32_16x16x32_bf16 v[116:119], v[186:189], v[202:205], v[116:119]
	v_mfma_f32_16x16x32_bf16 v[112:115], v[194:197], v[202:205], v[112:115]
	v_mfma_f32_16x16x32_bf16 v[100:103], v[186:189], v[210:213], v[100:103]
	v_mfma_f32_16x16x32_bf16 v[96:99], v[194:197], v[210:213], v[96:99]
	v_mfma_f32_16x16x32_bf16 v[84:87], v[186:189], v[218:221], v[84:87]
	v_mfma_f32_16x16x32_bf16 v[80:83], v[194:197], v[218:221], v[80:83]
	v_mfma_f32_16x16x32_bf16 v[68:71], v[186:189], v[226:229], v[68:71]
	v_mfma_f32_16x16x32_bf16 v[64:67], v[194:197], v[226:229], v[64:67]
	v_mfma_f32_16x16x32_bf16 v[116:119], v[190:193], v[206:209], v[116:119]
	v_mfma_f32_16x16x32_bf16 v[112:115], v[198:201], v[206:209], v[112:115]
	v_mfma_f32_16x16x32_bf16 v[100:103], v[190:193], v[214:217], v[100:103]
	v_mfma_f32_16x16x32_bf16 v[96:99], v[198:201], v[214:217], v[96:99]
	v_mfma_f32_16x16x32_bf16 v[84:87], v[190:193], v[222:225], v[84:87]
	v_mfma_f32_16x16x32_bf16 v[80:83], v[198:201], v[222:225], v[80:83]
	v_mfma_f32_16x16x32_bf16 v[68:71], v[190:193], v[230:233], v[68:71]
	v_mfma_f32_16x16x32_bf16 v[64:67], v[198:201], v[230:233], v[64:67]
	s_setprio 0
	s_barrier
	s_add_u32 s76, s76, 0x100
	s_addc_u32 s77, s77, 0
	s_add_u32 s4, s4, 0x100
	s_addc_u32 s5, s5, 0
	s_cmp_ge_u32 s78, s74
	s_mov_b32 s8, s78
	s_cbranch_scc0 .LBB0_1558
	s_and_b64 vcc, exec, s[26:27]
	s_cbranch_vccz .LBB0_1561
	s_barrier

.LBB0_1711:
	ds_read_b128 v[152:155], v139
	ds_read_b128 v[166:169], v139 offset:1024
	ds_read_b128 v[170:173], v139 offset:2048
	ds_read_b128 v[174:177], v139 offset:3072
	ds_read_b128 v[178:181], v161
	ds_read_b128 v[184:187], v161 offset:1024
	ds_read_b128 v[188:191], v161 offset:2048
	ds_read_b128 v[192:195], v161 offset:3072
	s_add_i32 s85, s50, 2
	s_add_u32 s8, s48, 0xfff80080
	s_addc_u32 s9, s49, -1
	s_cmp_eq_u32 s82, s50
	s_cselect_b32 s50, s5, s8
	s_cselect_b32 s51, s1, s9
	s_cselect_b32 s9, s39, s84
	s_cselect_b32 s8, s41, s83
	v_lshl_add_u64 v[156:157], s[48:49], 0, v[150:151]
	s_add_i32 m0, s53, 0xc000
	ds_read_b128 v[196:199], v162
	ds_read_b128 v[200:203], v162 offset:1024
	ds_read_b128 v[204:207], v162 offset:2048
	ds_read_b128 v[208:211], v162 offset:3072
	ds_read_b128 v[212:215], v162 offset:4096
	ds_read_b128 v[216:219], v162 offset:5120
	ds_read_b128 v[220:223], v162 offset:6144
	ds_read_b128 v[224:227], v162 offset:7168
	global_load_lds_dwordx4 v[156:157], off
	v_lshl_add_u64 v[156:157], s[48:49], 0, v[148:149]
	s_add_i32 m0, s53, 0xe000
	s_nop 0
	global_load_lds_dwordx4 v[156:157], off
	s_waitcnt vmcnt(8)
	s_waitcnt lgkmcnt(0)
	s_barrier
	s_setprio 1
	s_waitcnt lgkmcnt(0)
	v_mfma_f32_16x16x32_bf16 v[60:63], v[152:155], v[196:199], v[60:63]
	v_mfma_f32_16x16x32_bf16 v[56:59], v[170:173], v[196:199], v[56:59]
	v_mfma_f32_16x16x32_bf16 v[52:55], v[152:155], v[204:207], v[52:55]
	v_mfma_f32_16x16x32_bf16 v[48:51], v[170:173], v[204:207], v[48:51]
	v_mfma_f32_16x16x32_bf16 v[44:47], v[152:155], v[212:215], v[44:47]
	v_mfma_f32_16x16x32_bf16 v[40:43], v[170:173], v[212:215], v[40:43]
	v_mfma_f32_16x16x32_bf16 v[28:31], v[152:155], v[220:223], v[28:31]
	v_mfma_f32_16x16x32_bf16 v[24:27], v[170:173], v[220:223], v[24:27]
	v_mfma_f32_16x16x32_bf16 v[60:63], v[166:169], v[200:203], v[60:63]
	v_mfma_f32_16x16x32_bf16 v[56:59], v[174:177], v[200:203], v[56:59]
	v_mfma_f32_16x16x32_bf16 v[52:55], v[166:169], v[208:211], v[52:55]
	v_mfma_f32_16x16x32_bf16 v[48:51], v[174:177], v[208:211], v[48:51]
	v_mfma_f32_16x16x32_bf16 v[44:47], v[166:169], v[216:219], v[44:47]
	v_mfma_f32_16x16x32_bf16 v[40:43], v[174:177], v[216:219], v[40:43]
	v_mfma_f32_16x16x32_bf16 v[28:31], v[166:169], v[224:227], v[28:31]
	v_mfma_f32_16x16x32_bf16 v[24:27], v[174:177], v[224:227], v[24:27]
	v_mfma_f32_16x16x32_bf16 v[36:39], v[178:181], v[196:199], v[36:39]
	v_mfma_f32_16x16x32_bf16 v[32:35], v[188:191], v[196:199], v[32:35]
	v_mfma_f32_16x16x32_bf16 v[20:23], v[178:181], v[204:207], v[20:23]
	v_mfma_f32_16x16x32_bf16 v[16:19], v[188:191], v[204:207], v[16:19]
	v_mfma_f32_16x16x32_bf16 v[12:15], v[178:181], v[212:215], v[12:15]
	v_mfma_f32_16x16x32_bf16 v[8:11], v[188:191], v[212:215], v[8:11]
	v_mfma_f32_16x16x32_bf16 v[4:7], v[178:181], v[220:223], v[4:7]
	v_mfma_f32_16x16x32_bf16 v[0:3], v[188:191], v[220:223], v[0:3]
	v_mfma_f32_16x16x32_bf16 v[36:39], v[184:187], v[200:203], v[36:39]
	v_mfma_f32_16x16x32_bf16 v[32:35], v[192:195], v[200:203], v[32:35]
	v_mfma_f32_16x16x32_bf16 v[20:23], v[184:187], v[208:211], v[20:23]
	v_mfma_f32_16x16x32_bf16 v[16:19], v[192:195], v[208:211], v[16:19]
	v_mfma_f32_16x16x32_bf16 v[12:15], v[184:187], v[216:219], v[12:15]
	v_mfma_f32_16x16x32_bf16 v[8:11], v[192:195], v[216:219], v[8:11]
	v_mfma_f32_16x16x32_bf16 v[4:7], v[184:187], v[224:227], v[4:7]
	v_mfma_f32_16x16x32_bf16 v[0:3], v[192:195], v[224:227], v[0:3]
	s_setprio 0
	s_barrier
	s_add_i32 s86, s64, s52
	v_lshl_add_u64 v[156:157], s[8:9], 0, v[130:131]
	s_mov_b32 m0, s86
	ds_read_b128 v[196:199], v162 offset:16384
	ds_read_b128 v[200:203], v162 offset:17408
	ds_read_b128 v[204:207], v162 offset:18432
	ds_read_b128 v[208:211], v162 offset:19456
	ds_read_b128 v[212:215], v162 offset:20480
	ds_read_b128 v[216:219], v162 offset:21504
	ds_read_b128 v[220:223], v162 offset:22528
	ds_read_b128 v[224:227], v162 offset:23552
	global_load_lds_dwordx4 v[156:157], off
	s_add_i32 m0, s86, 0x2000
	s_add_u32 s86, s8, 0x80000
	v_lshl_add_u64 v[228:229], s[8:9], 0, v[134:135]
	s_addc_u32 s87, s9, 0
	s_add_i32 s88, s65, s52
	global_load_lds_dwordx4 v[228:229], off
	v_lshl_add_u64 v[230:231], s[86:87], 0, v[130:131]
	s_mov_b32 m0, s88
	v_lshl_add_u64 v[232:233], s[50:51], 0, v[132:133]
	global_load_lds_dwordx4 v[230:231], off
	v_lshl_add_u64 v[230:231], s[86:87], 0, v[134:135]
	s_add_i32 m0, s88, 0x2000
	s_nop 0
	global_load_lds_dwordx4 v[230:231], off
	v_lshl_add_u64 v[230:231], s[50:51], 0, v[128:129]
	s_mov_b32 m0, s53
	s_nop 0
	global_load_lds_dwordx4 v[230:231], off
	s_mov_b32 m0, s54
	s_nop 0
	global_load_lds_dwordx4 v[232:233], off
	s_waitcnt vmcnt(8)
	s_waitcnt lgkmcnt(0)
	s_barrier
	s_setprio 1
	s_waitcnt lgkmcnt(0)
	v_mfma_f32_16x16x32_bf16 v[120:123], v[152:155], v[196:199], v[120:123]
	v_mfma_f32_16x16x32_bf16 v[124:127], v[170:173], v[196:199], v[124:127]
	v_mfma_f32_16x16x32_bf16 v[104:107], v[152:155], v[204:207], v[104:107]
	v_mfma_f32_16x16x32_bf16 v[108:111], v[170:173], v[204:207], v[108:111]
	v_mfma_f32_16x16x32_bf16 v[88:91], v[152:155], v[212:215], v[88:91]
	v_mfma_f32_16x16x32_bf16 v[92:95], v[170:173], v[212:215], v[92:95]
	v_mfma_f32_16x16x32_bf16 v[72:75], v[152:155], v[220:223], v[72:75]
	v_mfma_f32_16x16x32_bf16 v[76:79], v[170:173], v[220:223], v[76:79]
	v_mfma_f32_16x16x32_bf16 v[120:123], v[166:169], v[200:203], v[120:123]
	v_mfma_f32_16x16x32_bf16 v[124:127], v[174:177], v[200:203], v[124:127]
	v_mfma_f32_16x16x32_bf16 v[104:107], v[166:169], v[208:211], v[104:107]
	v_mfma_f32_16x16x32_bf16 v[108:111], v[174:177], v[208:211], v[108:111]
	v_mfma_f32_16x16x32_bf16 v[88:91], v[166:169], v[216:219], v[88:91]
	v_mfma_f32_16x16x32_bf16 v[92:95], v[174:177], v[216:219], v[92:95]
	v_mfma_f32_16x16x32_bf16 v[72:75], v[166:169], v[224:227], v[72:75]
	v_mfma_f32_16x16x32_bf16 v[76:79], v[174:177], v[224:227], v[76:79]
	v_mfma_f32_16x16x32_bf16 v[116:119], v[178:181], v[196:199], v[116:119]
	v_mfma_f32_16x16x32_bf16 v[112:115], v[188:191], v[196:199], v[112:115]
	v_mfma_f32_16x16x32_bf16 v[100:103], v[178:181], v[204:207], v[100:103]
	v_mfma_f32_16x16x32_bf16 v[96:99], v[188:191], v[204:207], v[96:99]
	v_mfma_f32_16x16x32_bf16 v[84:87], v[178:181], v[212:215], v[84:87]
	v_mfma_f32_16x16x32_bf16 v[80:83], v[188:191], v[212:215], v[80:83]
	v_mfma_f32_16x16x32_bf16 v[68:71], v[178:181], v[220:223], v[68:71]
	v_mfma_f32_16x16x32_bf16 v[64:67], v[188:191], v[220:223], v[64:67]
	v_mfma_f32_16x16x32_bf16 v[116:119], v[184:187], v[200:203], v[116:119]
	v_mfma_f32_16x16x32_bf16 v[112:115], v[192:195], v[200:203], v[112:115]
	v_mfma_f32_16x16x32_bf16 v[100:103], v[184:187], v[208:211], v[100:103]
	v_mfma_f32_16x16x32_bf16 v[96:99], v[192:195], v[208:211], v[96:99]
	v_mfma_f32_16x16x32_bf16 v[84:87], v[184:187], v[216:219], v[84:87]
	v_mfma_f32_16x16x32_bf16 v[80:83], v[192:195], v[216:219], v[80:83]
	v_mfma_f32_16x16x32_bf16 v[68:71], v[184:187], v[224:227], v[68:71]
	v_mfma_f32_16x16x32_bf16 v[64:67], v[192:195], v[224:227], v[64:67]
	s_setprio 0
	s_barrier
	s_add_i32 s86, 16, 0x18000
	v_add_u32_e32 v136, s86, v159
	s_add_i32 s87, 16, 0x1c000
	ds_read_b128 v[152:155], v136
	ds_read_b128 v[166:169], v136 offset:1024
	ds_read_b128 v[170:173], v136 offset:2048
	ds_read_b128 v[174:177], v136 offset:3072
	v_add_u32_e32 v136, s87, v159
	ds_read_b128 v[178:181], v136
	ds_read_b128 v[184:187], v136 offset:1024
	ds_read_b128 v[188:191], v136 offset:2048
	ds_read_b128 v[192:195], v136 offset:3072
	s_add_u32 s50, s50, 0x80000
	s_addc_u32 s51, s51, 0
	s_mov_b32 m0, s55
	v_lshl_add_u64 v[234:235], s[50:51], 0, v[128:129]
	ds_read_b128 v[196:199], v162 offset:32768
	ds_read_b128 v[200:203], v162 offset:33792
	ds_read_b128 v[204:207], v162 offset:34816
	ds_read_b128 v[208:211], v162 offset:35840
	ds_read_b128 v[212:215], v162 offset:36864
	ds_read_b128 v[216:219], v162 offset:37888
	ds_read_b128 v[220:223], v162 offset:38912
	ds_read_b128 v[224:227], v162 offset:39936
	global_load_lds_dwordx4 v[234:235], off
	v_lshl_add_u64 v[234:235], s[50:51], 0, v[132:133]
	s_mov_b32 m0, s56
	s_nop 0
	global_load_lds_dwordx4 v[234:235], off
	s_waitcnt vmcnt(8)
	s_waitcnt lgkmcnt(0)
	s_barrier
	s_setprio 1
	s_waitcnt lgkmcnt(0)
	v_mfma_f32_16x16x32_bf16 v[60:63], v[152:155], v[196:199], v[60:63]
	v_mfma_f32_16x16x32_bf16 v[56:59], v[170:173], v[196:199], v[56:59]
	v_mfma_f32_16x16x32_bf16 v[52:55], v[152:155], v[204:207], v[52:55]
	v_mfma_f32_16x16x32_bf16 v[48:51], v[170:173], v[204:207], v[48:51]
	v_mfma_f32_16x16x32_bf16 v[44:47], v[152:155], v[212:215], v[44:47]
	v_mfma_f32_16x16x32_bf16 v[40:43], v[170:173], v[212:215], v[40:43]
	v_mfma_f32_16x16x32_bf16 v[28:31], v[152:155], v[220:223], v[28:31]
	v_mfma_f32_16x16x32_bf16 v[24:27], v[170:173], v[220:223], v[24:27]
	v_mfma_f32_16x16x32_bf16 v[60:63], v[166:169], v[200:203], v[60:63]
	v_mfma_f32_16x16x32_bf16 v[56:59], v[174:177], v[200:203], v[56:59]
	v_mfma_f32_16x16x32_bf16 v[52:55], v[166:169], v[208:211], v[52:55]
	v_mfma_f32_16x16x32_bf16 v[48:51], v[174:177], v[208:211], v[48:51]
	v_mfma_f32_16x16x32_bf16 v[44:47], v[166:169], v[216:219], v[44:47]
	v_mfma_f32_16x16x32_bf16 v[40:43], v[174:177], v[216:219], v[40:43]
	v_mfma_f32_16x16x32_bf16 v[28:31], v[166:169], v[224:227], v[28:31]
	v_mfma_f32_16x16x32_bf16 v[24:27], v[174:177], v[224:227], v[24:27]
	v_mfma_f32_16x16x32_bf16 v[36:39], v[178:181], v[196:199], v[36:39]
	v_mfma_f32_16x16x32_bf16 v[32:35], v[188:191], v[196:199], v[32:35]
	v_mfma_f32_16x16x32_bf16 v[20:23], v[178:181], v[204:207], v[20:23]
	v_mfma_f32_16x16x32_bf16 v[16:19], v[188:191], v[204:207], v[16:19]
	v_mfma_f32_16x16x32_bf16 v[12:15], v[178:181], v[212:215], v[12:15]
	v_mfma_f32_16x16x32_bf16 v[8:11], v[188:191], v[212:215], v[8:11]
	v_mfma_f32_16x16x32_bf16 v[4:7], v[178:181], v[220:223], v[4:7]
	v_mfma_f32_16x16x32_bf16 v[0:3], v[188:191], v[220:223], v[0:3]
	v_mfma_f32_16x16x32_bf16 v[36:39], v[184:187], v[200:203], v[36:39]
	v_mfma_f32_16x16x32_bf16 v[32:35], v[192:195], v[200:203], v[32:35]
	v_mfma_f32_16x16x32_bf16 v[20:23], v[184:187], v[208:211], v[20:23]
	v_mfma_f32_16x16x32_bf16 v[16:19], v[192:195], v[208:211], v[16:19]
	v_mfma_f32_16x16x32_bf16 v[12:15], v[184:187], v[216:219], v[12:15]
	v_mfma_f32_16x16x32_bf16 v[8:11], v[192:195], v[216:219], v[8:11]
	v_mfma_f32_16x16x32_bf16 v[4:7], v[184:187], v[224:227], v[4:7]
	v_mfma_f32_16x16x32_bf16 v[0:3], v[192:195], v[224:227], v[0:3]
	s_setprio 0
	s_barrier
	s_add_i32 s50, s86, s52
	v_lshl_add_u64 v[156:157], v[156:157], 0, s[28:29]
	s_mov_b32 m0, s50
	ds_read_b128 v[196:199], v162 offset:49152
	ds_read_b128 v[200:203], v162 offset:50176
	ds_read_b128 v[204:207], v162 offset:51200
	ds_read_b128 v[208:211], v162 offset:52224
	ds_read_b128 v[212:215], v162 offset:53248
	ds_read_b128 v[216:219], v162 offset:54272
	ds_read_b128 v[220:223], v162 offset:55296
	ds_read_b128 v[224:227], v162 offset:56320
	global_load_lds_dwordx4 v[156:157], off
	s_add_i32 m0, s50, 0x2000
	s_add_u32 s8, s8, 0x80080
	v_lshl_add_u64 v[156:157], v[228:229], 0, s[28:29]
	s_addc_u32 s9, s9, 0
	s_add_i32 s50, s87, s52
	global_load_lds_dwordx4 v[156:157], off
	v_lshl_add_u64 v[156:157], s[8:9], 0, v[130:131]
	s_mov_b32 m0, s50
	s_nop 0
	global_load_lds_dwordx4 v[156:157], off
	v_lshl_add_u64 v[156:157], s[8:9], 0, v[134:135]
	s_add_i32 m0, s50, 0x2000
	s_nop 0
	global_load_lds_dwordx4 v[156:157], off
	v_lshl_add_u64 v[156:157], v[230:231], 0, s[28:29]
	s_mov_b32 m0, s62
	s_nop 0
	global_load_lds_dwordx4 v[156:157], off
	v_lshl_add_u64 v[156:157], v[232:233], 0, s[28:29]
	s_mov_b32 m0, s63
	s_nop 0
	global_load_lds_dwordx4 v[156:157], off
	s_waitcnt vmcnt(8)
	s_waitcnt lgkmcnt(0)
	s_barrier
	s_setprio 1
	s_waitcnt lgkmcnt(0)
	v_mfma_f32_16x16x32_bf16 v[120:123], v[152:155], v[196:199], v[120:123]
	v_mfma_f32_16x16x32_bf16 v[124:127], v[170:173], v[196:199], v[124:127]
	v_mfma_f32_16x16x32_bf16 v[104:107], v[152:155], v[204:207], v[104:107]
	v_mfma_f32_16x16x32_bf16 v[108:111], v[170:173], v[204:207], v[108:111]
	v_mfma_f32_16x16x32_bf16 v[88:91], v[152:155], v[212:215], v[88:91]
	v_mfma_f32_16x16x32_bf16 v[92:95], v[170:173], v[212:215], v[92:95]
	v_mfma_f32_16x16x32_bf16 v[72:75], v[152:155], v[220:223], v[72:75]
	v_mfma_f32_16x16x32_bf16 v[76:79], v[170:173], v[220:223], v[76:79]
	v_mfma_f32_16x16x32_bf16 v[120:123], v[166:169], v[200:203], v[120:123]
	v_mfma_f32_16x16x32_bf16 v[124:127], v[174:177], v[200:203], v[124:127]
	v_mfma_f32_16x16x32_bf16 v[104:107], v[166:169], v[208:211], v[104:107]
	v_mfma_f32_16x16x32_bf16 v[108:111], v[174:177], v[208:211], v[108:111]
	v_mfma_f32_16x16x32_bf16 v[88:91], v[166:169], v[216:219], v[88:91]
	v_mfma_f32_16x16x32_bf16 v[92:95], v[174:177], v[216:219], v[92:95]
	v_mfma_f32_16x16x32_bf16 v[72:75], v[166:169], v[224:227], v[72:75]
	v_mfma_f32_16x16x32_bf16 v[76:79], v[174:177], v[224:227], v[76:79]
	v_mfma_f32_16x16x32_bf16 v[116:119], v[178:181], v[196:199], v[116:119]
	v_mfma_f32_16x16x32_bf16 v[112:115], v[188:191], v[196:199], v[112:115]
	v_mfma_f32_16x16x32_bf16 v[100:103], v[178:181], v[204:207], v[100:103]
	v_mfma_f32_16x16x32_bf16 v[96:99], v[188:191], v[204:207], v[96:99]
	v_mfma_f32_16x16x32_bf16 v[84:87], v[178:181], v[212:215], v[84:87]
	v_mfma_f32_16x16x32_bf16 v[80:83], v[188:191], v[212:215], v[80:83]
	v_mfma_f32_16x16x32_bf16 v[68:71], v[178:181], v[220:223], v[68:71]
	v_mfma_f32_16x16x32_bf16 v[64:67], v[188:191], v[220:223], v[64:67]
	v_mfma_f32_16x16x32_bf16 v[116:119], v[184:187], v[200:203], v[116:119]
	v_mfma_f32_16x16x32_bf16 v[112:115], v[192:195], v[200:203], v[112:115]
	v_mfma_f32_16x16x32_bf16 v[100:103], v[184:187], v[208:211], v[100:103]
	v_mfma_f32_16x16x32_bf16 v[96:99], v[192:195], v[208:211], v[96:99]
	v_mfma_f32_16x16x32_bf16 v[84:87], v[184:187], v[216:219], v[84:87]
	v_mfma_f32_16x16x32_bf16 v[80:83], v[192:195], v[216:219], v[80:83]
	v_mfma_f32_16x16x32_bf16 v[68:71], v[184:187], v[224:227], v[68:71]
	v_mfma_f32_16x16x32_bf16 v[64:67], v[192:195], v[224:227], v[64:67]
	s_setprio 0
	s_barrier
	s_add_u32 s83, s83, 0x100
	s_addc_u32 s84, s84, 0
	s_add_u32 s48, s48, 0x100
	s_addc_u32 s49, s49, 0
	s_cmp_ge_u32 s85, s81
	s_mov_b32 s50, s85
	s_cbranch_scc0 .LBB0_1711
	s_and_b64 vcc, exec, s[30:31]
	s_cbranch_vccz .LBB0_1714
	s_barrier

.LBB0_1843:
	v_add_u32_e32 v153, s47, v147
	ds_read_b128 v[164:167], v153
	ds_read_b128 v[168:171], v153 offset:1024
	ds_read_b128 v[172:175], v153 offset:2048
	ds_read_b128 v[176:179], v153 offset:3072
	v_add_u32_e32 v153, s48, v147
	ds_read_b128 v[184:187], v153
	ds_read_b128 v[188:191], v153 offset:1024
	ds_read_b128 v[192:195], v153 offset:2048
	ds_read_b128 v[196:199], v153 offset:3072
	s_add_u32 s34, s30, 0xfff80080
	s_addc_u32 s35, s31, -1
	s_and_b64 s[8:9], s[8:9], exec
	s_cselect_b32 s35, s17, s35
	s_cselect_b32 s34, s51, s34
	s_cselect_b32 s9, s15, s54
	s_cselect_b32 s8, s52, s53
	v_lshl_add_u64 v[180:181], s[30:31], 0, v[138:139]
	s_add_i32 m0, s38, 0xc000
	ds_read_b128 v[200:203], v151
	ds_read_b128 v[204:207], v151 offset:1024
	ds_read_b128 v[208:211], v151 offset:2048
	ds_read_b128 v[212:215], v151 offset:3072
	ds_read_b128 v[216:219], v151 offset:4096
	ds_read_b128 v[220:223], v151 offset:5120
	ds_read_b128 v[224:227], v151 offset:6144
	ds_read_b128 v[228:231], v151 offset:7168
	global_load_lds_dwordx4 v[180:181], off
	v_lshl_add_u64 v[180:181], s[30:31], 0, v[136:137]
	s_add_i32 m0, s38, 0xe000
	s_nop 0
	global_load_lds_dwordx4 v[180:181], off
	s_waitcnt vmcnt(8)
	s_waitcnt lgkmcnt(0)
	s_barrier
	s_setprio 1
	s_waitcnt lgkmcnt(0)
	v_mfma_f32_16x16x32_bf16 v[124:127], v[164:167], v[200:203], v[124:127]
	v_mfma_f32_16x16x32_bf16 v[120:123], v[172:175], v[200:203], v[120:123]
	v_mfma_f32_16x16x32_bf16 v[116:119], v[164:167], v[208:211], v[116:119]
	v_mfma_f32_16x16x32_bf16 v[112:115], v[172:175], v[208:211], v[112:115]
	v_mfma_f32_16x16x32_bf16 v[100:103], v[164:167], v[216:219], v[100:103]
	v_mfma_f32_16x16x32_bf16 v[96:99], v[172:175], v[216:219], v[96:99]
	v_mfma_f32_16x16x32_bf16 v[84:87], v[164:167], v[224:227], v[84:87]
	v_mfma_f32_16x16x32_bf16 v[80:83], v[172:175], v[224:227], v[80:83]
	v_mfma_f32_16x16x32_bf16 v[124:127], v[168:171], v[204:207], v[124:127]
	v_mfma_f32_16x16x32_bf16 v[120:123], v[176:179], v[204:207], v[120:123]
	v_mfma_f32_16x16x32_bf16 v[116:119], v[168:171], v[212:215], v[116:119]
	v_mfma_f32_16x16x32_bf16 v[112:115], v[176:179], v[212:215], v[112:115]
	v_mfma_f32_16x16x32_bf16 v[100:103], v[168:171], v[220:223], v[100:103]
	v_mfma_f32_16x16x32_bf16 v[96:99], v[176:179], v[220:223], v[96:99]
	v_mfma_f32_16x16x32_bf16 v[84:87], v[168:171], v[228:231], v[84:87]
	v_mfma_f32_16x16x32_bf16 v[80:83], v[176:179], v[228:231], v[80:83]
	v_mfma_f32_16x16x32_bf16 v[108:111], v[184:187], v[200:203], v[108:111]
	v_mfma_f32_16x16x32_bf16 v[104:107], v[192:195], v[200:203], v[104:107]
	v_mfma_f32_16x16x32_bf16 v[92:95], v[184:187], v[208:211], v[92:95]
	v_mfma_f32_16x16x32_bf16 v[88:91], v[192:195], v[208:211], v[88:91]
	v_mfma_f32_16x16x32_bf16 v[76:79], v[184:187], v[216:219], v[76:79]
	v_mfma_f32_16x16x32_bf16 v[72:75], v[192:195], v[216:219], v[72:75]
	v_mfma_f32_16x16x32_bf16 v[68:71], v[184:187], v[224:227], v[68:71]
	v_mfma_f32_16x16x32_bf16 v[64:67], v[192:195], v[224:227], v[64:67]
	v_mfma_f32_16x16x32_bf16 v[108:111], v[188:191], v[204:207], v[108:111]
	v_mfma_f32_16x16x32_bf16 v[104:107], v[196:199], v[204:207], v[104:107]
	v_mfma_f32_16x16x32_bf16 v[92:95], v[188:191], v[212:215], v[92:95]
	v_mfma_f32_16x16x32_bf16 v[88:91], v[196:199], v[212:215], v[88:91]
	v_mfma_f32_16x16x32_bf16 v[76:79], v[188:191], v[220:223], v[76:79]
	v_mfma_f32_16x16x32_bf16 v[72:75], v[196:199], v[220:223], v[72:75]
	v_mfma_f32_16x16x32_bf16 v[68:71], v[188:191], v[228:231], v[68:71]
	v_mfma_f32_16x16x32_bf16 v[64:67], v[196:199], v[228:231], v[64:67]
	s_setprio 0
	s_barrier
	s_add_i32 s56, s47, s37
	v_lshl_add_u64 v[180:181], s[8:9], 0, v[130:131]
	s_mov_b32 m0, s56
	ds_read_b128 v[200:203], v151 offset:16384
	ds_read_b128 v[204:207], v151 offset:17408
	ds_read_b128 v[208:211], v151 offset:18432
	ds_read_b128 v[212:215], v151 offset:19456
	ds_read_b128 v[216:219], v151 offset:20480
	ds_read_b128 v[220:223], v151 offset:21504
	ds_read_b128 v[224:227], v151 offset:22528
	ds_read_b128 v[228:231], v151 offset:23552
	global_load_lds_dwordx4 v[180:181], off
	s_add_i32 m0, s56, 0x2000
	s_add_u32 s56, s8, 0x80000
	v_lshl_add_u64 v[232:233], s[8:9], 0, v[134:135]
	s_addc_u32 s57, s9, 0
	s_add_i32 s58, s48, s37
	global_load_lds_dwordx4 v[232:233], off
	v_lshl_add_u64 v[234:235], s[56:57], 0, v[130:131]
	s_mov_b32 m0, s58
	v_lshl_add_u64 v[236:237], s[34:35], 0, v[132:133]
	global_load_lds_dwordx4 v[234:235], off
	v_lshl_add_u64 v[234:235], s[56:57], 0, v[134:135]
	s_add_i32 m0, s58, 0x2000
	s_nop 0
	global_load_lds_dwordx4 v[234:235], off
	v_lshl_add_u64 v[234:235], s[34:35], 0, v[128:129]
	s_mov_b32 m0, s38
	s_nop 0
	global_load_lds_dwordx4 v[234:235], off
	s_mov_b32 m0, s39
	s_nop 0
	global_load_lds_dwordx4 v[236:237], off
	s_waitcnt vmcnt(8)
	s_waitcnt lgkmcnt(0)
	s_barrier
	s_setprio 1
	s_waitcnt lgkmcnt(0)
	v_mfma_f32_16x16x32_bf16 v[60:63], v[164:167], v[200:203], v[60:63]
	v_mfma_f32_16x16x32_bf16 v[56:59], v[172:175], v[200:203], v[56:59]
	v_mfma_f32_16x16x32_bf16 v[52:55], v[164:167], v[208:211], v[52:55]
	v_mfma_f32_16x16x32_bf16 v[48:51], v[172:175], v[208:211], v[48:51]
	v_mfma_f32_16x16x32_bf16 v[36:39], v[164:167], v[216:219], v[36:39]
	v_mfma_f32_16x16x32_bf16 v[32:35], v[172:175], v[216:219], v[32:35]
	v_mfma_f32_16x16x32_bf16 v[20:23], v[164:167], v[224:227], v[20:23]
	v_mfma_f32_16x16x32_bf16 v[16:19], v[172:175], v[224:227], v[16:19]
	v_mfma_f32_16x16x32_bf16 v[60:63], v[168:171], v[204:207], v[60:63]
	v_mfma_f32_16x16x32_bf16 v[56:59], v[176:179], v[204:207], v[56:59]
	v_mfma_f32_16x16x32_bf16 v[52:55], v[168:171], v[212:215], v[52:55]
	v_mfma_f32_16x16x32_bf16 v[48:51], v[176:179], v[212:215], v[48:51]
	v_mfma_f32_16x16x32_bf16 v[36:39], v[168:171], v[220:223], v[36:39]
	v_mfma_f32_16x16x32_bf16 v[32:35], v[176:179], v[220:223], v[32:35]
	v_mfma_f32_16x16x32_bf16 v[20:23], v[168:171], v[228:231], v[20:23]
	v_mfma_f32_16x16x32_bf16 v[16:19], v[176:179], v[228:231], v[16:19]
	v_mfma_f32_16x16x32_bf16 v[44:47], v[184:187], v[200:203], v[44:47]
	v_mfma_f32_16x16x32_bf16 v[40:43], v[192:195], v[200:203], v[40:43]
	v_mfma_f32_16x16x32_bf16 v[28:31], v[184:187], v[208:211], v[28:31]
	v_mfma_f32_16x16x32_bf16 v[24:27], v[192:195], v[208:211], v[24:27]
	v_mfma_f32_16x16x32_bf16 v[12:15], v[184:187], v[216:219], v[12:15]
	v_mfma_f32_16x16x32_bf16 v[8:11], v[192:195], v[216:219], v[8:11]
	v_mfma_f32_16x16x32_bf16 v[4:7], v[184:187], v[224:227], v[4:7]
	v_mfma_f32_16x16x32_bf16 v[0:3], v[192:195], v[224:227], v[0:3]
	v_mfma_f32_16x16x32_bf16 v[44:47], v[188:191], v[204:207], v[44:47]
	v_mfma_f32_16x16x32_bf16 v[40:43], v[196:199], v[204:207], v[40:43]
	v_mfma_f32_16x16x32_bf16 v[28:31], v[188:191], v[212:215], v[28:31]
	v_mfma_f32_16x16x32_bf16 v[24:27], v[196:199], v[212:215], v[24:27]
	v_mfma_f32_16x16x32_bf16 v[12:15], v[188:191], v[220:223], v[12:15]
	v_mfma_f32_16x16x32_bf16 v[8:11], v[196:199], v[220:223], v[8:11]
	v_mfma_f32_16x16x32_bf16 v[4:7], v[188:191], v[228:231], v[4:7]
	v_mfma_f32_16x16x32_bf16 v[0:3], v[196:199], v[228:231], v[0:3]
	s_setprio 0
	s_barrier
	s_add_i32 s56, 16, 0x18000
	v_add_u32_e32 v153, s56, v147
	s_add_i32 s57, 16, 0x1c000
	ds_read_b128 v[164:167], v153
	ds_read_b128 v[168:171], v153 offset:1024
	ds_read_b128 v[172:175], v153 offset:2048
	ds_read_b128 v[176:179], v153 offset:3072
	v_add_u32_e32 v153, s57, v147
	ds_read_b128 v[184:187], v153
	ds_read_b128 v[188:191], v153 offset:1024
	ds_read_b128 v[192:195], v153 offset:2048
	ds_read_b128 v[196:199], v153 offset:3072
	s_add_u32 s34, s34, 0x80000
	s_addc_u32 s35, s35, 0
	s_mov_b32 m0, s40
	v_lshl_add_u64 v[238:239], s[34:35], 0, v[128:129]
	ds_read_b128 v[200:203], v151 offset:32768
	ds_read_b128 v[204:207], v151 offset:33792
	ds_read_b128 v[208:211], v151 offset:34816
	ds_read_b128 v[212:215], v151 offset:35840
	ds_read_b128 v[216:219], v151 offset:36864
	ds_read_b128 v[220:223], v151 offset:37888
	ds_read_b128 v[224:227], v151 offset:38912
	ds_read_b128 v[228:231], v151 offset:39936
	global_load_lds_dwordx4 v[238:239], off
	v_lshl_add_u64 v[238:239], s[34:35], 0, v[132:133]
	s_mov_b32 m0, s41
	s_nop 0
	global_load_lds_dwordx4 v[238:239], off
	s_waitcnt vmcnt(8)
	s_waitcnt lgkmcnt(0)
	s_barrier
	s_setprio 1
	s_waitcnt lgkmcnt(0)
	v_mfma_f32_16x16x32_bf16 v[124:127], v[164:167], v[200:203], v[124:127]
	v_mfma_f32_16x16x32_bf16 v[120:123], v[172:175], v[200:203], v[120:123]
	v_mfma_f32_16x16x32_bf16 v[116:119], v[164:167], v[208:211], v[116:119]
	v_mfma_f32_16x16x32_bf16 v[112:115], v[172:175], v[208:211], v[112:115]
	v_mfma_f32_16x16x32_bf16 v[100:103], v[164:167], v[216:219], v[100:103]
	v_mfma_f32_16x16x32_bf16 v[96:99], v[172:175], v[216:219], v[96:99]
	v_mfma_f32_16x16x32_bf16 v[84:87], v[164:167], v[224:227], v[84:87]
	v_mfma_f32_16x16x32_bf16 v[80:83], v[172:175], v[224:227], v[80:83]
	v_mfma_f32_16x16x32_bf16 v[124:127], v[168:171], v[204:207], v[124:127]
	v_mfma_f32_16x16x32_bf16 v[120:123], v[176:179], v[204:207], v[120:123]
	v_mfma_f32_16x16x32_bf16 v[116:119], v[168:171], v[212:215], v[116:119]
	v_mfma_f32_16x16x32_bf16 v[112:115], v[176:179], v[212:215], v[112:115]
	v_mfma_f32_16x16x32_bf16 v[100:103], v[168:171], v[220:223], v[100:103]
	v_mfma_f32_16x16x32_bf16 v[96:99], v[176:179], v[220:223], v[96:99]
	v_mfma_f32_16x16x32_bf16 v[84:87], v[168:171], v[228:231], v[84:87]
	v_mfma_f32_16x16x32_bf16 v[80:83], v[176:179], v[228:231], v[80:83]
	v_mfma_f32_16x16x32_bf16 v[108:111], v[184:187], v[200:203], v[108:111]
	v_mfma_f32_16x16x32_bf16 v[104:107], v[192:195], v[200:203], v[104:107]
	v_mfma_f32_16x16x32_bf16 v[92:95], v[184:187], v[208:211], v[92:95]
	v_mfma_f32_16x16x32_bf16 v[88:91], v[192:195], v[208:211], v[88:91]
	v_mfma_f32_16x16x32_bf16 v[76:79], v[184:187], v[216:219], v[76:79]
	v_mfma_f32_16x16x32_bf16 v[72:75], v[192:195], v[216:219], v[72:75]
	v_mfma_f32_16x16x32_bf16 v[68:71], v[184:187], v[224:227], v[68:71]
	v_mfma_f32_16x16x32_bf16 v[64:67], v[192:195], v[224:227], v[64:67]
	v_mfma_f32_16x16x32_bf16 v[108:111], v[188:191], v[204:207], v[108:111]
	v_mfma_f32_16x16x32_bf16 v[104:107], v[196:199], v[204:207], v[104:107]
	v_mfma_f32_16x16x32_bf16 v[92:95], v[188:191], v[212:215], v[92:95]
	v_mfma_f32_16x16x32_bf16 v[88:91], v[196:199], v[212:215], v[88:91]
	v_mfma_f32_16x16x32_bf16 v[76:79], v[188:191], v[220:223], v[76:79]
	v_mfma_f32_16x16x32_bf16 v[72:75], v[196:199], v[220:223], v[72:75]
	v_mfma_f32_16x16x32_bf16 v[68:71], v[188:191], v[228:231], v[68:71]
	v_mfma_f32_16x16x32_bf16 v[64:67], v[196:199], v[228:231], v[64:67]
	s_setprio 0
	s_barrier
	s_add_i32 s34, s56, s37
	v_lshl_add_u64 v[180:181], v[180:181], 0, s[10:11]
	s_mov_b32 m0, s34
	ds_read_b128 v[200:203], v151 offset:49152
	ds_read_b128 v[204:207], v151 offset:50176
	ds_read_b128 v[208:211], v151 offset:51200
	ds_read_b128 v[212:215], v151 offset:52224
	ds_read_b128 v[216:219], v151 offset:53248
	ds_read_b128 v[220:223], v151 offset:54272
	ds_read_b128 v[224:227], v151 offset:55296
	ds_read_b128 v[228:231], v151 offset:56320
	global_load_lds_dwordx4 v[180:181], off
	s_add_i32 m0, s34, 0x2000
	s_add_u32 s8, s8, 0x80080
	v_lshl_add_u64 v[180:181], v[232:233], 0, s[10:11]
	s_addc_u32 s9, s9, 0
	s_add_i32 s34, s57, s37
	global_load_lds_dwordx4 v[180:181], off
	v_lshl_add_u64 v[180:181], s[8:9], 0, v[130:131]
	s_mov_b32 m0, s34
	s_nop 0
	global_load_lds_dwordx4 v[180:181], off
	v_lshl_add_u64 v[180:181], s[8:9], 0, v[134:135]
	s_add_i32 m0, s34, 0x2000
	s_nop 0
	global_load_lds_dwordx4 v[180:181], off
	v_lshl_add_u64 v[180:181], v[234:235], 0, s[10:11]
	s_mov_b32 m0, s43
	s_nop 0
	global_load_lds_dwordx4 v[180:181], off
	v_lshl_add_u64 v[180:181], v[236:237], 0, s[10:11]
	s_mov_b32 m0, s44
	s_nop 0
	global_load_lds_dwordx4 v[180:181], off
	s_waitcnt vmcnt(8)
	s_waitcnt lgkmcnt(0)
	s_barrier
	s_setprio 1
	s_waitcnt lgkmcnt(0)
	v_mfma_f32_16x16x32_bf16 v[60:63], v[164:167], v[200:203], v[60:63]
	v_mfma_f32_16x16x32_bf16 v[56:59], v[172:175], v[200:203], v[56:59]
	v_mfma_f32_16x16x32_bf16 v[52:55], v[164:167], v[208:211], v[52:55]
	v_mfma_f32_16x16x32_bf16 v[48:51], v[172:175], v[208:211], v[48:51]
	v_mfma_f32_16x16x32_bf16 v[36:39], v[164:167], v[216:219], v[36:39]
	v_mfma_f32_16x16x32_bf16 v[32:35], v[172:175], v[216:219], v[32:35]
	v_mfma_f32_16x16x32_bf16 v[20:23], v[164:167], v[224:227], v[20:23]
	v_mfma_f32_16x16x32_bf16 v[16:19], v[172:175], v[224:227], v[16:19]
	v_mfma_f32_16x16x32_bf16 v[60:63], v[168:171], v[204:207], v[60:63]
	v_mfma_f32_16x16x32_bf16 v[56:59], v[176:179], v[204:207], v[56:59]
	v_mfma_f32_16x16x32_bf16 v[52:55], v[168:171], v[212:215], v[52:55]
	v_mfma_f32_16x16x32_bf16 v[48:51], v[176:179], v[212:215], v[48:51]
	v_mfma_f32_16x16x32_bf16 v[36:39], v[168:171], v[220:223], v[36:39]
	v_mfma_f32_16x16x32_bf16 v[32:35], v[176:179], v[220:223], v[32:35]
	v_mfma_f32_16x16x32_bf16 v[20:23], v[168:171], v[228:231], v[20:23]
	v_mfma_f32_16x16x32_bf16 v[16:19], v[176:179], v[228:231], v[16:19]
	v_mfma_f32_16x16x32_bf16 v[44:47], v[184:187], v[200:203], v[44:47]
	v_mfma_f32_16x16x32_bf16 v[40:43], v[192:195], v[200:203], v[40:43]
	v_mfma_f32_16x16x32_bf16 v[28:31], v[184:187], v[208:211], v[28:31]
	v_mfma_f32_16x16x32_bf16 v[24:27], v[192:195], v[208:211], v[24:27]
	v_mfma_f32_16x16x32_bf16 v[12:15], v[184:187], v[216:219], v[12:15]
	v_mfma_f32_16x16x32_bf16 v[8:11], v[192:195], v[216:219], v[8:11]
	v_mfma_f32_16x16x32_bf16 v[4:7], v[184:187], v[224:227], v[4:7]
	v_mfma_f32_16x16x32_bf16 v[0:3], v[192:195], v[224:227], v[0:3]
	v_mfma_f32_16x16x32_bf16 v[44:47], v[188:191], v[204:207], v[44:47]
	v_mfma_f32_16x16x32_bf16 v[40:43], v[196:199], v[204:207], v[40:43]
	v_mfma_f32_16x16x32_bf16 v[28:31], v[188:191], v[212:215], v[28:31]
	v_mfma_f32_16x16x32_bf16 v[24:27], v[196:199], v[212:215], v[24:27]
	v_mfma_f32_16x16x32_bf16 v[12:15], v[188:191], v[220:223], v[12:15]
	v_mfma_f32_16x16x32_bf16 v[8:11], v[196:199], v[220:223], v[8:11]
	v_mfma_f32_16x16x32_bf16 v[4:7], v[188:191], v[228:231], v[4:7]
	v_mfma_f32_16x16x32_bf16 v[0:3], v[196:199], v[228:231], v[0:3]
	s_setprio 0
	s_barrier
	s_add_i32 s55, s55, 2
	s_add_u32 s53, s53, 0x100
	s_addc_u32 s54, s54, 0
	s_add_u32 s30, s30, 0x100
	s_addc_u32 s31, s31, 0
	s_cmp_gt_u32 s55, 29
	s_cbranch_scc1 .LBB0_1846

.LBB0_1927:
	ds_read_b128 v[150:153], v137
	ds_read_b128 v[162:165], v137 offset:1024
	ds_read_b128 v[166:169], v137 offset:2048
	ds_read_b128 v[170:173], v137 offset:3072
	ds_read_b128 v[174:177], v159
	ds_read_b128 v[178:181], v159 offset:1024
	ds_read_b128 v[184:187], v159 offset:2048
	ds_read_b128 v[188:191], v159 offset:3072
	s_add_i32 s95, s40, 2
	s_add_u32 s38, s36, 0x100
	s_addc_u32 s39, s37, 0
	s_cmp_eq_u32 s92, s40
	s_cselect_b32 s40, s34, s93
	s_cselect_b32 s43, s31, s39
	s_cselect_b32 s42, s30, s38
	s_cselect_b32 s41, s35, s94
	v_lshl_add_u64 v[154:155], s[36:37], 0, v[148:149]
	s_add_i32 m0, s46, 0xc000
	ds_read_b128 v[192:195], v160
	ds_read_b128 v[196:199], v160 offset:1024
	ds_read_b128 v[200:203], v160 offset:2048
	ds_read_b128 v[204:207], v160 offset:3072
	ds_read_b128 v[208:211], v160 offset:4096
	ds_read_b128 v[212:215], v160 offset:5120
	ds_read_b128 v[216:219], v160 offset:6144
	ds_read_b128 v[220:223], v160 offset:7168
	global_load_lds_dwordx4 v[154:155], off
	v_lshl_add_u64 v[154:155], s[36:37], 0, v[146:147]
	s_add_i32 m0, s46, 0xe000
	s_nop 0
	global_load_lds_dwordx4 v[154:155], off
	s_waitcnt vmcnt(8)
	s_waitcnt lgkmcnt(0)
	s_barrier
	s_setprio 1
	s_waitcnt lgkmcnt(0)
	v_mfma_f32_16x16x32_bf16 v[76:79], v[150:153], v[192:195], v[76:79]
	v_mfma_f32_16x16x32_bf16 v[72:75], v[166:169], v[192:195], v[72:75]
	v_mfma_f32_16x16x32_bf16 v[68:71], v[150:153], v[200:203], v[68:71]
	v_mfma_f32_16x16x32_bf16 v[64:67], v[166:169], v[200:203], v[64:67]
	v_mfma_f32_16x16x32_bf16 v[56:59], v[150:153], v[208:211], v[56:59]
	v_mfma_f32_16x16x32_bf16 v[48:51], v[166:169], v[208:211], v[48:51]
	v_mfma_f32_16x16x32_bf16 v[36:39], v[150:153], v[216:219], v[36:39]
	v_mfma_f32_16x16x32_bf16 v[32:35], v[166:169], v[216:219], v[32:35]
	v_mfma_f32_16x16x32_bf16 v[76:79], v[162:165], v[196:199], v[76:79]
	v_mfma_f32_16x16x32_bf16 v[72:75], v[170:173], v[196:199], v[72:75]
	v_mfma_f32_16x16x32_bf16 v[68:71], v[162:165], v[204:207], v[68:71]
	v_mfma_f32_16x16x32_bf16 v[64:67], v[170:173], v[204:207], v[64:67]
	v_mfma_f32_16x16x32_bf16 v[56:59], v[162:165], v[212:215], v[56:59]
	v_mfma_f32_16x16x32_bf16 v[48:51], v[170:173], v[212:215], v[48:51]
	v_mfma_f32_16x16x32_bf16 v[36:39], v[162:165], v[220:223], v[36:39]
	v_mfma_f32_16x16x32_bf16 v[32:35], v[170:173], v[220:223], v[32:35]
	v_mfma_f32_16x16x32_bf16 v[44:47], v[174:177], v[192:195], v[44:47]
	v_mfma_f32_16x16x32_bf16 v[40:43], v[184:187], v[192:195], v[40:43]
	v_mfma_f32_16x16x32_bf16 v[28:31], v[174:177], v[200:203], v[28:31]
	v_mfma_f32_16x16x32_bf16 v[24:27], v[184:187], v[200:203], v[24:27]
	v_mfma_f32_16x16x32_bf16 v[20:23], v[174:177], v[208:211], v[20:23]
	v_mfma_f32_16x16x32_bf16 v[16:19], v[184:187], v[208:211], v[16:19]
	v_mfma_f32_16x16x32_bf16 v[8:11], v[174:177], v[216:219], v[8:11]
	v_mfma_f32_16x16x32_bf16 v[4:7], v[184:187], v[216:219], v[4:7]
	v_mfma_f32_16x16x32_bf16 v[44:47], v[178:181], v[196:199], v[44:47]
	v_mfma_f32_16x16x32_bf16 v[40:43], v[188:191], v[196:199], v[40:43]
	v_mfma_f32_16x16x32_bf16 v[28:31], v[178:181], v[204:207], v[28:31]
	v_mfma_f32_16x16x32_bf16 v[24:27], v[188:191], v[204:207], v[24:27]
	v_mfma_f32_16x16x32_bf16 v[20:23], v[178:181], v[212:215], v[20:23]
	v_mfma_f32_16x16x32_bf16 v[16:19], v[188:191], v[212:215], v[16:19]
	v_mfma_f32_16x16x32_bf16 v[8:11], v[178:181], v[220:223], v[8:11]
	v_mfma_f32_16x16x32_bf16 v[4:7], v[188:191], v[220:223], v[4:7]
	s_setprio 0
	s_barrier
	s_add_i32 s36, s55, s45
	v_lshl_add_u64 v[154:155], s[40:41], 0, v[130:131]
	s_mov_b32 m0, s36
	ds_read_b128 v[192:195], v160 offset:16384
	ds_read_b128 v[196:199], v160 offset:17408
	ds_read_b128 v[200:203], v160 offset:18432
	ds_read_b128 v[204:207], v160 offset:19456
	ds_read_b128 v[208:211], v160 offset:20480
	ds_read_b128 v[212:215], v160 offset:21504
	ds_read_b128 v[216:219], v160 offset:22528
	ds_read_b128 v[220:223], v160 offset:23552
	global_load_lds_dwordx4 v[154:155], off
	s_add_i32 m0, s36, 0x2000
	s_add_u32 s36, s40, 0x160000
	v_lshl_add_u64 v[224:225], s[40:41], 0, v[134:135]
	s_addc_u32 s37, s41, 0
	s_add_i32 s96, s56, s45
	global_load_lds_dwordx4 v[224:225], off
	v_lshl_add_u64 v[226:227], s[36:37], 0, v[130:131]
	s_mov_b32 m0, s96
	v_lshl_add_u64 v[228:229], s[42:43], 0, v[132:133]
	global_load_lds_dwordx4 v[226:227], off
	v_lshl_add_u64 v[226:227], s[36:37], 0, v[134:135]
	s_add_i32 m0, s96, 0x2000
	s_nop 0
	global_load_lds_dwordx4 v[226:227], off
	v_lshl_add_u64 v[226:227], s[42:43], 0, v[128:129]
	s_mov_b32 m0, s46
	s_nop 0
	global_load_lds_dwordx4 v[226:227], off
	s_mov_b32 m0, s47
	s_nop 0
	global_load_lds_dwordx4 v[228:229], off
	s_waitcnt vmcnt(8)
	s_waitcnt lgkmcnt(0)
	s_barrier
	s_setprio 1
	s_waitcnt lgkmcnt(0)
	v_mfma_f32_16x16x32_bf16 v[124:127], v[150:153], v[192:195], v[124:127]
	v_mfma_f32_16x16x32_bf16 v[120:123], v[166:169], v[192:195], v[120:123]
	v_mfma_f32_16x16x32_bf16 v[108:111], v[150:153], v[200:203], v[108:111]
	v_mfma_f32_16x16x32_bf16 v[104:107], v[166:169], v[200:203], v[104:107]
	v_mfma_f32_16x16x32_bf16 v[92:95], v[150:153], v[208:211], v[92:95]
	v_mfma_f32_16x16x32_bf16 v[88:91], v[166:169], v[208:211], v[88:91]
	v_mfma_f32_16x16x32_bf16 v[60:63], v[150:153], v[216:219], v[60:63]
	v_mfma_f32_16x16x32_bf16 v[52:55], v[166:169], v[216:219], v[52:55]
	v_mfma_f32_16x16x32_bf16 v[124:127], v[162:165], v[196:199], v[124:127]
	v_mfma_f32_16x16x32_bf16 v[120:123], v[170:173], v[196:199], v[120:123]
	v_mfma_f32_16x16x32_bf16 v[108:111], v[162:165], v[204:207], v[108:111]
	v_mfma_f32_16x16x32_bf16 v[104:107], v[170:173], v[204:207], v[104:107]
	v_mfma_f32_16x16x32_bf16 v[92:95], v[162:165], v[212:215], v[92:95]
	v_mfma_f32_16x16x32_bf16 v[88:91], v[170:173], v[212:215], v[88:91]
	v_mfma_f32_16x16x32_bf16 v[60:63], v[162:165], v[220:223], v[60:63]
	v_mfma_f32_16x16x32_bf16 v[52:55], v[170:173], v[220:223], v[52:55]
	v_mfma_f32_16x16x32_bf16 v[116:119], v[174:177], v[192:195], v[116:119]
	v_mfma_f32_16x16x32_bf16 v[112:115], v[184:187], v[192:195], v[112:115]
	v_mfma_f32_16x16x32_bf16 v[100:103], v[174:177], v[200:203], v[100:103]
	v_mfma_f32_16x16x32_bf16 v[96:99], v[184:187], v[200:203], v[96:99]
	v_mfma_f32_16x16x32_bf16 v[84:87], v[174:177], v[208:211], v[84:87]
	v_mfma_f32_16x16x32_bf16 v[80:83], v[184:187], v[208:211], v[80:83]
	v_mfma_f32_16x16x32_bf16 v[12:15], v[174:177], v[216:219], v[12:15]
	v_mfma_f32_16x16x32_bf16 v[0:3], v[184:187], v[216:219], v[0:3]
	v_mfma_f32_16x16x32_bf16 v[116:119], v[178:181], v[196:199], v[116:119]
	v_mfma_f32_16x16x32_bf16 v[112:115], v[188:191], v[196:199], v[112:115]
	v_mfma_f32_16x16x32_bf16 v[100:103], v[178:181], v[204:207], v[100:103]
	v_mfma_f32_16x16x32_bf16 v[96:99], v[188:191], v[204:207], v[96:99]
	v_mfma_f32_16x16x32_bf16 v[84:87], v[178:181], v[212:215], v[84:87]
	v_mfma_f32_16x16x32_bf16 v[80:83], v[188:191], v[212:215], v[80:83]
	v_mfma_f32_16x16x32_bf16 v[12:15], v[178:181], v[220:223], v[12:15]
	v_mfma_f32_16x16x32_bf16 v[0:3], v[188:191], v[220:223], v[0:3]
	s_setprio 0
	s_barrier
	s_add_i32 s96, 16, 0x18000
	v_add_u32_e32 v161, s96, v157
	s_add_i32 s97, 16, 0x1c000
	ds_read_b128 v[150:153], v161
	ds_read_b128 v[162:165], v161 offset:1024
	ds_read_b128 v[166:169], v161 offset:2048
	ds_read_b128 v[170:173], v161 offset:3072
	v_add_u32_e32 v161, s97, v157
	ds_read_b128 v[174:177], v161
	ds_read_b128 v[178:181], v161 offset:1024
	ds_read_b128 v[184:187], v161 offset:2048
	ds_read_b128 v[188:191], v161 offset:3072
	s_add_u32 s36, s42, 0x160000
	s_addc_u32 s37, s43, 0
	s_mov_b32 m0, s48
	v_lshl_add_u64 v[230:231], s[36:37], 0, v[128:129]
	ds_read_b128 v[192:195], v160 offset:32768
	ds_read_b128 v[196:199], v160 offset:33792
	ds_read_b128 v[200:203], v160 offset:34816
	ds_read_b128 v[204:207], v160 offset:35840
	ds_read_b128 v[208:211], v160 offset:36864
	ds_read_b128 v[212:215], v160 offset:37888
	ds_read_b128 v[216:219], v160 offset:38912
	ds_read_b128 v[220:223], v160 offset:39936
	global_load_lds_dwordx4 v[230:231], off
	v_lshl_add_u64 v[230:231], s[36:37], 0, v[132:133]
	s_mov_b32 m0, s49
	s_nop 0
	global_load_lds_dwordx4 v[230:231], off
	s_waitcnt vmcnt(8)
	s_waitcnt lgkmcnt(0)
	s_barrier
	s_setprio 1
	s_waitcnt lgkmcnt(0)
	v_mfma_f32_16x16x32_bf16 v[76:79], v[150:153], v[192:195], v[76:79]
	v_mfma_f32_16x16x32_bf16 v[72:75], v[166:169], v[192:195], v[72:75]
	v_mfma_f32_16x16x32_bf16 v[68:71], v[150:153], v[200:203], v[68:71]
	v_mfma_f32_16x16x32_bf16 v[64:67], v[166:169], v[200:203], v[64:67]
	v_mfma_f32_16x16x32_bf16 v[56:59], v[150:153], v[208:211], v[56:59]
	v_mfma_f32_16x16x32_bf16 v[48:51], v[166:169], v[208:211], v[48:51]
	v_mfma_f32_16x16x32_bf16 v[36:39], v[150:153], v[216:219], v[36:39]
	v_mfma_f32_16x16x32_bf16 v[32:35], v[166:169], v[216:219], v[32:35]
	v_mfma_f32_16x16x32_bf16 v[76:79], v[162:165], v[196:199], v[76:79]
	v_mfma_f32_16x16x32_bf16 v[72:75], v[170:173], v[196:199], v[72:75]
	v_mfma_f32_16x16x32_bf16 v[68:71], v[162:165], v[204:207], v[68:71]
	v_mfma_f32_16x16x32_bf16 v[64:67], v[170:173], v[204:207], v[64:67]
	v_mfma_f32_16x16x32_bf16 v[56:59], v[162:165], v[212:215], v[56:59]
	v_mfma_f32_16x16x32_bf16 v[48:51], v[170:173], v[212:215], v[48:51]
	v_mfma_f32_16x16x32_bf16 v[36:39], v[162:165], v[220:223], v[36:39]
	v_mfma_f32_16x16x32_bf16 v[32:35], v[170:173], v[220:223], v[32:35]
	v_mfma_f32_16x16x32_bf16 v[44:47], v[174:177], v[192:195], v[44:47]
	v_mfma_f32_16x16x32_bf16 v[40:43], v[184:187], v[192:195], v[40:43]
	v_mfma_f32_16x16x32_bf16 v[28:31], v[174:177], v[200:203], v[28:31]
	v_mfma_f32_16x16x32_bf16 v[24:27], v[184:187], v[200:203], v[24:27]
	v_mfma_f32_16x16x32_bf16 v[20:23], v[174:177], v[208:211], v[20:23]
	v_mfma_f32_16x16x32_bf16 v[16:19], v[184:187], v[208:211], v[16:19]
	v_mfma_f32_16x16x32_bf16 v[8:11], v[174:177], v[216:219], v[8:11]
	v_mfma_f32_16x16x32_bf16 v[4:7], v[184:187], v[216:219], v[4:7]
	v_mfma_f32_16x16x32_bf16 v[44:47], v[178:181], v[196:199], v[44:47]
	v_mfma_f32_16x16x32_bf16 v[40:43], v[188:191], v[196:199], v[40:43]
	v_mfma_f32_16x16x32_bf16 v[28:31], v[178:181], v[204:207], v[28:31]
	v_mfma_f32_16x16x32_bf16 v[24:27], v[188:191], v[204:207], v[24:27]
	v_mfma_f32_16x16x32_bf16 v[20:23], v[178:181], v[212:215], v[20:23]
	v_mfma_f32_16x16x32_bf16 v[16:19], v[188:191], v[212:215], v[16:19]
	v_mfma_f32_16x16x32_bf16 v[8:11], v[178:181], v[220:223], v[8:11]
	v_mfma_f32_16x16x32_bf16 v[4:7], v[188:191], v[220:223], v[4:7]
	s_setprio 0
	s_barrier
	s_add_i32 s36, s96, s45
	v_lshl_add_u64 v[154:155], v[154:155], 0, s[8:9]
	s_mov_b32 m0, s36
	ds_read_b128 v[192:195], v160 offset:49152
	ds_read_b128 v[196:199], v160 offset:50176
	ds_read_b128 v[200:203], v160 offset:51200
	ds_read_b128 v[204:207], v160 offset:52224
	ds_read_b128 v[208:211], v160 offset:53248
	ds_read_b128 v[212:215], v160 offset:54272
	ds_read_b128 v[216:219], v160 offset:55296
	ds_read_b128 v[220:223], v160 offset:56320
	global_load_lds_dwordx4 v[154:155], off
	s_add_i32 m0, s36, 0x2000
	s_add_u32 s36, s40, 0x160080
	v_lshl_add_u64 v[154:155], v[224:225], 0, s[8:9]
	s_addc_u32 s37, s41, 0
	s_add_i32 s40, s97, s45
	global_load_lds_dwordx4 v[154:155], off
	v_lshl_add_u64 v[154:155], s[36:37], 0, v[130:131]
	s_mov_b32 m0, s40
	s_nop 0
	global_load_lds_dwordx4 v[154:155], off
	v_lshl_add_u64 v[154:155], s[36:37], 0, v[134:135]
	s_add_i32 m0, s40, 0x2000
	s_nop 0
	global_load_lds_dwordx4 v[154:155], off
	v_lshl_add_u64 v[154:155], v[226:227], 0, s[8:9]
	s_mov_b32 m0, s53
	s_nop 0
	global_load_lds_dwordx4 v[154:155], off
	v_lshl_add_u64 v[154:155], v[228:229], 0, s[8:9]
	s_mov_b32 m0, s54
	s_nop 0
	global_load_lds_dwordx4 v[154:155], off
	s_waitcnt vmcnt(8)
	s_waitcnt lgkmcnt(0)
	s_barrier
	s_setprio 1
	s_waitcnt lgkmcnt(0)
	v_mfma_f32_16x16x32_bf16 v[124:127], v[150:153], v[192:195], v[124:127]
	v_mfma_f32_16x16x32_bf16 v[120:123], v[166:169], v[192:195], v[120:123]
	v_mfma_f32_16x16x32_bf16 v[108:111], v[150:153], v[200:203], v[108:111]
	v_mfma_f32_16x16x32_bf16 v[104:107], v[166:169], v[200:203], v[104:107]
	v_mfma_f32_16x16x32_bf16 v[92:95], v[150:153], v[208:211], v[92:95]
	v_mfma_f32_16x16x32_bf16 v[88:91], v[166:169], v[208:211], v[88:91]
	v_mfma_f32_16x16x32_bf16 v[60:63], v[150:153], v[216:219], v[60:63]
	v_mfma_f32_16x16x32_bf16 v[52:55], v[166:169], v[216:219], v[52:55]
	v_mfma_f32_16x16x32_bf16 v[124:127], v[162:165], v[196:199], v[124:127]
	v_mfma_f32_16x16x32_bf16 v[120:123], v[170:173], v[196:199], v[120:123]
	v_mfma_f32_16x16x32_bf16 v[108:111], v[162:165], v[204:207], v[108:111]
	v_mfma_f32_16x16x32_bf16 v[104:107], v[170:173], v[204:207], v[104:107]
	v_mfma_f32_16x16x32_bf16 v[92:95], v[162:165], v[212:215], v[92:95]
	v_mfma_f32_16x16x32_bf16 v[88:91], v[170:173], v[212:215], v[88:91]
	v_mfma_f32_16x16x32_bf16 v[60:63], v[162:165], v[220:223], v[60:63]
	v_mfma_f32_16x16x32_bf16 v[52:55], v[170:173], v[220:223], v[52:55]
	v_mfma_f32_16x16x32_bf16 v[116:119], v[174:177], v[192:195], v[116:119]
	v_mfma_f32_16x16x32_bf16 v[112:115], v[184:187], v[192:195], v[112:115]
	v_mfma_f32_16x16x32_bf16 v[100:103], v[174:177], v[200:203], v[100:103]
	v_mfma_f32_16x16x32_bf16 v[96:99], v[184:187], v[200:203], v[96:99]
	v_mfma_f32_16x16x32_bf16 v[84:87], v[174:177], v[208:211], v[84:87]
	v_mfma_f32_16x16x32_bf16 v[80:83], v[184:187], v[208:211], v[80:83]
	v_mfma_f32_16x16x32_bf16 v[12:15], v[174:177], v[216:219], v[12:15]
	v_mfma_f32_16x16x32_bf16 v[0:3], v[184:187], v[216:219], v[0:3]
	v_mfma_f32_16x16x32_bf16 v[116:119], v[178:181], v[196:199], v[116:119]
	v_mfma_f32_16x16x32_bf16 v[112:115], v[188:191], v[196:199], v[112:115]
	v_mfma_f32_16x16x32_bf16 v[100:103], v[178:181], v[204:207], v[100:103]
	v_mfma_f32_16x16x32_bf16 v[96:99], v[188:191], v[204:207], v[96:99]
	v_mfma_f32_16x16x32_bf16 v[84:87], v[178:181], v[212:215], v[84:87]
	v_mfma_f32_16x16x32_bf16 v[80:83], v[188:191], v[212:215], v[80:83]
	v_mfma_f32_16x16x32_bf16 v[12:15], v[178:181], v[220:223], v[12:15]
	v_mfma_f32_16x16x32_bf16 v[0:3], v[188:191], v[220:223], v[0:3]
	s_setprio 0
	s_barrier
	s_add_u32 s93, s93, 0x100
	s_addc_u32 s94, s94, 0
	s_cmp_ge_u32 s95, s91
	s_mov_b64 s[36:37], s[38:39]
	s_mov_b32 s40, s95
	s_cbranch_scc0 .LBB0_1927
	s_and_b64 vcc, exec, s[10:11]
	s_cbranch_vccz .LBB0_1930
	s_barrier
